# variant: all LDS-DMA loads of a load segment issued right after its first ds_read
# baseline (speedup 1.0000x reference)
; #define PG8_STAGE(bufoff, gbase, voff) do { _Pragma("unroll") for (int _i = 0; _i < 2; ++_i) \
;         __builtin_amdgcn_global_load_lds((const unsigned*)((const char*)(gbase) + (voff)[_i]), (LAS unsigned*)(lds + (bufoff) + ldsw + _i * 8192), 16, 0, 0); } while (0)
; #define PG8_LDA(dst, b, h) do { _Pragma("unroll") for (int m = 0; m < 4; ++m) _Pragma("unroll") for (int k = 0; k < 2; ++k) dst[m][k] = *(const LAS bf16x8*)(lds + PG8_SA(b, h) + aoff + m * 2048 + k * 1024); } while (0)
; #define PG8_LDB(dst, b, h) do { _Pragma("unroll") for (int n = 0; n < 2; ++n) _Pragma("unroll") for (int k = 0; k < 2; ++k) dst[n][k] = *(const LAS bf16x8*)(lds + PG8_SB(b, h) + boff + n * 2048 + k * 1024); } while (0)
; #define PG8_MMA(ai, bj, At, Bt) do { __builtin_amdgcn_s_setprio(1); _Pragma("unroll") for (int m = 0; m < 4; ++m) _Pragma("unroll") for (int n = 0; n < 2; ++n) _Pragma("unroll") for (int k = 0; k < 2; ++k) \
;         acc[ai][bj][m][n] = __builtin_amdgcn_mfma_f32_16x16x32_bf16(Bt[n][k], At[m][k], acc[ai][bj][m][n], 0, 0, 0); __builtin_amdgcn_s_setprio(0); } while (0)
; #define PG8_WAIT_V(n) asm volatile("s_waitcnt vmcnt(" #n ")" ::: "memory")
; #define PG8_WAIT_L(n) asm volatile("s_waitcnt lgkmcnt(" #n ")" ::: "memory")
; #define PG8_BAR __builtin_amdgcn_s_barrier()
; template <class Epi>
; __device__ __forceinline__ void gemm_phase(LAS unsigned char* lds, const Gemm g, const StaticOrder& S, const Epi& E, const int tid) {
;     ...
;             const char* a2 = last ? nA : (s2 ? cA2 + (size_t)(t + 2 - nt) * kstep : cA + (size_t)(t + 2) * kstep);
;             const char* b2 = last ? nB : (s2 ? cB2 + (size_t)(t + 2 - nt) * kstep : cB + (size_t)(t + 2) * kstep);
;             const char* a3 = a2 + kstep; const char* b3 = b2 + kstep;
;             if constexpr (Epi::TWO) { if (t == nt) E.mid(acc, cur, wr, wc, fr, fq); }
;             if constexpr (SP2) {
;             PG8_LDB(B0, 0, 0); PG8_LDB(B1, 0, 1); PG8_SCHED; PG8_LDA(At, 0, 0); PG8_STAGE(PG8_SA(1, 1), a1 + hstep, voffA);
;             PG8_WAIT_V(8); PG8_WAIT_L(0); PG8_BAR; PG8_MMA(0, 0, At, B0); PG8_MMA(0, 1, At, B1); PG8_BAR; PG8_SCHED;
;             PG8_LDA(At, 0, 1); PG8_STAGE(PG8_SB(0, 0), b2, voffB); PG8_STAGE(PG8_SB(0, 1), b2 + bhs, voffB); PG8_STAGE(PG8_SA(0, 0), a2, voffA);
;             PG8_WAIT_V(8); PG8_WAIT_L(0); PG8_BAR; PG8_MMA(1, 0, At, B0); PG8_MMA(1, 1, At, B1); PG8_BAR; PG8_SCHED;
.LBB0_126:
	s_add_u32 s30, s28, 0xffe00080
	s_addc_u32 s31, s29, -1
	s_add_i32 s52, 0, 0x10000
	s_cmpk_eq_i32 s51, 0x7c
	s_cselect_b32 s35, s17, s31
	s_cselect_b32 s34, s27, s30
	s_cselect_b32 s31, s15, s50
	s_cselect_b32 s30, s33, s49
	s_add_i32 s54, 0, 0x14000
	v_add_u32_e32 v30, s52, v193
	v_add_u32_e32 v54, s54, v193
	ds_read_b128 v[18:21], v30
	ds_read_b128 v[22:25], v30 offset:1024
	ds_read_b128 v[26:29], v30 offset:2048
	ds_read_b128 v[30:33], v30 offset:3072
	ds_read_b128 v[42:45], v54
	ds_read_b128 v[46:49], v54 offset:1024
	ds_read_b128 v[50:53], v54 offset:2048
	ds_read_b128 v[54:57], v54 offset:3072
	v_lshl_add_u64 v[172:173], s[28:29], 0, v[180:181]
	s_add_i32 m0, s37, 0xc000
	ds_read_b128 v[182:185], v199
	global_load_lds_dwordx4 v[172:173], off
	v_lshl_add_u64 v[172:173], s[28:29], 0, v[178:179]
	s_add_i32 m0, s37, 0xe000
	s_nop 0
	global_load_lds_dwordx4 v[172:173], off
	ds_read_b128 v[186:189], v199 offset:1024
	ds_read_b128 v[212:215], v199 offset:2048
	ds_read_b128 v[216:219], v199 offset:3072
	ds_read_b128 v[220:223], v199 offset:4096
	ds_read_b128 v[224:227], v199 offset:5120
	ds_read_b128 v[228:231], v199 offset:6144
	ds_read_b128 v[232:235], v199 offset:7168
	s_waitcnt vmcnt(8)
	s_waitcnt lgkmcnt(0)
	s_barrier
	s_setprio 1
	s_waitcnt lgkmcnt(0)
	v_mfma_f32_16x16x32_bf16 v[158:161], v[18:21], v[182:185], v[158:161]
	v_mfma_f32_16x16x32_bf16 v[154:157], v[26:29], v[182:185], v[154:157]
	v_mfma_f32_16x16x32_bf16 v[142:145], v[18:21], v[212:215], v[142:145]
	v_mfma_f32_16x16x32_bf16 v[138:141], v[26:29], v[212:215], v[138:141]
	v_mfma_f32_16x16x32_bf16 v[126:129], v[18:21], v[220:223], v[126:129]
	v_mfma_f32_16x16x32_bf16 v[122:125], v[26:29], v[220:223], v[122:125]
	v_mfma_f32_16x16x32_bf16 v[110:113], v[18:21], v[228:231], v[110:113]
	v_mfma_f32_16x16x32_bf16 v[106:109], v[26:29], v[228:231], v[106:109]
	v_mfma_f32_16x16x32_bf16 v[158:161], v[22:25], v[186:189], v[158:161]
	v_mfma_f32_16x16x32_bf16 v[154:157], v[30:33], v[186:189], v[154:157]
	v_mfma_f32_16x16x32_bf16 v[142:145], v[22:25], v[216:219], v[142:145]
	v_mfma_f32_16x16x32_bf16 v[138:141], v[30:33], v[216:219], v[138:141]
	v_mfma_f32_16x16x32_bf16 v[126:129], v[22:25], v[224:227], v[126:129]
	v_mfma_f32_16x16x32_bf16 v[122:125], v[30:33], v[224:227], v[122:125]
	v_mfma_f32_16x16x32_bf16 v[110:113], v[22:25], v[232:235], v[110:113]
	v_mfma_f32_16x16x32_bf16 v[106:109], v[30:33], v[232:235], v[106:109]
	s_setprio 0
	s_setprio 1
	v_mfma_f32_16x16x32_bf16 v[150:153], v[42:45], v[182:185], v[150:153]
	v_mfma_f32_16x16x32_bf16 v[146:149], v[50:53], v[182:185], v[146:149]
	v_mfma_f32_16x16x32_bf16 v[134:137], v[42:45], v[212:215], v[134:137]
	v_mfma_f32_16x16x32_bf16 v[130:133], v[50:53], v[212:215], v[130:133]
	v_mfma_f32_16x16x32_bf16 v[118:121], v[42:45], v[220:223], v[118:121]
	v_mfma_f32_16x16x32_bf16 v[114:117], v[50:53], v[220:223], v[114:117]
	v_mfma_f32_16x16x32_bf16 v[102:105], v[42:45], v[228:231], v[102:105]
	v_mfma_f32_16x16x32_bf16 v[98:101], v[50:53], v[228:231], v[98:101]
	v_mfma_f32_16x16x32_bf16 v[150:153], v[46:49], v[186:189], v[150:153]
	v_mfma_f32_16x16x32_bf16 v[146:149], v[54:57], v[186:189], v[146:149]
	v_mfma_f32_16x16x32_bf16 v[134:137], v[46:49], v[216:219], v[134:137]
	v_mfma_f32_16x16x32_bf16 v[130:133], v[54:57], v[216:219], v[130:133]
	v_mfma_f32_16x16x32_bf16 v[118:121], v[46:49], v[224:227], v[118:121]
	v_mfma_f32_16x16x32_bf16 v[114:117], v[54:57], v[224:227], v[114:117]
	v_mfma_f32_16x16x32_bf16 v[102:105], v[46:49], v[232:235], v[102:105]
	v_mfma_f32_16x16x32_bf16 v[98:101], v[54:57], v[232:235], v[98:101]
	s_setprio 0
	s_barrier
	s_add_i32 s52, s52, s36
	v_lshl_add_u64 v[172:173], s[30:31], 0, v[0:1]
	s_mov_b32 m0, s52
	ds_read_b128 v[182:185], v199 offset:16384
	global_load_lds_dwordx4 v[172:173], off
	s_add_i32 m0, s52, 0x2000
	s_add_u32 s52, s30, 0x20000
	v_lshl_add_u64 v[174:175], s[30:31], 0, v[166:167]
	s_addc_u32 s53, s31, 0
	s_add_i32 s54, s54, s36
	global_load_lds_dwordx4 v[174:175], off
	v_lshl_add_u64 v[176:177], s[52:53], 0, v[0:1]
	s_mov_b32 m0, s54
	v_lshl_add_u64 v[200:201], s[34:35], 0, v[164:165]
	global_load_lds_dwordx4 v[176:177], off
	v_lshl_add_u64 v[176:177], s[52:53], 0, v[166:167]
	s_add_i32 m0, s54, 0x2000
	s_nop 0
	global_load_lds_dwordx4 v[176:177], off
	v_lshl_add_u64 v[176:177], s[34:35], 0, v[162:163]
	s_mov_b32 m0, s37
	s_nop 0
	global_load_lds_dwordx4 v[176:177], off
	s_mov_b32 m0, s38
	s_nop 0
	global_load_lds_dwordx4 v[200:201], off
	ds_read_b128 v[186:189], v199 offset:17408
	ds_read_b128 v[212:215], v199 offset:18432
	ds_read_b128 v[216:219], v199 offset:19456
	ds_read_b128 v[220:223], v199 offset:20480
	ds_read_b128 v[224:227], v199 offset:21504
	ds_read_b128 v[228:231], v199 offset:22528
	ds_read_b128 v[232:235], v199 offset:23552
	s_waitcnt vmcnt(8)
	s_waitcnt lgkmcnt(0)
	s_barrier
; #define PG8_STAGE(bufoff, gbase, voff) do { _Pragma("unroll") for (int _i = 0; _i < 2; ++_i) \
;         __builtin_amdgcn_global_load_lds((const unsigned*)((const char*)(gbase) + (voff)[_i]), (LAS unsigned*)(lds + (bufoff) + ldsw + _i * 8192), 16, 0, 0); } while (0)
; #define PG8_LDA(dst, b, h) do { _Pragma("unroll") for (int m = 0; m < 4; ++m) _Pragma("unroll") for (int k = 0; k < 2; ++k) dst[m][k] = *(const LAS bf16x8*)(lds + PG8_SA(b, h) + aoff + m * 2048 + k * 1024); } while (0)
; #define PG8_LDB(dst, b, h) do { _Pragma("unroll") for (int n = 0; n < 2; ++n) _Pragma("unroll") for (int k = 0; k < 2; ++k) dst[n][k] = *(const LAS bf16x8*)(lds + PG8_SB(b, h) + boff + n * 2048 + k * 1024); } while (0)
; #define PG8_MMA(ai, bj, At, Bt) do { __builtin_amdgcn_s_setprio(1); _Pragma("unroll") for (int m = 0; m < 4; ++m) _Pragma("unroll") for (int n = 0; n < 2; ++n) _Pragma("unroll") for (int k = 0; k < 2; ++k) \
;         acc[ai][bj][m][n] = __builtin_amdgcn_mfma_f32_16x16x32_bf16(Bt[n][k], At[m][k], acc[ai][bj][m][n], 0, 0, 0); __builtin_amdgcn_s_setprio(0); } while (0)
; #define PG8_WAIT_V(n) asm volatile("s_waitcnt vmcnt(" #n ")" ::: "memory")
; #define PG8_WAIT_L(n) asm volatile("s_waitcnt lgkmcnt(" #n ")" ::: "memory")
; #define PG8_BAR __builtin_amdgcn_s_barrier()
; #define PG8_SCHED __builtin_amdgcn_sched_barrier(0)
; template <class Epi>
; __device__ __forceinline__ void gemm_phase(LAS unsigned char* lds, const Gemm g, const StaticOrder& S, const Epi& E, const int tid) {
;     ...
;             PG8_WAIT_V(8); PG8_WAIT_L(0); PG8_BAR; PG8_MMA(1, 0, At, B0); PG8_MMA(1, 1, At, B1); PG8_BAR; PG8_SCHED;
;             PG8_LDB(B0, 1, 0); PG8_LDB(B1, 1, 1); PG8_SCHED; PG8_LDA(At, 1, 0); PG8_STAGE(PG8_SA(0, 1), a2 + hstep, voffA);
;             PG8_WAIT_V(8); PG8_WAIT_L(0); PG8_BAR; PG8_MMA(0, 0, At, B0); PG8_MMA(0, 1, At, B1); PG8_BAR; PG8_SCHED;
	s_setprio 1
	s_waitcnt lgkmcnt(0)
	v_mfma_f32_16x16x32_bf16 v[94:97], v[18:21], v[182:185], v[94:97]
	v_mfma_f32_16x16x32_bf16 v[90:93], v[26:29], v[182:185], v[90:93]
	v_mfma_f32_16x16x32_bf16 v[78:81], v[18:21], v[212:215], v[78:81]
	v_mfma_f32_16x16x32_bf16 v[74:77], v[26:29], v[212:215], v[74:77]
	v_mfma_f32_16x16x32_bf16 v[62:65], v[18:21], v[220:223], v[62:65]
	v_mfma_f32_16x16x32_bf16 v[58:61], v[26:29], v[220:223], v[58:61]
	v_mfma_f32_16x16x32_bf16 v[14:17], v[18:21], v[228:231], v[14:17]
	v_mfma_f32_16x16x32_bf16 v[10:13], v[26:29], v[228:231], v[10:13]
	v_mfma_f32_16x16x32_bf16 v[94:97], v[22:25], v[186:189], v[94:97]
	v_mfma_f32_16x16x32_bf16 v[90:93], v[30:33], v[186:189], v[90:93]
	v_mfma_f32_16x16x32_bf16 v[78:81], v[22:25], v[216:219], v[78:81]
	v_mfma_f32_16x16x32_bf16 v[74:77], v[30:33], v[216:219], v[74:77]
	v_mfma_f32_16x16x32_bf16 v[62:65], v[22:25], v[224:227], v[62:65]
	v_mfma_f32_16x16x32_bf16 v[58:61], v[30:33], v[224:227], v[58:61]
	v_mfma_f32_16x16x32_bf16 v[14:17], v[22:25], v[232:235], v[14:17]
	v_mfma_f32_16x16x32_bf16 v[10:13], v[30:33], v[232:235], v[10:13]
	s_setprio 0
	s_setprio 1
	v_mfma_f32_16x16x32_bf16 v[38:41], v[42:45], v[220:223], v[38:41]
	v_mfma_f32_16x16x32_bf16 v[34:37], v[50:53], v[220:223], v[34:37]
	v_mfma_f32_16x16x32_bf16 v[6:9], v[42:45], v[228:231], v[6:9]
	v_mfma_f32_16x16x32_bf16 v[2:5], v[50:53], v[228:231], v[2:5]
	v_mfma_f32_16x16x32_bf16 v[18:21], v[42:45], v[182:185], v[86:89]
	v_mfma_f32_16x16x32_bf16 v[22:25], v[50:53], v[182:185], v[82:85]
	v_mfma_f32_16x16x32_bf16 v[26:29], v[42:45], v[212:215], v[70:73]
	v_mfma_f32_16x16x32_bf16 v[30:33], v[50:53], v[212:215], v[66:69]
	v_mfma_f32_16x16x32_bf16 v[38:41], v[46:49], v[224:227], v[38:41]
	v_mfma_f32_16x16x32_bf16 v[34:37], v[54:57], v[224:227], v[34:37]
	v_mfma_f32_16x16x32_bf16 v[6:9], v[46:49], v[232:235], v[6:9]
	v_mfma_f32_16x16x32_bf16 v[2:5], v[54:57], v[232:235], v[2:5]
	v_mfma_f32_16x16x32_bf16 v[18:21], v[46:49], v[186:189], v[18:21]
	v_mfma_f32_16x16x32_bf16 v[22:25], v[54:57], v[186:189], v[22:25]
	v_mfma_f32_16x16x32_bf16 v[26:29], v[46:49], v[216:219], v[26:29]
	v_mfma_f32_16x16x32_bf16 v[30:33], v[54:57], v[216:219], v[30:33]
	s_setprio 0
	s_barrier
	s_add_i32 s52, 0, 0x18000
	s_add_i32 s53, 0, 0x1c000
	v_add_u32_e32 v54, s52, v193
	v_add_u32_e32 v66, s53, v193
	ds_read_b128 v[42:45], v54
	ds_read_b128 v[46:49], v54 offset:1024
	ds_read_b128 v[50:53], v54 offset:2048
	ds_read_b128 v[54:57], v54 offset:3072
	ds_read_b128 v[182:185], v66
	ds_read_b128 v[186:189], v66 offset:1024
	ds_read_b128 v[212:215], v66 offset:2048
	ds_read_b128 v[216:219], v66 offset:3072
	s_add_u32 s34, s34, 0x200000
	s_addc_u32 s35, s35, 0
	s_mov_b32 m0, s39
	v_lshl_add_u64 v[236:237], s[34:35], 0, v[162:163]
	ds_read_b128 v[66:69], v199 offset:32768
	global_load_lds_dwordx4 v[236:237], off
	v_lshl_add_u64 v[236:237], s[34:35], 0, v[164:165]
	s_mov_b32 m0, s44
	s_nop 0
	global_load_lds_dwordx4 v[236:237], off
	ds_read_b128 v[70:73], v199 offset:33792
	ds_read_b128 v[82:85], v199 offset:34816
	ds_read_b128 v[86:89], v199 offset:35840
	ds_read_b128 v[220:223], v199 offset:36864
	ds_read_b128 v[224:227], v199 offset:37888
	ds_read_b128 v[228:231], v199 offset:38912
	ds_read_b128 v[232:235], v199 offset:39936
	s_waitcnt vmcnt(8)
	s_waitcnt lgkmcnt(0)
	s_barrier
	s_setprio 1
	s_waitcnt lgkmcnt(0)
	v_mfma_f32_16x16x32_bf16 v[158:161], v[42:45], v[66:69], v[158:161]
	v_mfma_f32_16x16x32_bf16 v[154:157], v[50:53], v[66:69], v[154:157]
	v_mfma_f32_16x16x32_bf16 v[142:145], v[42:45], v[82:85], v[142:145]
	v_mfma_f32_16x16x32_bf16 v[138:141], v[50:53], v[82:85], v[138:141]
	v_mfma_f32_16x16x32_bf16 v[126:129], v[42:45], v[220:223], v[126:129]
	v_mfma_f32_16x16x32_bf16 v[122:125], v[50:53], v[220:223], v[122:125]
	v_mfma_f32_16x16x32_bf16 v[110:113], v[42:45], v[228:231], v[110:113]
	v_mfma_f32_16x16x32_bf16 v[106:109], v[50:53], v[228:231], v[106:109]
	v_mfma_f32_16x16x32_bf16 v[158:161], v[46:49], v[70:73], v[158:161]
	v_mfma_f32_16x16x32_bf16 v[154:157], v[54:57], v[70:73], v[154:157]
	v_mfma_f32_16x16x32_bf16 v[142:145], v[46:49], v[86:89], v[142:145]
	v_mfma_f32_16x16x32_bf16 v[138:141], v[54:57], v[86:89], v[138:141]
	v_mfma_f32_16x16x32_bf16 v[126:129], v[46:49], v[224:227], v[126:129]
	v_mfma_f32_16x16x32_bf16 v[122:125], v[54:57], v[224:227], v[122:125]
	v_mfma_f32_16x16x32_bf16 v[110:113], v[46:49], v[232:235], v[110:113]
	v_mfma_f32_16x16x32_bf16 v[106:109], v[54:57], v[232:235], v[106:109]
	s_setprio 0
	s_setprio 1
	v_mfma_f32_16x16x32_bf16 v[150:153], v[182:185], v[66:69], v[150:153]
	v_mfma_f32_16x16x32_bf16 v[66:69], v[212:215], v[66:69], v[146:149]
	v_mfma_f32_16x16x32_bf16 v[146:149], v[216:219], v[70:73], v[66:69]
	v_mfma_f32_16x16x32_bf16 v[66:69], v[182:185], v[82:85], v[134:137]
	v_mfma_f32_16x16x32_bf16 v[134:137], v[186:189], v[86:89], v[66:69]
	v_mfma_f32_16x16x32_bf16 v[66:69], v[212:215], v[82:85], v[130:133]
	v_mfma_f32_16x16x32_bf16 v[130:133], v[216:219], v[86:89], v[66:69]
	v_mfma_f32_16x16x32_bf16 v[66:69], v[182:185], v[220:223], v[118:121]
	v_mfma_f32_16x16x32_bf16 v[118:121], v[186:189], v[224:227], v[66:69]
	v_mfma_f32_16x16x32_bf16 v[66:69], v[212:215], v[220:223], v[114:117]
	v_mfma_f32_16x16x32_bf16 v[114:117], v[216:219], v[224:227], v[66:69]
	v_mfma_f32_16x16x32_bf16 v[66:69], v[182:185], v[228:231], v[102:105]
	v_mfma_f32_16x16x32_bf16 v[102:105], v[186:189], v[232:235], v[66:69]
	v_mfma_f32_16x16x32_bf16 v[66:69], v[212:215], v[228:231], v[98:101]
	v_mfma_f32_16x16x32_bf16 v[150:153], v[186:189], v[70:73], v[150:153]
	v_mfma_f32_16x16x32_bf16 v[98:101], v[216:219], v[232:235], v[66:69]
	s_setprio 0
	s_barrier
; #define PG8_STAGE(bufoff, gbase, voff) do { _Pragma("unroll") for (int _i = 0; _i < 2; ++_i) \
;         __builtin_amdgcn_global_load_lds((const unsigned*)((const char*)(gbase) + (voff)[_i]), (LAS unsigned*)(lds + (bufoff) + ldsw + _i * 8192), 16, 0, 0); } while (0)
; #define PG8_LDA(dst, b, h) do { _Pragma("unroll") for (int m = 0; m < 4; ++m) _Pragma("unroll") for (int k = 0; k < 2; ++k) dst[m][k] = *(const LAS bf16x8*)(lds + PG8_SA(b, h) + aoff + m * 2048 + k * 1024); } while (0)
; #define PG8_MMA(ai, bj, At, Bt) do { __builtin_amdgcn_s_setprio(1); _Pragma("unroll") for (int m = 0; m < 4; ++m) _Pragma("unroll") for (int n = 0; n < 2; ++n) _Pragma("unroll") for (int k = 0; k < 2; ++k) \
;         acc[ai][bj][m][n] = __builtin_amdgcn_mfma_f32_16x16x32_bf16(Bt[n][k], At[m][k], acc[ai][bj][m][n], 0, 0, 0); __builtin_amdgcn_s_setprio(0); } while (0)
; #define PG8_WAIT_V(n) asm volatile("s_waitcnt vmcnt(" #n ")" ::: "memory")
; #define PG8_WAIT_L(n) asm volatile("s_waitcnt lgkmcnt(" #n ")" ::: "memory")
; #define PG8_BAR __builtin_amdgcn_s_barrier()
; #define PG8_SCHED __builtin_amdgcn_sched_barrier(0)
; template <class Epi>
; __device__ __forceinline__ void gemm_phase(LAS unsigned char* lds, const Gemm g, const StaticOrder& S, const Epi& E, const int tid) {
;     ...
;             PG8_LDA(At, 1, 1); PG8_STAGE(PG8_SB(1, 0), b3, voffB); PG8_STAGE(PG8_SB(1, 1), b3 + bhs, voffB); PG8_STAGE(PG8_SA(1, 0), a3, voffA);
;             PG8_WAIT_V(8); PG8_WAIT_L(0); PG8_BAR; PG8_MMA(1, 0, At, B0); PG8_MMA(1, 1, At, B1); PG8_BAR; PG8_SCHED;
;     ...
;         if (ALIGN_EPI) { if (wr == 0) PG8_BAR; }
	s_add_i32 s34, s52, s36
	v_lshl_add_u64 v[82:83], v[172:173], 0, s[70:71]
	s_mov_b32 m0, s34
	s_nop 0
	ds_read_b128 v[66:69], v199 offset:49152
	global_load_lds_dwordx4 v[82:83], off
	s_add_i32 m0, s34, 0x2000
	s_add_u32 s30, s30, 0x20080
	v_lshl_add_u64 v[82:83], v[174:175], 0, s[70:71]
	s_addc_u32 s31, s31, 0
	s_add_i32 s34, s53, s36
	global_load_lds_dwordx4 v[82:83], off
	v_lshl_add_u64 v[82:83], s[30:31], 0, v[0:1]
	s_mov_b32 m0, s34
	s_nop 0
	global_load_lds_dwordx4 v[82:83], off
	v_lshl_add_u64 v[82:83], s[30:31], 0, v[166:167]
	s_add_i32 m0, s34, 0x2000
	s_nop 0
	global_load_lds_dwordx4 v[82:83], off
	v_lshl_add_u64 v[82:83], v[176:177], 0, s[70:71]
	s_mov_b32 m0, s45
	s_nop 0
	global_load_lds_dwordx4 v[82:83], off
	v_lshl_add_u64 v[82:83], v[200:201], 0, s[70:71]
	s_mov_b32 m0, s46
	s_nop 0
	global_load_lds_dwordx4 v[82:83], off
	ds_read_b128 v[70:73], v199 offset:50176
	ds_read_b128 v[220:223], v199 offset:51200
	ds_read_b128 v[224:227], v199 offset:52224
	ds_read_b128 v[228:231], v199 offset:53248
	ds_read_b128 v[232:235], v199 offset:54272
	ds_read_b128 v[236:239], v199 offset:55296
	ds_read_b128 v[240:243], v199 offset:56320
	s_waitcnt vmcnt(8)
	s_waitcnt lgkmcnt(0)
	s_barrier
	s_setprio 1
	s_waitcnt lgkmcnt(0)
	v_mfma_f32_16x16x32_bf16 v[82:85], v[42:45], v[66:69], v[94:97]
	v_mfma_f32_16x16x32_bf16 v[94:97], v[46:49], v[70:73], v[82:85]
	v_mfma_f32_16x16x32_bf16 v[82:85], v[50:53], v[66:69], v[90:93]
	v_mfma_f32_16x16x32_bf16 v[78:81], v[42:45], v[220:223], v[78:81]
	v_mfma_f32_16x16x32_bf16 v[74:77], v[50:53], v[220:223], v[74:77]
	v_mfma_f32_16x16x32_bf16 v[62:65], v[42:45], v[228:231], v[62:65]
	v_mfma_f32_16x16x32_bf16 v[58:61], v[50:53], v[228:231], v[58:61]
	v_mfma_f32_16x16x32_bf16 v[14:17], v[42:45], v[236:239], v[14:17]
	v_mfma_f32_16x16x32_bf16 v[10:13], v[50:53], v[236:239], v[10:13]
	v_mfma_f32_16x16x32_bf16 v[90:93], v[54:57], v[70:73], v[82:85]
	v_mfma_f32_16x16x32_bf16 v[78:81], v[46:49], v[224:227], v[78:81]
	v_mfma_f32_16x16x32_bf16 v[74:77], v[54:57], v[224:227], v[74:77]
	v_mfma_f32_16x16x32_bf16 v[62:65], v[46:49], v[232:235], v[62:65]
	v_mfma_f32_16x16x32_bf16 v[58:61], v[54:57], v[232:235], v[58:61]
	v_mfma_f32_16x16x32_bf16 v[14:17], v[46:49], v[240:243], v[14:17]
	v_mfma_f32_16x16x32_bf16 v[10:13], v[54:57], v[240:243], v[10:13]
	s_setprio 0
	s_setprio 1
	v_mfma_f32_16x16x32_bf16 v[18:21], v[182:185], v[66:69], v[18:21]
	v_mfma_f32_16x16x32_bf16 v[86:89], v[186:189], v[70:73], v[18:21]
	v_mfma_f32_16x16x32_bf16 v[18:21], v[212:215], v[66:69], v[22:25]
	v_mfma_f32_16x16x32_bf16 v[82:85], v[216:219], v[70:73], v[18:21]
	v_mfma_f32_16x16x32_bf16 v[18:21], v[182:185], v[220:223], v[26:29]
	v_mfma_f32_16x16x32_bf16 v[70:73], v[186:189], v[224:227], v[18:21]
	v_mfma_f32_16x16x32_bf16 v[18:21], v[212:215], v[220:223], v[30:33]
	v_mfma_f32_16x16x32_bf16 v[66:69], v[216:219], v[224:227], v[18:21]
	v_mfma_f32_16x16x32_bf16 v[18:21], v[182:185], v[228:231], v[38:41]
	v_mfma_f32_16x16x32_bf16 v[38:41], v[186:189], v[232:235], v[18:21]
	v_mfma_f32_16x16x32_bf16 v[18:21], v[212:215], v[228:231], v[34:37]
	v_mfma_f32_16x16x32_bf16 v[6:9], v[182:185], v[236:239], v[6:9]
	v_mfma_f32_16x16x32_bf16 v[2:5], v[212:215], v[236:239], v[2:5]
	v_mfma_f32_16x16x32_bf16 v[34:37], v[216:219], v[232:235], v[18:21]
	v_mfma_f32_16x16x32_bf16 v[6:9], v[186:189], v[240:243], v[6:9]
	v_mfma_f32_16x16x32_bf16 v[2:5], v[216:219], v[240:243], v[2:5]
	s_setprio 0
	s_barrier
	s_add_i32 s51, s51, 2
	s_add_u32 s49, s49, 0x100
	s_addc_u32 s50, s50, 0
	s_add_u32 s28, s28, 0x100
	s_addc_u32 s29, s29, 0
	s_cmpk_gt_u32 s51, 0x7d
	s_cbranch_scc0 .LBB0_126
	s_and_b64 vcc, exec, s[12:13]
	s_cbranch_vccz .LBB0_129
	s_barrier

; #define PG8_STAGE(bufoff, gbase, voff) do { _Pragma("unroll") for (int _i = 0; _i < 2; ++_i) \
;         __builtin_amdgcn_global_load_lds((const unsigned*)((const char*)(gbase) + (voff)[_i]), (LAS unsigned*)(lds + (bufoff) + ldsw + _i * 8192), 16, 0, 0); } while (0)
; #define PG8_LDA(dst, b, h) do { _Pragma("unroll") for (int m = 0; m < 4; ++m) _Pragma("unroll") for (int k = 0; k < 2; ++k) dst[m][k] = *(const LAS bf16x8*)(lds + PG8_SA(b, h) + aoff + m * 2048 + k * 1024); } while (0)
; #define PG8_LDB(dst, b, h) do { _Pragma("unroll") for (int n = 0; n < 2; ++n) _Pragma("unroll") for (int k = 0; k < 2; ++k) dst[n][k] = *(const LAS bf16x8*)(lds + PG8_SB(b, h) + boff + n * 2048 + k * 1024); } while (0)
; #define PG8_MMA(ai, bj, At, Bt) do { __builtin_amdgcn_s_setprio(1); _Pragma("unroll") for (int m = 0; m < 4; ++m) _Pragma("unroll") for (int n = 0; n < 2; ++n) _Pragma("unroll") for (int k = 0; k < 2; ++k) \
;         acc[ai][bj][m][n] = __builtin_amdgcn_mfma_f32_16x16x32_bf16(Bt[n][k], At[m][k], acc[ai][bj][m][n], 0, 0, 0); __builtin_amdgcn_s_setprio(0); } while (0)
; #define PG8_WAIT_V(n) asm volatile("s_waitcnt vmcnt(" #n ")" ::: "memory")
; #define PG8_WAIT_L(n) asm volatile("s_waitcnt lgkmcnt(" #n ")" ::: "memory")
; #define PG8_BAR __builtin_amdgcn_s_barrier()
; template <class Epi>
; __device__ __forceinline__ void gemm_phase(LAS unsigned char* lds, const Gemm g, const StaticOrder& S, const Epi& E, const int tid) {
;     ...
;             const char* a2 = last ? nA : (s2 ? cA2 + (size_t)(t + 2 - nt) * kstep : cA + (size_t)(t + 2) * kstep);
;             const char* b2 = last ? nB : (s2 ? cB2 + (size_t)(t + 2 - nt) * kstep : cB + (size_t)(t + 2) * kstep);
;             const char* a3 = a2 + kstep; const char* b3 = b2 + kstep;
;             if constexpr (Epi::TWO) { if (t == nt) E.mid(acc, cur, wr, wc, fr, fq); }
;             if constexpr (SP2) {
;             PG8_LDB(B0, 0, 0); PG8_LDB(B1, 0, 1); PG8_SCHED; PG8_LDA(At, 0, 0); PG8_STAGE(PG8_SA(1, 1), a1 + hstep, voffA);
;             PG8_WAIT_V(8); PG8_WAIT_L(0); PG8_BAR; PG8_MMA(0, 0, At, B0); PG8_MMA(0, 1, At, B1); PG8_BAR; PG8_SCHED;
;             PG8_LDA(At, 0, 1); PG8_STAGE(PG8_SB(0, 0), b2, voffB); PG8_STAGE(PG8_SB(0, 1), b2 + bhs, voffB); PG8_STAGE(PG8_SA(0, 0), a2, voffA);
;             PG8_WAIT_V(8); PG8_WAIT_L(0); PG8_BAR; PG8_MMA(1, 0, At, B0); PG8_MMA(1, 1, At, B1); PG8_BAR; PG8_SCHED;
.LBB0_173:
	s_add_u32 s28, s26, 0xfff80080
	s_addc_u32 s29, s27, -1
	s_add_i32 s47, 0, 0x10000
	s_cmp_eq_u32 s46, 28
	s_cselect_b32 s31, s17, s29
	s_cselect_b32 s30, s42, s28
	v_add_u32_e32 v142, s47, v149
	s_cselect_b32 s29, s15, s45
	s_cselect_b32 s28, s43, s44
	s_add_i32 s50, 0, 0x14000
	ds_read_b128 v[156:159], v142
	ds_read_b128 v[160:163], v142 offset:1024
	ds_read_b128 v[164:167], v142 offset:2048
	ds_read_b128 v[178:181], v142 offset:3072
	v_add_u32_e32 v142, s50, v149
	ds_read_b128 v[182:185], v142
	ds_read_b128 v[186:189], v142 offset:1024
	ds_read_b128 v[190:193], v142 offset:2048
	ds_read_b128 v[194:197], v142 offset:3072
	v_lshl_add_u64 v[142:143], s[26:27], 0, v[140:141]
	s_add_i32 m0, s2, 0xc000
	ds_read_b128 v[198:201], v154
	global_load_lds_dwordx4 v[142:143], off
	v_lshl_add_u64 v[142:143], s[26:27], 0, v[138:139]
	s_add_i32 m0, s2, 0xe000
	s_nop 0
	global_load_lds_dwordx4 v[142:143], off
	ds_read_b128 v[212:215], v154 offset:1024
	ds_read_b128 v[216:219], v154 offset:2048
	ds_read_b128 v[220:223], v154 offset:3072
	ds_read_b128 v[224:227], v154 offset:4096
	ds_read_b128 v[228:231], v154 offset:5120
	ds_read_b128 v[232:235], v154 offset:6144
	ds_read_b128 v[236:239], v154 offset:7168
	s_waitcnt vmcnt(8)
	s_waitcnt lgkmcnt(0)
	s_barrier
	s_setprio 1
	s_waitcnt lgkmcnt(0)
	v_mfma_f32_16x16x32_bf16 v[126:129], v[156:159], v[198:201], v[126:129]
	v_mfma_f32_16x16x32_bf16 v[122:125], v[164:167], v[198:201], v[122:125]
	v_mfma_f32_16x16x32_bf16 v[110:113], v[156:159], v[216:219], v[110:113]
	v_mfma_f32_16x16x32_bf16 v[106:109], v[164:167], v[216:219], v[106:109]
	v_mfma_f32_16x16x32_bf16 v[94:97], v[156:159], v[224:227], v[94:97]
	v_mfma_f32_16x16x32_bf16 v[90:93], v[164:167], v[224:227], v[90:93]
	v_mfma_f32_16x16x32_bf16 v[78:81], v[156:159], v[232:235], v[78:81]
	v_mfma_f32_16x16x32_bf16 v[74:77], v[164:167], v[232:235], v[74:77]
	v_mfma_f32_16x16x32_bf16 v[126:129], v[160:163], v[212:215], v[126:129]
	v_mfma_f32_16x16x32_bf16 v[122:125], v[178:181], v[212:215], v[122:125]
	v_mfma_f32_16x16x32_bf16 v[110:113], v[160:163], v[220:223], v[110:113]
	v_mfma_f32_16x16x32_bf16 v[106:109], v[178:181], v[220:223], v[106:109]
	v_mfma_f32_16x16x32_bf16 v[94:97], v[160:163], v[228:231], v[94:97]
	v_mfma_f32_16x16x32_bf16 v[90:93], v[178:181], v[228:231], v[90:93]
	v_mfma_f32_16x16x32_bf16 v[78:81], v[160:163], v[236:239], v[78:81]
	v_mfma_f32_16x16x32_bf16 v[74:77], v[178:181], v[236:239], v[74:77]
	s_setprio 0
	s_setprio 1
	v_mfma_f32_16x16x32_bf16 v[118:121], v[182:185], v[198:201], v[118:121]
	v_mfma_f32_16x16x32_bf16 v[114:117], v[190:193], v[198:201], v[114:117]
	v_mfma_f32_16x16x32_bf16 v[102:105], v[182:185], v[216:219], v[102:105]
	v_mfma_f32_16x16x32_bf16 v[98:101], v[190:193], v[216:219], v[98:101]
	v_mfma_f32_16x16x32_bf16 v[86:89], v[182:185], v[224:227], v[86:89]
	v_mfma_f32_16x16x32_bf16 v[82:85], v[190:193], v[224:227], v[82:85]
	v_mfma_f32_16x16x32_bf16 v[70:73], v[182:185], v[232:235], v[70:73]
	v_mfma_f32_16x16x32_bf16 v[66:69], v[190:193], v[232:235], v[66:69]
	v_mfma_f32_16x16x32_bf16 v[118:121], v[186:189], v[212:215], v[118:121]
	v_mfma_f32_16x16x32_bf16 v[114:117], v[194:197], v[212:215], v[114:117]
	v_mfma_f32_16x16x32_bf16 v[102:105], v[186:189], v[220:223], v[102:105]
	v_mfma_f32_16x16x32_bf16 v[98:101], v[194:197], v[220:223], v[98:101]
	v_mfma_f32_16x16x32_bf16 v[86:89], v[186:189], v[228:231], v[86:89]
	v_mfma_f32_16x16x32_bf16 v[82:85], v[194:197], v[228:231], v[82:85]
	v_mfma_f32_16x16x32_bf16 v[70:73], v[186:189], v[236:239], v[70:73]
	v_mfma_f32_16x16x32_bf16 v[66:69], v[194:197], v[236:239], v[66:69]
	s_setprio 0
	s_barrier
	s_add_i32 s47, s47, s34
	v_lshl_add_u64 v[142:143], s[28:29], 0, v[0:1]
	s_mov_b32 m0, s47
	ds_read_b128 v[198:201], v154 offset:16384
	global_load_lds_dwordx4 v[142:143], off
	s_add_i32 m0, s47, 0x2000
	s_add_u32 s48, s28, 0x8000
	v_lshl_add_u64 v[168:169], s[28:29], 0, v[134:135]
	s_addc_u32 s49, s29, 0
	s_add_i32 s47, s50, s34
	global_load_lds_dwordx4 v[168:169], off
	v_lshl_add_u64 v[172:173], s[48:49], 0, v[0:1]
	s_mov_b32 m0, s47
	v_lshl_add_u64 v[174:175], s[30:31], 0, v[132:133]
	global_load_lds_dwordx4 v[172:173], off
	v_lshl_add_u64 v[172:173], s[48:49], 0, v[134:135]
	s_add_i32 m0, s47, 0x2000
	s_nop 0
	global_load_lds_dwordx4 v[172:173], off
	v_lshl_add_u64 v[172:173], s[30:31], 0, v[130:131]
	s_mov_b32 m0, s2
	s_nop 0
	global_load_lds_dwordx4 v[172:173], off
	s_mov_b32 m0, s25
	s_nop 0
	global_load_lds_dwordx4 v[174:175], off
	ds_read_b128 v[212:215], v154 offset:17408
	ds_read_b128 v[216:219], v154 offset:18432
	ds_read_b128 v[220:223], v154 offset:19456
	ds_read_b128 v[224:227], v154 offset:20480
	ds_read_b128 v[228:231], v154 offset:21504
	ds_read_b128 v[232:235], v154 offset:22528
	ds_read_b128 v[236:239], v154 offset:23552
	s_waitcnt vmcnt(8)
	s_waitcnt lgkmcnt(0)
	s_barrier
; #define PG8_STAGE(bufoff, gbase, voff) do { _Pragma("unroll") for (int _i = 0; _i < 2; ++_i) \
;         __builtin_amdgcn_global_load_lds((const unsigned*)((const char*)(gbase) + (voff)[_i]), (LAS unsigned*)(lds + (bufoff) + ldsw + _i * 8192), 16, 0, 0); } while (0)
; #define PG8_LDA(dst, b, h) do { _Pragma("unroll") for (int m = 0; m < 4; ++m) _Pragma("unroll") for (int k = 0; k < 2; ++k) dst[m][k] = *(const LAS bf16x8*)(lds + PG8_SA(b, h) + aoff + m * 2048 + k * 1024); } while (0)
; #define PG8_LDB(dst, b, h) do { _Pragma("unroll") for (int n = 0; n < 2; ++n) _Pragma("unroll") for (int k = 0; k < 2; ++k) dst[n][k] = *(const LAS bf16x8*)(lds + PG8_SB(b, h) + boff + n * 2048 + k * 1024); } while (0)
; #define PG8_MMA(ai, bj, At, Bt) do { __builtin_amdgcn_s_setprio(1); _Pragma("unroll") for (int m = 0; m < 4; ++m) _Pragma("unroll") for (int n = 0; n < 2; ++n) _Pragma("unroll") for (int k = 0; k < 2; ++k) \
;         acc[ai][bj][m][n] = __builtin_amdgcn_mfma_f32_16x16x32_bf16(Bt[n][k], At[m][k], acc[ai][bj][m][n], 0, 0, 0); __builtin_amdgcn_s_setprio(0); } while (0)
; #define PG8_WAIT_V(n) asm volatile("s_waitcnt vmcnt(" #n ")" ::: "memory")
; #define PG8_WAIT_L(n) asm volatile("s_waitcnt lgkmcnt(" #n ")" ::: "memory")
; #define PG8_BAR __builtin_amdgcn_s_barrier()
; #define PG8_SCHED __builtin_amdgcn_sched_barrier(0)
; template <class Epi>
; __device__ __forceinline__ void gemm_phase(LAS unsigned char* lds, const Gemm g, const StaticOrder& S, const Epi& E, const int tid) {
;     ...
;             PG8_WAIT_V(8); PG8_WAIT_L(0); PG8_BAR; PG8_MMA(1, 0, At, B0); PG8_MMA(1, 1, At, B1); PG8_BAR; PG8_SCHED;
;             PG8_LDB(B0, 1, 0); PG8_LDB(B1, 1, 1); PG8_SCHED; PG8_LDA(At, 1, 0); PG8_STAGE(PG8_SA(0, 1), a2 + hstep, voffA);
;             PG8_WAIT_V(8); PG8_WAIT_L(0); PG8_BAR; PG8_MMA(0, 0, At, B0); PG8_MMA(0, 1, At, B1); PG8_BAR; PG8_SCHED;
	s_setprio 1
	s_waitcnt lgkmcnt(0)
	v_mfma_f32_16x16x32_bf16 v[62:65], v[156:159], v[198:201], v[62:65]
	v_mfma_f32_16x16x32_bf16 v[58:61], v[164:167], v[198:201], v[58:61]
	v_mfma_f32_16x16x32_bf16 v[46:49], v[156:159], v[216:219], v[46:49]
	v_mfma_f32_16x16x32_bf16 v[42:45], v[164:167], v[216:219], v[42:45]
	v_mfma_f32_16x16x32_bf16 v[30:33], v[156:159], v[224:227], v[30:33]
	v_mfma_f32_16x16x32_bf16 v[26:29], v[164:167], v[224:227], v[26:29]
	v_mfma_f32_16x16x32_bf16 v[14:17], v[156:159], v[232:235], v[14:17]
	v_mfma_f32_16x16x32_bf16 v[10:13], v[164:167], v[232:235], v[10:13]
	v_mfma_f32_16x16x32_bf16 v[62:65], v[160:163], v[212:215], v[62:65]
	v_mfma_f32_16x16x32_bf16 v[58:61], v[178:181], v[212:215], v[58:61]
	v_mfma_f32_16x16x32_bf16 v[46:49], v[160:163], v[220:223], v[46:49]
	v_mfma_f32_16x16x32_bf16 v[42:45], v[178:181], v[220:223], v[42:45]
	v_mfma_f32_16x16x32_bf16 v[30:33], v[160:163], v[228:231], v[30:33]
	v_mfma_f32_16x16x32_bf16 v[26:29], v[178:181], v[228:231], v[26:29]
	v_mfma_f32_16x16x32_bf16 v[14:17], v[160:163], v[236:239], v[14:17]
	v_mfma_f32_16x16x32_bf16 v[10:13], v[178:181], v[236:239], v[10:13]
	s_setprio 0
	s_setprio 1
	v_mfma_f32_16x16x32_bf16 v[54:57], v[182:185], v[198:201], v[54:57]
	v_mfma_f32_16x16x32_bf16 v[50:53], v[190:193], v[198:201], v[50:53]
	v_mfma_f32_16x16x32_bf16 v[38:41], v[182:185], v[216:219], v[38:41]
	v_mfma_f32_16x16x32_bf16 v[34:37], v[190:193], v[216:219], v[34:37]
	v_mfma_f32_16x16x32_bf16 v[22:25], v[182:185], v[224:227], v[22:25]
	v_mfma_f32_16x16x32_bf16 v[18:21], v[190:193], v[224:227], v[18:21]
	v_mfma_f32_16x16x32_bf16 v[6:9], v[182:185], v[232:235], v[6:9]
	v_mfma_f32_16x16x32_bf16 v[2:5], v[190:193], v[232:235], v[2:5]
	v_mfma_f32_16x16x32_bf16 v[54:57], v[186:189], v[212:215], v[54:57]
	v_mfma_f32_16x16x32_bf16 v[50:53], v[194:197], v[212:215], v[50:53]
	v_mfma_f32_16x16x32_bf16 v[38:41], v[186:189], v[220:223], v[38:41]
	v_mfma_f32_16x16x32_bf16 v[34:37], v[194:197], v[220:223], v[34:37]
	v_mfma_f32_16x16x32_bf16 v[22:25], v[186:189], v[228:231], v[22:25]
	v_mfma_f32_16x16x32_bf16 v[18:21], v[194:197], v[228:231], v[18:21]
	v_mfma_f32_16x16x32_bf16 v[6:9], v[186:189], v[236:239], v[6:9]
	v_mfma_f32_16x16x32_bf16 v[2:5], v[194:197], v[236:239], v[2:5]
	s_setprio 0
	s_barrier
	s_add_i32 s47, 0, 0x18000
	v_add_u32_e32 v155, s47, v149
	s_add_i32 s48, 0, 0x1c000
	ds_read_b128 v[156:159], v155
	ds_read_b128 v[160:163], v155 offset:1024
	ds_read_b128 v[164:167], v155 offset:2048
	ds_read_b128 v[178:181], v155 offset:3072
	v_add_u32_e32 v155, s48, v149
	ds_read_b128 v[182:185], v155
	ds_read_b128 v[186:189], v155 offset:1024
	ds_read_b128 v[190:193], v155 offset:2048
	ds_read_b128 v[194:197], v155 offset:3072
	s_add_u32 s30, s30, 0x80000
	s_addc_u32 s31, s31, 0
	s_mov_b32 m0, s35
	v_lshl_add_u64 v[176:177], s[30:31], 0, v[130:131]
	ds_read_b128 v[198:201], v154 offset:32768
	global_load_lds_dwordx4 v[176:177], off
	v_lshl_add_u64 v[176:177], s[30:31], 0, v[132:133]
	s_mov_b32 m0, s36
	s_nop 0
	global_load_lds_dwordx4 v[176:177], off
	ds_read_b128 v[212:215], v154 offset:33792
	ds_read_b128 v[216:219], v154 offset:34816
	ds_read_b128 v[220:223], v154 offset:35840
	ds_read_b128 v[224:227], v154 offset:36864
	ds_read_b128 v[228:231], v154 offset:37888
	ds_read_b128 v[232:235], v154 offset:38912
	ds_read_b128 v[236:239], v154 offset:39936
	s_waitcnt vmcnt(8)
	s_waitcnt lgkmcnt(0)
	s_barrier
	s_setprio 1
	s_waitcnt lgkmcnt(0)
	v_mfma_f32_16x16x32_bf16 v[126:129], v[156:159], v[198:201], v[126:129]
	v_mfma_f32_16x16x32_bf16 v[122:125], v[164:167], v[198:201], v[122:125]
	v_mfma_f32_16x16x32_bf16 v[110:113], v[156:159], v[216:219], v[110:113]
	v_mfma_f32_16x16x32_bf16 v[106:109], v[164:167], v[216:219], v[106:109]
	v_mfma_f32_16x16x32_bf16 v[94:97], v[156:159], v[224:227], v[94:97]
	v_mfma_f32_16x16x32_bf16 v[90:93], v[164:167], v[224:227], v[90:93]
	v_mfma_f32_16x16x32_bf16 v[78:81], v[156:159], v[232:235], v[78:81]
	v_mfma_f32_16x16x32_bf16 v[74:77], v[164:167], v[232:235], v[74:77]
	v_mfma_f32_16x16x32_bf16 v[126:129], v[160:163], v[212:215], v[126:129]
	v_mfma_f32_16x16x32_bf16 v[122:125], v[178:181], v[212:215], v[122:125]
	v_mfma_f32_16x16x32_bf16 v[110:113], v[160:163], v[220:223], v[110:113]
	v_mfma_f32_16x16x32_bf16 v[106:109], v[178:181], v[220:223], v[106:109]
	v_mfma_f32_16x16x32_bf16 v[94:97], v[160:163], v[228:231], v[94:97]
	v_mfma_f32_16x16x32_bf16 v[90:93], v[178:181], v[228:231], v[90:93]
	v_mfma_f32_16x16x32_bf16 v[78:81], v[160:163], v[236:239], v[78:81]
	v_mfma_f32_16x16x32_bf16 v[74:77], v[178:181], v[236:239], v[74:77]
	s_setprio 0
	s_setprio 1
	v_mfma_f32_16x16x32_bf16 v[118:121], v[182:185], v[198:201], v[118:121]
	v_mfma_f32_16x16x32_bf16 v[114:117], v[190:193], v[198:201], v[114:117]
	v_mfma_f32_16x16x32_bf16 v[102:105], v[182:185], v[216:219], v[102:105]
	v_mfma_f32_16x16x32_bf16 v[98:101], v[190:193], v[216:219], v[98:101]
	v_mfma_f32_16x16x32_bf16 v[86:89], v[182:185], v[224:227], v[86:89]
	v_mfma_f32_16x16x32_bf16 v[82:85], v[190:193], v[224:227], v[82:85]
	v_mfma_f32_16x16x32_bf16 v[70:73], v[182:185], v[232:235], v[70:73]
	v_mfma_f32_16x16x32_bf16 v[66:69], v[190:193], v[232:235], v[66:69]
	v_mfma_f32_16x16x32_bf16 v[118:121], v[186:189], v[212:215], v[118:121]
	v_mfma_f32_16x16x32_bf16 v[114:117], v[194:197], v[212:215], v[114:117]
	v_mfma_f32_16x16x32_bf16 v[102:105], v[186:189], v[220:223], v[102:105]
	v_mfma_f32_16x16x32_bf16 v[98:101], v[194:197], v[220:223], v[98:101]
	v_mfma_f32_16x16x32_bf16 v[86:89], v[186:189], v[228:231], v[86:89]
	v_mfma_f32_16x16x32_bf16 v[82:85], v[194:197], v[228:231], v[82:85]
	v_mfma_f32_16x16x32_bf16 v[70:73], v[186:189], v[236:239], v[70:73]
	v_mfma_f32_16x16x32_bf16 v[66:69], v[194:197], v[236:239], v[66:69]
	s_setprio 0
	s_barrier
; #define PG8_STAGE(bufoff, gbase, voff) do { _Pragma("unroll") for (int _i = 0; _i < 2; ++_i) \
;         __builtin_amdgcn_global_load_lds((const unsigned*)((const char*)(gbase) + (voff)[_i]), (LAS unsigned*)(lds + (bufoff) + ldsw + _i * 8192), 16, 0, 0); } while (0)
; #define PG8_LDA(dst, b, h) do { _Pragma("unroll") for (int m = 0; m < 4; ++m) _Pragma("unroll") for (int k = 0; k < 2; ++k) dst[m][k] = *(const LAS bf16x8*)(lds + PG8_SA(b, h) + aoff + m * 2048 + k * 1024); } while (0)
; #define PG8_MMA(ai, bj, At, Bt) do { __builtin_amdgcn_s_setprio(1); _Pragma("unroll") for (int m = 0; m < 4; ++m) _Pragma("unroll") for (int n = 0; n < 2; ++n) _Pragma("unroll") for (int k = 0; k < 2; ++k) \
;         acc[ai][bj][m][n] = __builtin_amdgcn_mfma_f32_16x16x32_bf16(Bt[n][k], At[m][k], acc[ai][bj][m][n], 0, 0, 0); __builtin_amdgcn_s_setprio(0); } while (0)
; #define PG8_WAIT_V(n) asm volatile("s_waitcnt vmcnt(" #n ")" ::: "memory")
; #define PG8_WAIT_L(n) asm volatile("s_waitcnt lgkmcnt(" #n ")" ::: "memory")
; #define PG8_BAR __builtin_amdgcn_s_barrier()
; #define PG8_SCHED __builtin_amdgcn_sched_barrier(0)
; template <class Epi>
; __device__ __forceinline__ void gemm_phase(LAS unsigned char* lds, const Gemm g, const StaticOrder& S, const Epi& E, const int tid) {
;     ...
;             PG8_LDA(At, 1, 1); PG8_STAGE(PG8_SB(1, 0), b3, voffB); PG8_STAGE(PG8_SB(1, 1), b3 + bhs, voffB); PG8_STAGE(PG8_SA(1, 0), a3, voffA);
;             PG8_WAIT_V(8); PG8_WAIT_L(0); PG8_BAR; PG8_MMA(1, 0, At, B0); PG8_MMA(1, 1, At, B1); PG8_BAR; PG8_SCHED;
;     ...
;         if (ALIGN_EPI) { if (wr == 0) PG8_BAR; }
	s_add_i32 s30, s47, s34
	v_lshl_add_u64 v[142:143], v[142:143], 0, s[70:71]
	s_mov_b32 m0, s30
	ds_read_b128 v[198:201], v154 offset:49152
	global_load_lds_dwordx4 v[142:143], off
	s_add_i32 m0, s30, 0x2000
	s_add_u32 s28, s28, 0x8080
	v_lshl_add_u64 v[142:143], v[168:169], 0, s[70:71]
	s_addc_u32 s29, s29, 0
	s_add_i32 s30, s48, s34
	global_load_lds_dwordx4 v[142:143], off
	v_lshl_add_u64 v[142:143], s[28:29], 0, v[0:1]
	s_mov_b32 m0, s30
	s_nop 0
	global_load_lds_dwordx4 v[142:143], off
	v_lshl_add_u64 v[142:143], s[28:29], 0, v[134:135]
	s_add_i32 m0, s30, 0x2000
	s_nop 0
	global_load_lds_dwordx4 v[142:143], off
	v_lshl_add_u64 v[142:143], v[172:173], 0, s[70:71]
	s_mov_b32 m0, s37
	s_nop 0
	global_load_lds_dwordx4 v[142:143], off
	v_lshl_add_u64 v[142:143], v[174:175], 0, s[70:71]
	s_mov_b32 m0, s38
	s_nop 0
	global_load_lds_dwordx4 v[142:143], off
	ds_read_b128 v[212:215], v154 offset:50176
	ds_read_b128 v[216:219], v154 offset:51200
	ds_read_b128 v[220:223], v154 offset:52224
	ds_read_b128 v[224:227], v154 offset:53248
	ds_read_b128 v[228:231], v154 offset:54272
	ds_read_b128 v[232:235], v154 offset:55296
	ds_read_b128 v[236:239], v154 offset:56320
	s_waitcnt vmcnt(8)
	s_waitcnt lgkmcnt(0)
	s_barrier
	s_setprio 1
	s_waitcnt lgkmcnt(0)
	v_mfma_f32_16x16x32_bf16 v[62:65], v[156:159], v[198:201], v[62:65]
	v_mfma_f32_16x16x32_bf16 v[58:61], v[164:167], v[198:201], v[58:61]
	v_mfma_f32_16x16x32_bf16 v[46:49], v[156:159], v[216:219], v[46:49]
	v_mfma_f32_16x16x32_bf16 v[42:45], v[164:167], v[216:219], v[42:45]
	v_mfma_f32_16x16x32_bf16 v[30:33], v[156:159], v[224:227], v[30:33]
	v_mfma_f32_16x16x32_bf16 v[26:29], v[164:167], v[224:227], v[26:29]
	v_mfma_f32_16x16x32_bf16 v[14:17], v[156:159], v[232:235], v[14:17]
	v_mfma_f32_16x16x32_bf16 v[10:13], v[164:167], v[232:235], v[10:13]
	v_mfma_f32_16x16x32_bf16 v[62:65], v[160:163], v[212:215], v[62:65]
	v_mfma_f32_16x16x32_bf16 v[58:61], v[178:181], v[212:215], v[58:61]
	v_mfma_f32_16x16x32_bf16 v[46:49], v[160:163], v[220:223], v[46:49]
	v_mfma_f32_16x16x32_bf16 v[42:45], v[178:181], v[220:223], v[42:45]
	v_mfma_f32_16x16x32_bf16 v[30:33], v[160:163], v[228:231], v[30:33]
	v_mfma_f32_16x16x32_bf16 v[26:29], v[178:181], v[228:231], v[26:29]
	v_mfma_f32_16x16x32_bf16 v[14:17], v[160:163], v[236:239], v[14:17]
	v_mfma_f32_16x16x32_bf16 v[10:13], v[178:181], v[236:239], v[10:13]
	s_setprio 0
	s_setprio 1
	v_mfma_f32_16x16x32_bf16 v[54:57], v[182:185], v[198:201], v[54:57]
	v_mfma_f32_16x16x32_bf16 v[50:53], v[190:193], v[198:201], v[50:53]
	v_mfma_f32_16x16x32_bf16 v[38:41], v[182:185], v[216:219], v[38:41]
	v_mfma_f32_16x16x32_bf16 v[34:37], v[190:193], v[216:219], v[34:37]
	v_mfma_f32_16x16x32_bf16 v[22:25], v[182:185], v[224:227], v[22:25]
	v_mfma_f32_16x16x32_bf16 v[18:21], v[190:193], v[224:227], v[18:21]
	v_mfma_f32_16x16x32_bf16 v[6:9], v[182:185], v[232:235], v[6:9]
	v_mfma_f32_16x16x32_bf16 v[2:5], v[190:193], v[232:235], v[2:5]
	v_mfma_f32_16x16x32_bf16 v[54:57], v[186:189], v[212:215], v[54:57]
	v_mfma_f32_16x16x32_bf16 v[50:53], v[194:197], v[212:215], v[50:53]
	v_mfma_f32_16x16x32_bf16 v[38:41], v[186:189], v[220:223], v[38:41]
	v_mfma_f32_16x16x32_bf16 v[34:37], v[194:197], v[220:223], v[34:37]
	v_mfma_f32_16x16x32_bf16 v[22:25], v[186:189], v[228:231], v[22:25]
	v_mfma_f32_16x16x32_bf16 v[18:21], v[194:197], v[228:231], v[18:21]
	v_mfma_f32_16x16x32_bf16 v[6:9], v[186:189], v[236:239], v[6:9]
	v_mfma_f32_16x16x32_bf16 v[2:5], v[194:197], v[236:239], v[2:5]
	s_setprio 0
	s_barrier
	s_add_i32 s46, s46, 2
	s_add_u32 s44, s44, 0x100
	s_addc_u32 s45, s45, 0
	s_add_u32 s26, s26, 0x100
	s_addc_u32 s27, s27, 0
	s_cmp_gt_u32 s46, 29
	s_cbranch_scc0 .LBB0_173
	v_readlane_b32 s42, v251, 53
	s_and_b64 vcc, exec, s[12:13]
	v_readlane_b32 s43, v251, 54
	s_cbranch_vccz .LBB0_176
	s_barrier

; #define PG8_STAGE(bufoff, gbase, voff) do { _Pragma("unroll") for (int _i = 0; _i < 2; ++_i) \
;         __builtin_amdgcn_global_load_lds((const unsigned*)((const char*)(gbase) + (voff)[_i]), (LAS unsigned*)(lds + (bufoff) + ldsw + _i * 8192), 16, 0, 0); } while (0)
; #define PG8_LDA(dst, b, h) do { _Pragma("unroll") for (int m = 0; m < 4; ++m) _Pragma("unroll") for (int k = 0; k < 2; ++k) dst[m][k] = *(const LAS bf16x8*)(lds + PG8_SA(b, h) + aoff + m * 2048 + k * 1024); } while (0)
; #define PG8_LDB(dst, b, h) do { _Pragma("unroll") for (int n = 0; n < 2; ++n) _Pragma("unroll") for (int k = 0; k < 2; ++k) dst[n][k] = *(const LAS bf16x8*)(lds + PG8_SB(b, h) + boff + n * 2048 + k * 1024); } while (0)
; #define PG8_MMA(ai, bj, At, Bt) do { __builtin_amdgcn_s_setprio(1); _Pragma("unroll") for (int m = 0; m < 4; ++m) _Pragma("unroll") for (int n = 0; n < 2; ++n) _Pragma("unroll") for (int k = 0; k < 2; ++k) \
;         acc[ai][bj][m][n] = __builtin_amdgcn_mfma_f32_16x16x32_bf16(Bt[n][k], At[m][k], acc[ai][bj][m][n], 0, 0, 0); __builtin_amdgcn_s_setprio(0); } while (0)
; #define PG8_WAIT_V(n) asm volatile("s_waitcnt vmcnt(" #n ")" ::: "memory")
; #define PG8_WAIT_L(n) asm volatile("s_waitcnt lgkmcnt(" #n ")" ::: "memory")
; #define PG8_BAR __builtin_amdgcn_s_barrier()
; template <class Epi>
; __device__ __forceinline__ void gemm_phase(LAS unsigned char* lds, const Gemm g, const StaticOrder& S, const Epi& E, const int tid) {
;     ...
;             const char* a2 = last ? nA : (s2 ? cA2 + (size_t)(t + 2 - nt) * kstep : cA + (size_t)(t + 2) * kstep);
;             const char* b2 = last ? nB : (s2 ? cB2 + (size_t)(t + 2 - nt) * kstep : cB + (size_t)(t + 2) * kstep);
;             const char* a3 = a2 + kstep; const char* b3 = b2 + kstep;
;             if constexpr (Epi::TWO) { if (t == nt) E.mid(acc, cur, wr, wc, fr, fq); }
;             if constexpr (SP2) {
;             PG8_LDB(B0, 0, 0); PG8_LDB(B1, 0, 1); PG8_SCHED; PG8_LDA(At, 0, 0); PG8_STAGE(PG8_SA(1, 1), a1 + hstep, voffA);
;             PG8_WAIT_V(8); PG8_WAIT_L(0); PG8_BAR; PG8_MMA(0, 0, At, B0); PG8_MMA(0, 1, At, B1); PG8_BAR; PG8_SCHED;
;             PG8_LDA(At, 0, 1); PG8_STAGE(PG8_SB(0, 0), b2, voffB); PG8_STAGE(PG8_SB(0, 1), b2 + bhs, voffB); PG8_STAGE(PG8_SA(0, 0), a2, voffA);
;             PG8_WAIT_V(8); PG8_WAIT_L(0); PG8_BAR; PG8_MMA(1, 0, At, B0); PG8_MMA(1, 1, At, B1); PG8_BAR; PG8_SCHED;
.LBB0_206:
	s_add_u32 s30, s28, 0xfffe0080
	s_addc_u32 s31, s29, -1
	s_add_i32 s52, 0, 0x10000
	s_cmp_eq_u32 s51, 4
	s_cselect_b32 s35, s17, s31
	s_cselect_b32 s34, s27, s30
	s_cselect_b32 s31, s15, s50
	s_cselect_b32 s30, s33, s49
	s_add_i32 s54, 0, 0x14000
	v_add_u32_e32 v30, s52, v193
	v_add_u32_e32 v54, s54, v193
	ds_read_b128 v[18:21], v30
	ds_read_b128 v[22:25], v30 offset:1024
	ds_read_b128 v[26:29], v30 offset:2048
	ds_read_b128 v[30:33], v30 offset:3072
	ds_read_b128 v[42:45], v54
	ds_read_b128 v[46:49], v54 offset:1024
	ds_read_b128 v[50:53], v54 offset:2048
	ds_read_b128 v[54:57], v54 offset:3072
	v_lshl_add_u64 v[172:173], s[28:29], 0, v[180:181]
	s_add_i32 m0, s37, 0xc000
	ds_read_b128 v[182:185], v199
	global_load_lds_dwordx4 v[172:173], off
	v_lshl_add_u64 v[172:173], s[28:29], 0, v[178:179]
	s_add_i32 m0, s37, 0xe000
	s_nop 0
	global_load_lds_dwordx4 v[172:173], off
	ds_read_b128 v[186:189], v199 offset:1024
	ds_read_b128 v[212:215], v199 offset:2048
	ds_read_b128 v[216:219], v199 offset:3072
	ds_read_b128 v[220:223], v199 offset:4096
	ds_read_b128 v[224:227], v199 offset:5120
	ds_read_b128 v[228:231], v199 offset:6144
	ds_read_b128 v[232:235], v199 offset:7168
	s_waitcnt vmcnt(8)
	s_waitcnt lgkmcnt(0)
	s_barrier
	s_setprio 1
	s_waitcnt lgkmcnt(0)
	v_mfma_f32_16x16x32_bf16 v[158:161], v[18:21], v[182:185], v[158:161]
	v_mfma_f32_16x16x32_bf16 v[154:157], v[26:29], v[182:185], v[154:157]
	v_mfma_f32_16x16x32_bf16 v[142:145], v[18:21], v[212:215], v[142:145]
	v_mfma_f32_16x16x32_bf16 v[138:141], v[26:29], v[212:215], v[138:141]
	v_mfma_f32_16x16x32_bf16 v[126:129], v[18:21], v[220:223], v[126:129]
	v_mfma_f32_16x16x32_bf16 v[122:125], v[26:29], v[220:223], v[122:125]
	v_mfma_f32_16x16x32_bf16 v[110:113], v[18:21], v[228:231], v[110:113]
	v_mfma_f32_16x16x32_bf16 v[106:109], v[26:29], v[228:231], v[106:109]
	v_mfma_f32_16x16x32_bf16 v[158:161], v[22:25], v[186:189], v[158:161]
	v_mfma_f32_16x16x32_bf16 v[154:157], v[30:33], v[186:189], v[154:157]
	v_mfma_f32_16x16x32_bf16 v[142:145], v[22:25], v[216:219], v[142:145]
	v_mfma_f32_16x16x32_bf16 v[138:141], v[30:33], v[216:219], v[138:141]
	v_mfma_f32_16x16x32_bf16 v[126:129], v[22:25], v[224:227], v[126:129]
	v_mfma_f32_16x16x32_bf16 v[122:125], v[30:33], v[224:227], v[122:125]
	v_mfma_f32_16x16x32_bf16 v[110:113], v[22:25], v[232:235], v[110:113]
	v_mfma_f32_16x16x32_bf16 v[106:109], v[30:33], v[232:235], v[106:109]
	s_setprio 0
	s_setprio 1
	v_mfma_f32_16x16x32_bf16 v[150:153], v[42:45], v[182:185], v[150:153]
	v_mfma_f32_16x16x32_bf16 v[146:149], v[50:53], v[182:185], v[146:149]
	v_mfma_f32_16x16x32_bf16 v[134:137], v[42:45], v[212:215], v[134:137]
	v_mfma_f32_16x16x32_bf16 v[130:133], v[50:53], v[212:215], v[130:133]
	v_mfma_f32_16x16x32_bf16 v[118:121], v[42:45], v[220:223], v[118:121]
	v_mfma_f32_16x16x32_bf16 v[114:117], v[50:53], v[220:223], v[114:117]
	v_mfma_f32_16x16x32_bf16 v[102:105], v[42:45], v[228:231], v[102:105]
	v_mfma_f32_16x16x32_bf16 v[98:101], v[50:53], v[228:231], v[98:101]
	v_mfma_f32_16x16x32_bf16 v[150:153], v[46:49], v[186:189], v[150:153]
	v_mfma_f32_16x16x32_bf16 v[146:149], v[54:57], v[186:189], v[146:149]
	v_mfma_f32_16x16x32_bf16 v[134:137], v[46:49], v[216:219], v[134:137]
	v_mfma_f32_16x16x32_bf16 v[130:133], v[54:57], v[216:219], v[130:133]
	v_mfma_f32_16x16x32_bf16 v[118:121], v[46:49], v[224:227], v[118:121]
	v_mfma_f32_16x16x32_bf16 v[114:117], v[54:57], v[224:227], v[114:117]
	v_mfma_f32_16x16x32_bf16 v[102:105], v[46:49], v[232:235], v[102:105]
	v_mfma_f32_16x16x32_bf16 v[98:101], v[54:57], v[232:235], v[98:101]
	s_setprio 0
	s_barrier
	s_add_i32 s52, s52, s36
	v_lshl_add_u64 v[172:173], s[30:31], 0, v[0:1]
	s_mov_b32 m0, s52
	ds_read_b128 v[182:185], v199 offset:16384
	global_load_lds_dwordx4 v[172:173], off
	s_add_i32 m0, s52, 0x2000
	s_add_u32 s52, s30, 0x2000
	v_lshl_add_u64 v[174:175], s[30:31], 0, v[166:167]
	s_addc_u32 s53, s31, 0
	s_add_i32 s54, s54, s36
	global_load_lds_dwordx4 v[174:175], off
	v_lshl_add_u64 v[176:177], s[52:53], 0, v[0:1]
	s_mov_b32 m0, s54
	v_lshl_add_u64 v[200:201], s[34:35], 0, v[164:165]
	global_load_lds_dwordx4 v[176:177], off
	v_lshl_add_u64 v[176:177], s[52:53], 0, v[166:167]
	s_add_i32 m0, s54, 0x2000
	s_nop 0
	global_load_lds_dwordx4 v[176:177], off
	v_lshl_add_u64 v[176:177], s[34:35], 0, v[162:163]
	s_mov_b32 m0, s37
	s_nop 0
	global_load_lds_dwordx4 v[176:177], off
	s_mov_b32 m0, s38
	s_nop 0
	global_load_lds_dwordx4 v[200:201], off
	ds_read_b128 v[186:189], v199 offset:17408
	ds_read_b128 v[212:215], v199 offset:18432
	ds_read_b128 v[216:219], v199 offset:19456
	ds_read_b128 v[220:223], v199 offset:20480
	ds_read_b128 v[224:227], v199 offset:21504
	ds_read_b128 v[228:231], v199 offset:22528
	ds_read_b128 v[232:235], v199 offset:23552
	s_waitcnt vmcnt(8)
	s_waitcnt lgkmcnt(0)
	s_barrier
; #define PG8_STAGE(bufoff, gbase, voff) do { _Pragma("unroll") for (int _i = 0; _i < 2; ++_i) \
;         __builtin_amdgcn_global_load_lds((const unsigned*)((const char*)(gbase) + (voff)[_i]), (LAS unsigned*)(lds + (bufoff) + ldsw + _i * 8192), 16, 0, 0); } while (0)
; #define PG8_LDA(dst, b, h) do { _Pragma("unroll") for (int m = 0; m < 4; ++m) _Pragma("unroll") for (int k = 0; k < 2; ++k) dst[m][k] = *(const LAS bf16x8*)(lds + PG8_SA(b, h) + aoff + m * 2048 + k * 1024); } while (0)
; #define PG8_LDB(dst, b, h) do { _Pragma("unroll") for (int n = 0; n < 2; ++n) _Pragma("unroll") for (int k = 0; k < 2; ++k) dst[n][k] = *(const LAS bf16x8*)(lds + PG8_SB(b, h) + boff + n * 2048 + k * 1024); } while (0)
; #define PG8_MMA(ai, bj, At, Bt) do { __builtin_amdgcn_s_setprio(1); _Pragma("unroll") for (int m = 0; m < 4; ++m) _Pragma("unroll") for (int n = 0; n < 2; ++n) _Pragma("unroll") for (int k = 0; k < 2; ++k) \
;         acc[ai][bj][m][n] = __builtin_amdgcn_mfma_f32_16x16x32_bf16(Bt[n][k], At[m][k], acc[ai][bj][m][n], 0, 0, 0); __builtin_amdgcn_s_setprio(0); } while (0)
; #define PG8_WAIT_V(n) asm volatile("s_waitcnt vmcnt(" #n ")" ::: "memory")
; #define PG8_WAIT_L(n) asm volatile("s_waitcnt lgkmcnt(" #n ")" ::: "memory")
; #define PG8_BAR __builtin_amdgcn_s_barrier()
; #define PG8_SCHED __builtin_amdgcn_sched_barrier(0)
; template <class Epi>
; __device__ __forceinline__ void gemm_phase(LAS unsigned char* lds, const Gemm g, const StaticOrder& S, const Epi& E, const int tid) {
;     ...
;             PG8_WAIT_V(8); PG8_WAIT_L(0); PG8_BAR; PG8_MMA(1, 0, At, B0); PG8_MMA(1, 1, At, B1); PG8_BAR; PG8_SCHED;
;             PG8_LDB(B0, 1, 0); PG8_LDB(B1, 1, 1); PG8_SCHED; PG8_LDA(At, 1, 0); PG8_STAGE(PG8_SA(0, 1), a2 + hstep, voffA);
;             PG8_WAIT_V(8); PG8_WAIT_L(0); PG8_BAR; PG8_MMA(0, 0, At, B0); PG8_MMA(0, 1, At, B1); PG8_BAR; PG8_SCHED;
	s_setprio 1
	s_waitcnt lgkmcnt(0)
	v_mfma_f32_16x16x32_bf16 v[94:97], v[18:21], v[182:185], v[94:97]
	v_mfma_f32_16x16x32_bf16 v[90:93], v[26:29], v[182:185], v[90:93]
	v_mfma_f32_16x16x32_bf16 v[78:81], v[18:21], v[212:215], v[78:81]
	v_mfma_f32_16x16x32_bf16 v[74:77], v[26:29], v[212:215], v[74:77]
	v_mfma_f32_16x16x32_bf16 v[62:65], v[18:21], v[220:223], v[62:65]
	v_mfma_f32_16x16x32_bf16 v[58:61], v[26:29], v[220:223], v[58:61]
	v_mfma_f32_16x16x32_bf16 v[14:17], v[18:21], v[228:231], v[14:17]
	v_mfma_f32_16x16x32_bf16 v[10:13], v[26:29], v[228:231], v[10:13]
	v_mfma_f32_16x16x32_bf16 v[94:97], v[22:25], v[186:189], v[94:97]
	v_mfma_f32_16x16x32_bf16 v[90:93], v[30:33], v[186:189], v[90:93]
	v_mfma_f32_16x16x32_bf16 v[78:81], v[22:25], v[216:219], v[78:81]
	v_mfma_f32_16x16x32_bf16 v[74:77], v[30:33], v[216:219], v[74:77]
	v_mfma_f32_16x16x32_bf16 v[62:65], v[22:25], v[224:227], v[62:65]
	v_mfma_f32_16x16x32_bf16 v[58:61], v[30:33], v[224:227], v[58:61]
	v_mfma_f32_16x16x32_bf16 v[14:17], v[22:25], v[232:235], v[14:17]
	v_mfma_f32_16x16x32_bf16 v[10:13], v[30:33], v[232:235], v[10:13]
	s_setprio 0
	s_setprio 1
	v_mfma_f32_16x16x32_bf16 v[38:41], v[42:45], v[220:223], v[38:41]
	v_mfma_f32_16x16x32_bf16 v[34:37], v[50:53], v[220:223], v[34:37]
	v_mfma_f32_16x16x32_bf16 v[6:9], v[42:45], v[228:231], v[6:9]
	v_mfma_f32_16x16x32_bf16 v[2:5], v[50:53], v[228:231], v[2:5]
	v_mfma_f32_16x16x32_bf16 v[18:21], v[42:45], v[182:185], v[86:89]
	v_mfma_f32_16x16x32_bf16 v[22:25], v[50:53], v[182:185], v[82:85]
	v_mfma_f32_16x16x32_bf16 v[26:29], v[42:45], v[212:215], v[70:73]
	v_mfma_f32_16x16x32_bf16 v[30:33], v[50:53], v[212:215], v[66:69]
	v_mfma_f32_16x16x32_bf16 v[38:41], v[46:49], v[224:227], v[38:41]
	v_mfma_f32_16x16x32_bf16 v[34:37], v[54:57], v[224:227], v[34:37]
	v_mfma_f32_16x16x32_bf16 v[6:9], v[46:49], v[232:235], v[6:9]
	v_mfma_f32_16x16x32_bf16 v[2:5], v[54:57], v[232:235], v[2:5]
	v_mfma_f32_16x16x32_bf16 v[18:21], v[46:49], v[186:189], v[18:21]
	v_mfma_f32_16x16x32_bf16 v[22:25], v[54:57], v[186:189], v[22:25]
	v_mfma_f32_16x16x32_bf16 v[26:29], v[46:49], v[216:219], v[26:29]
	v_mfma_f32_16x16x32_bf16 v[30:33], v[54:57], v[216:219], v[30:33]
	s_setprio 0
	s_barrier
	s_add_i32 s52, 0, 0x18000
	s_add_i32 s53, 0, 0x1c000
	v_add_u32_e32 v54, s52, v193
	v_add_u32_e32 v66, s53, v193
	ds_read_b128 v[42:45], v54
	ds_read_b128 v[46:49], v54 offset:1024
	ds_read_b128 v[50:53], v54 offset:2048
	ds_read_b128 v[54:57], v54 offset:3072
	ds_read_b128 v[182:185], v66
	ds_read_b128 v[186:189], v66 offset:1024
	ds_read_b128 v[212:215], v66 offset:2048
	ds_read_b128 v[216:219], v66 offset:3072
	s_add_u32 s34, s34, 0x20000
	s_addc_u32 s35, s35, 0
	s_mov_b32 m0, s39
	v_lshl_add_u64 v[236:237], s[34:35], 0, v[162:163]
	ds_read_b128 v[66:69], v199 offset:32768
	global_load_lds_dwordx4 v[236:237], off
	v_lshl_add_u64 v[236:237], s[34:35], 0, v[164:165]
	s_mov_b32 m0, s44
	s_nop 0
	global_load_lds_dwordx4 v[236:237], off
	ds_read_b128 v[70:73], v199 offset:33792
	ds_read_b128 v[82:85], v199 offset:34816
	ds_read_b128 v[86:89], v199 offset:35840
	ds_read_b128 v[220:223], v199 offset:36864
	ds_read_b128 v[224:227], v199 offset:37888
	ds_read_b128 v[228:231], v199 offset:38912
	ds_read_b128 v[232:235], v199 offset:39936
	s_waitcnt vmcnt(8)
	s_waitcnt lgkmcnt(0)
	s_barrier
	s_setprio 1
	s_waitcnt lgkmcnt(0)
	v_mfma_f32_16x16x32_bf16 v[158:161], v[42:45], v[66:69], v[158:161]
	v_mfma_f32_16x16x32_bf16 v[154:157], v[50:53], v[66:69], v[154:157]
	v_mfma_f32_16x16x32_bf16 v[142:145], v[42:45], v[82:85], v[142:145]
	v_mfma_f32_16x16x32_bf16 v[138:141], v[50:53], v[82:85], v[138:141]
	v_mfma_f32_16x16x32_bf16 v[126:129], v[42:45], v[220:223], v[126:129]
	v_mfma_f32_16x16x32_bf16 v[122:125], v[50:53], v[220:223], v[122:125]
	v_mfma_f32_16x16x32_bf16 v[110:113], v[42:45], v[228:231], v[110:113]
	v_mfma_f32_16x16x32_bf16 v[106:109], v[50:53], v[228:231], v[106:109]
	v_mfma_f32_16x16x32_bf16 v[158:161], v[46:49], v[70:73], v[158:161]
	v_mfma_f32_16x16x32_bf16 v[154:157], v[54:57], v[70:73], v[154:157]
	v_mfma_f32_16x16x32_bf16 v[142:145], v[46:49], v[86:89], v[142:145]
	v_mfma_f32_16x16x32_bf16 v[138:141], v[54:57], v[86:89], v[138:141]
	v_mfma_f32_16x16x32_bf16 v[126:129], v[46:49], v[224:227], v[126:129]
	v_mfma_f32_16x16x32_bf16 v[122:125], v[54:57], v[224:227], v[122:125]
	v_mfma_f32_16x16x32_bf16 v[110:113], v[46:49], v[232:235], v[110:113]
	v_mfma_f32_16x16x32_bf16 v[106:109], v[54:57], v[232:235], v[106:109]
	s_setprio 0
	s_setprio 1
	v_mfma_f32_16x16x32_bf16 v[150:153], v[182:185], v[66:69], v[150:153]
	v_mfma_f32_16x16x32_bf16 v[66:69], v[212:215], v[66:69], v[146:149]
	v_mfma_f32_16x16x32_bf16 v[146:149], v[216:219], v[70:73], v[66:69]
	v_mfma_f32_16x16x32_bf16 v[66:69], v[182:185], v[82:85], v[134:137]
	v_mfma_f32_16x16x32_bf16 v[134:137], v[186:189], v[86:89], v[66:69]
	v_mfma_f32_16x16x32_bf16 v[66:69], v[212:215], v[82:85], v[130:133]
	v_mfma_f32_16x16x32_bf16 v[130:133], v[216:219], v[86:89], v[66:69]
	v_mfma_f32_16x16x32_bf16 v[66:69], v[182:185], v[220:223], v[118:121]
	v_mfma_f32_16x16x32_bf16 v[118:121], v[186:189], v[224:227], v[66:69]
	v_mfma_f32_16x16x32_bf16 v[66:69], v[212:215], v[220:223], v[114:117]
	v_mfma_f32_16x16x32_bf16 v[114:117], v[216:219], v[224:227], v[66:69]
	v_mfma_f32_16x16x32_bf16 v[66:69], v[182:185], v[228:231], v[102:105]
	v_mfma_f32_16x16x32_bf16 v[102:105], v[186:189], v[232:235], v[66:69]
	v_mfma_f32_16x16x32_bf16 v[66:69], v[212:215], v[228:231], v[98:101]
	v_mfma_f32_16x16x32_bf16 v[150:153], v[186:189], v[70:73], v[150:153]
	v_mfma_f32_16x16x32_bf16 v[98:101], v[216:219], v[232:235], v[66:69]
	s_setprio 0
	s_barrier
; #define PG8_STAGE(bufoff, gbase, voff) do { _Pragma("unroll") for (int _i = 0; _i < 2; ++_i) \
;         __builtin_amdgcn_global_load_lds((const unsigned*)((const char*)(gbase) + (voff)[_i]), (LAS unsigned*)(lds + (bufoff) + ldsw + _i * 8192), 16, 0, 0); } while (0)
; #define PG8_LDA(dst, b, h) do { _Pragma("unroll") for (int m = 0; m < 4; ++m) _Pragma("unroll") for (int k = 0; k < 2; ++k) dst[m][k] = *(const LAS bf16x8*)(lds + PG8_SA(b, h) + aoff + m * 2048 + k * 1024); } while (0)
; #define PG8_MMA(ai, bj, At, Bt) do { __builtin_amdgcn_s_setprio(1); _Pragma("unroll") for (int m = 0; m < 4; ++m) _Pragma("unroll") for (int n = 0; n < 2; ++n) _Pragma("unroll") for (int k = 0; k < 2; ++k) \
;         acc[ai][bj][m][n] = __builtin_amdgcn_mfma_f32_16x16x32_bf16(Bt[n][k], At[m][k], acc[ai][bj][m][n], 0, 0, 0); __builtin_amdgcn_s_setprio(0); } while (0)
; #define PG8_WAIT_V(n) asm volatile("s_waitcnt vmcnt(" #n ")" ::: "memory")
; #define PG8_WAIT_L(n) asm volatile("s_waitcnt lgkmcnt(" #n ")" ::: "memory")
; #define PG8_BAR __builtin_amdgcn_s_barrier()
; #define PG8_SCHED __builtin_amdgcn_sched_barrier(0)
; template <class Epi>
; __device__ __forceinline__ void gemm_phase(LAS unsigned char* lds, const Gemm g, const StaticOrder& S, const Epi& E, const int tid) {
;     ...
;             PG8_LDA(At, 1, 1); PG8_STAGE(PG8_SB(1, 0), b3, voffB); PG8_STAGE(PG8_SB(1, 1), b3 + bhs, voffB); PG8_STAGE(PG8_SA(1, 0), a3, voffA);
;             PG8_WAIT_V(8); PG8_WAIT_L(0); PG8_BAR; PG8_MMA(1, 0, At, B0); PG8_MMA(1, 1, At, B1); PG8_BAR; PG8_SCHED;
;     ...
;         if (ALIGN_EPI) { if (wr == 0) PG8_BAR; }
	s_add_i32 s34, s52, s36
	v_lshl_add_u64 v[82:83], v[172:173], 0, s[70:71]
	s_mov_b32 m0, s34
	s_nop 0
	ds_read_b128 v[66:69], v199 offset:49152
	global_load_lds_dwordx4 v[82:83], off
	s_add_i32 m0, s34, 0x2000
	s_add_u32 s30, s30, 0x2080
	v_lshl_add_u64 v[82:83], v[174:175], 0, s[70:71]
	s_addc_u32 s31, s31, 0
	s_add_i32 s34, s53, s36
	global_load_lds_dwordx4 v[82:83], off
	v_lshl_add_u64 v[82:83], s[30:31], 0, v[0:1]
	s_mov_b32 m0, s34
	s_nop 0
	global_load_lds_dwordx4 v[82:83], off
	v_lshl_add_u64 v[82:83], s[30:31], 0, v[166:167]
	s_add_i32 m0, s34, 0x2000
	s_nop 0
	global_load_lds_dwordx4 v[82:83], off
	v_lshl_add_u64 v[82:83], v[176:177], 0, s[70:71]
	s_mov_b32 m0, s45
	s_nop 0
	global_load_lds_dwordx4 v[82:83], off
	v_lshl_add_u64 v[82:83], v[200:201], 0, s[70:71]
	s_mov_b32 m0, s46
	s_nop 0
	global_load_lds_dwordx4 v[82:83], off
	ds_read_b128 v[70:73], v199 offset:50176
	ds_read_b128 v[220:223], v199 offset:51200
	ds_read_b128 v[224:227], v199 offset:52224
	ds_read_b128 v[228:231], v199 offset:53248
	ds_read_b128 v[232:235], v199 offset:54272
	ds_read_b128 v[236:239], v199 offset:55296
	ds_read_b128 v[240:243], v199 offset:56320
	s_waitcnt vmcnt(8)
	s_waitcnt lgkmcnt(0)
	s_barrier
	s_setprio 1
	s_waitcnt lgkmcnt(0)
	v_mfma_f32_16x16x32_bf16 v[82:85], v[42:45], v[66:69], v[94:97]
	v_mfma_f32_16x16x32_bf16 v[94:97], v[46:49], v[70:73], v[82:85]
	v_mfma_f32_16x16x32_bf16 v[82:85], v[50:53], v[66:69], v[90:93]
	v_mfma_f32_16x16x32_bf16 v[78:81], v[42:45], v[220:223], v[78:81]
	v_mfma_f32_16x16x32_bf16 v[74:77], v[50:53], v[220:223], v[74:77]
	v_mfma_f32_16x16x32_bf16 v[62:65], v[42:45], v[228:231], v[62:65]
	v_mfma_f32_16x16x32_bf16 v[58:61], v[50:53], v[228:231], v[58:61]
	v_mfma_f32_16x16x32_bf16 v[14:17], v[42:45], v[236:239], v[14:17]
	v_mfma_f32_16x16x32_bf16 v[10:13], v[50:53], v[236:239], v[10:13]
	v_mfma_f32_16x16x32_bf16 v[90:93], v[54:57], v[70:73], v[82:85]
	v_mfma_f32_16x16x32_bf16 v[78:81], v[46:49], v[224:227], v[78:81]
	v_mfma_f32_16x16x32_bf16 v[74:77], v[54:57], v[224:227], v[74:77]
	v_mfma_f32_16x16x32_bf16 v[62:65], v[46:49], v[232:235], v[62:65]
	v_mfma_f32_16x16x32_bf16 v[58:61], v[54:57], v[232:235], v[58:61]
	v_mfma_f32_16x16x32_bf16 v[14:17], v[46:49], v[240:243], v[14:17]
	v_mfma_f32_16x16x32_bf16 v[10:13], v[54:57], v[240:243], v[10:13]
	s_setprio 0
	s_setprio 1
	v_mfma_f32_16x16x32_bf16 v[18:21], v[182:185], v[66:69], v[18:21]
	v_mfma_f32_16x16x32_bf16 v[86:89], v[186:189], v[70:73], v[18:21]
	v_mfma_f32_16x16x32_bf16 v[18:21], v[212:215], v[66:69], v[22:25]
	v_mfma_f32_16x16x32_bf16 v[82:85], v[216:219], v[70:73], v[18:21]
	v_mfma_f32_16x16x32_bf16 v[18:21], v[182:185], v[220:223], v[26:29]
	v_mfma_f32_16x16x32_bf16 v[70:73], v[186:189], v[224:227], v[18:21]
	v_mfma_f32_16x16x32_bf16 v[18:21], v[212:215], v[220:223], v[30:33]
	v_mfma_f32_16x16x32_bf16 v[66:69], v[216:219], v[224:227], v[18:21]
	v_mfma_f32_16x16x32_bf16 v[18:21], v[182:185], v[228:231], v[38:41]
	v_mfma_f32_16x16x32_bf16 v[38:41], v[186:189], v[232:235], v[18:21]
	v_mfma_f32_16x16x32_bf16 v[18:21], v[212:215], v[228:231], v[34:37]
	v_mfma_f32_16x16x32_bf16 v[6:9], v[182:185], v[236:239], v[6:9]
	v_mfma_f32_16x16x32_bf16 v[2:5], v[212:215], v[236:239], v[2:5]
	v_mfma_f32_16x16x32_bf16 v[34:37], v[216:219], v[232:235], v[18:21]
	v_mfma_f32_16x16x32_bf16 v[6:9], v[186:189], v[240:243], v[6:9]
	v_mfma_f32_16x16x32_bf16 v[2:5], v[216:219], v[240:243], v[2:5]
	s_setprio 0
	s_barrier
	s_add_i32 s51, s51, 2
	s_add_u32 s49, s49, 0x100
	s_addc_u32 s50, s50, 0
	s_add_u32 s28, s28, 0x100
	s_addc_u32 s29, s29, 0
	s_cmp_gt_u32 s51, 5
	s_cbranch_scc0 .LBB0_206
	s_and_b64 vcc, exec, s[12:13]
	s_cbranch_vccz .LBB0_209
	s_barrier

; #define PG8_STAGE(bufoff, gbase, voff) do { _Pragma("unroll") for (int _i = 0; _i < 2; ++_i) \
;         __builtin_amdgcn_global_load_lds((const unsigned*)((const char*)(gbase) + (voff)[_i]), (LAS unsigned*)(lds + (bufoff) + ldsw + _i * 8192), 16, 0, 0); } while (0)
; #define PG8_LDA(dst, b, h) do { _Pragma("unroll") for (int m = 0; m < 4; ++m) _Pragma("unroll") for (int k = 0; k < 2; ++k) dst[m][k] = *(const LAS bf16x8*)(lds + PG8_SA(b, h) + aoff + m * 2048 + k * 1024); } while (0)
; #define PG8_LDB(dst, b, h) do { _Pragma("unroll") for (int n = 0; n < 2; ++n) _Pragma("unroll") for (int k = 0; k < 2; ++k) dst[n][k] = *(const LAS bf16x8*)(lds + PG8_SB(b, h) + boff + n * 2048 + k * 1024); } while (0)
; #define PG8_MMA(ai, bj, At, Bt) do { __builtin_amdgcn_s_setprio(1); _Pragma("unroll") for (int m = 0; m < 4; ++m) _Pragma("unroll") for (int n = 0; n < 2; ++n) _Pragma("unroll") for (int k = 0; k < 2; ++k) \
;         acc[ai][bj][m][n] = __builtin_amdgcn_mfma_f32_16x16x32_bf16(Bt[n][k], At[m][k], acc[ai][bj][m][n], 0, 0, 0); __builtin_amdgcn_s_setprio(0); } while (0)
; #define PG8_WAIT_V(n) asm volatile("s_waitcnt vmcnt(" #n ")" ::: "memory")
; #define PG8_WAIT_L(n) asm volatile("s_waitcnt lgkmcnt(" #n ")" ::: "memory")
; #define PG8_BAR __builtin_amdgcn_s_barrier()
; template <class Epi>
; __device__ __forceinline__ void gemm_phase(LAS unsigned char* lds, const Gemm g, const StaticOrder& S, const Epi& E, const int tid) {
;     ...
;             const char* a2 = last ? nA : (s2 ? cA2 + (size_t)(t + 2 - nt) * kstep : cA + (size_t)(t + 2) * kstep);
;             const char* b2 = last ? nB : (s2 ? cB2 + (size_t)(t + 2 - nt) * kstep : cB + (size_t)(t + 2) * kstep);
;             const char* a3 = a2 + kstep; const char* b3 = b2 + kstep;
;             if constexpr (Epi::TWO) { if (t == nt) E.mid(acc, cur, wr, wc, fr, fq); }
;             if constexpr (SP2) {
;             PG8_LDB(B0, 0, 0); PG8_LDB(B1, 0, 1); PG8_SCHED; PG8_LDA(At, 0, 0); PG8_STAGE(PG8_SA(1, 1), a1 + hstep, voffA);
;             PG8_WAIT_V(8); PG8_WAIT_L(0); PG8_BAR; PG8_MMA(0, 0, At, B0); PG8_MMA(0, 1, At, B1); PG8_BAR; PG8_SCHED;
;             PG8_LDA(At, 0, 1); PG8_STAGE(PG8_SB(0, 0), b2, voffB); PG8_STAGE(PG8_SB(0, 1), b2 + bhs, voffB); PG8_STAGE(PG8_SA(0, 0), a2, voffA);
;             PG8_WAIT_V(8); PG8_WAIT_L(0); PG8_BAR; PG8_MMA(1, 0, At, B0); PG8_MMA(1, 1, At, B1); PG8_BAR; PG8_SCHED;
.LBB0_261:
	s_add_u32 s30, s28, 0xfff80080
	s_addc_u32 s31, s29, -1
	s_add_i32 s49, 0, 0x10000
	s_cmp_eq_u32 s48, 28
	s_cselect_b32 s35, s19, s31
	s_cselect_b32 s34, s44, s30
	v_add_u32_e32 v142, s49, v149
	s_cselect_b32 s31, s17, s47
	s_cselect_b32 s30, s45, s46
	s_add_i32 s52, 0, 0x14000
	ds_read_b128 v[156:159], v142
	ds_read_b128 v[160:163], v142 offset:1024
	ds_read_b128 v[164:167], v142 offset:2048
	ds_read_b128 v[178:181], v142 offset:3072
	v_add_u32_e32 v142, s52, v149
	ds_read_b128 v[182:185], v142
	ds_read_b128 v[186:189], v142 offset:1024
	ds_read_b128 v[190:193], v142 offset:2048
	ds_read_b128 v[194:197], v142 offset:3072
	v_lshl_add_u64 v[142:143], s[28:29], 0, v[140:141]
	s_add_i32 m0, s2, 0xc000
	ds_read_b128 v[198:201], v154
	global_load_lds_dwordx4 v[142:143], off
	v_lshl_add_u64 v[142:143], s[28:29], 0, v[138:139]
	s_add_i32 m0, s2, 0xe000
	s_nop 0
	global_load_lds_dwordx4 v[142:143], off
	ds_read_b128 v[212:215], v154 offset:1024
	ds_read_b128 v[216:219], v154 offset:2048
	ds_read_b128 v[220:223], v154 offset:3072
	ds_read_b128 v[224:227], v154 offset:4096
	ds_read_b128 v[228:231], v154 offset:5120
	ds_read_b128 v[232:235], v154 offset:6144
	ds_read_b128 v[236:239], v154 offset:7168
	s_waitcnt vmcnt(8)
	s_waitcnt lgkmcnt(0)
	s_barrier
	s_setprio 1
	s_waitcnt lgkmcnt(0)
	v_mfma_f32_16x16x32_bf16 v[126:129], v[156:159], v[198:201], v[126:129]
	v_mfma_f32_16x16x32_bf16 v[122:125], v[164:167], v[198:201], v[122:125]
	v_mfma_f32_16x16x32_bf16 v[110:113], v[156:159], v[216:219], v[110:113]
	v_mfma_f32_16x16x32_bf16 v[106:109], v[164:167], v[216:219], v[106:109]
	v_mfma_f32_16x16x32_bf16 v[94:97], v[156:159], v[224:227], v[94:97]
	v_mfma_f32_16x16x32_bf16 v[90:93], v[164:167], v[224:227], v[90:93]
	v_mfma_f32_16x16x32_bf16 v[78:81], v[156:159], v[232:235], v[78:81]
	v_mfma_f32_16x16x32_bf16 v[74:77], v[164:167], v[232:235], v[74:77]
	v_mfma_f32_16x16x32_bf16 v[126:129], v[160:163], v[212:215], v[126:129]
	v_mfma_f32_16x16x32_bf16 v[122:125], v[178:181], v[212:215], v[122:125]
	v_mfma_f32_16x16x32_bf16 v[110:113], v[160:163], v[220:223], v[110:113]
	v_mfma_f32_16x16x32_bf16 v[106:109], v[178:181], v[220:223], v[106:109]
	v_mfma_f32_16x16x32_bf16 v[94:97], v[160:163], v[228:231], v[94:97]
	v_mfma_f32_16x16x32_bf16 v[90:93], v[178:181], v[228:231], v[90:93]
	v_mfma_f32_16x16x32_bf16 v[78:81], v[160:163], v[236:239], v[78:81]
	v_mfma_f32_16x16x32_bf16 v[74:77], v[178:181], v[236:239], v[74:77]
	s_setprio 0
	s_setprio 1
	v_mfma_f32_16x16x32_bf16 v[118:121], v[182:185], v[198:201], v[118:121]
	v_mfma_f32_16x16x32_bf16 v[114:117], v[190:193], v[198:201], v[114:117]
	v_mfma_f32_16x16x32_bf16 v[102:105], v[182:185], v[216:219], v[102:105]
	v_mfma_f32_16x16x32_bf16 v[98:101], v[190:193], v[216:219], v[98:101]
	v_mfma_f32_16x16x32_bf16 v[86:89], v[182:185], v[224:227], v[86:89]
	v_mfma_f32_16x16x32_bf16 v[82:85], v[190:193], v[224:227], v[82:85]
	v_mfma_f32_16x16x32_bf16 v[70:73], v[182:185], v[232:235], v[70:73]
	v_mfma_f32_16x16x32_bf16 v[66:69], v[190:193], v[232:235], v[66:69]
	v_mfma_f32_16x16x32_bf16 v[118:121], v[186:189], v[212:215], v[118:121]
	v_mfma_f32_16x16x32_bf16 v[114:117], v[194:197], v[212:215], v[114:117]
	v_mfma_f32_16x16x32_bf16 v[102:105], v[186:189], v[220:223], v[102:105]
	v_mfma_f32_16x16x32_bf16 v[98:101], v[194:197], v[220:223], v[98:101]
	v_mfma_f32_16x16x32_bf16 v[86:89], v[186:189], v[228:231], v[86:89]
	v_mfma_f32_16x16x32_bf16 v[82:85], v[194:197], v[228:231], v[82:85]
	v_mfma_f32_16x16x32_bf16 v[70:73], v[186:189], v[236:239], v[70:73]
	v_mfma_f32_16x16x32_bf16 v[66:69], v[194:197], v[236:239], v[66:69]
	s_setprio 0
	s_barrier
	s_add_i32 s49, s49, s36
	v_lshl_add_u64 v[142:143], s[30:31], 0, v[0:1]
	s_mov_b32 m0, s49
	ds_read_b128 v[198:201], v154 offset:16384
	global_load_lds_dwordx4 v[142:143], off
	s_add_i32 m0, s49, 0x2000
	s_add_u32 s50, s30, 0x8000
	v_lshl_add_u64 v[168:169], s[30:31], 0, v[134:135]
	s_addc_u32 s51, s31, 0
	s_add_i32 s49, s52, s36
	global_load_lds_dwordx4 v[168:169], off
	v_lshl_add_u64 v[172:173], s[50:51], 0, v[0:1]
	s_mov_b32 m0, s49
	v_lshl_add_u64 v[174:175], s[34:35], 0, v[132:133]
	global_load_lds_dwordx4 v[172:173], off
	v_lshl_add_u64 v[172:173], s[50:51], 0, v[134:135]
	s_add_i32 m0, s49, 0x2000
	s_nop 0
	global_load_lds_dwordx4 v[172:173], off
	v_lshl_add_u64 v[172:173], s[34:35], 0, v[130:131]
	s_mov_b32 m0, s2
	s_nop 0
	global_load_lds_dwordx4 v[172:173], off
	s_mov_b32 m0, s27
	s_nop 0
	global_load_lds_dwordx4 v[174:175], off
	ds_read_b128 v[212:215], v154 offset:17408
	ds_read_b128 v[216:219], v154 offset:18432
	ds_read_b128 v[220:223], v154 offset:19456
	ds_read_b128 v[224:227], v154 offset:20480
	ds_read_b128 v[228:231], v154 offset:21504
	ds_read_b128 v[232:235], v154 offset:22528
	ds_read_b128 v[236:239], v154 offset:23552
	s_waitcnt vmcnt(8)
	s_waitcnt lgkmcnt(0)
	s_barrier
; #define PG8_STAGE(bufoff, gbase, voff) do { _Pragma("unroll") for (int _i = 0; _i < 2; ++_i) \
;         __builtin_amdgcn_global_load_lds((const unsigned*)((const char*)(gbase) + (voff)[_i]), (LAS unsigned*)(lds + (bufoff) + ldsw + _i * 8192), 16, 0, 0); } while (0)
; #define PG8_LDA(dst, b, h) do { _Pragma("unroll") for (int m = 0; m < 4; ++m) _Pragma("unroll") for (int k = 0; k < 2; ++k) dst[m][k] = *(const LAS bf16x8*)(lds + PG8_SA(b, h) + aoff + m * 2048 + k * 1024); } while (0)
; #define PG8_LDB(dst, b, h) do { _Pragma("unroll") for (int n = 0; n < 2; ++n) _Pragma("unroll") for (int k = 0; k < 2; ++k) dst[n][k] = *(const LAS bf16x8*)(lds + PG8_SB(b, h) + boff + n * 2048 + k * 1024); } while (0)
; #define PG8_MMA(ai, bj, At, Bt) do { __builtin_amdgcn_s_setprio(1); _Pragma("unroll") for (int m = 0; m < 4; ++m) _Pragma("unroll") for (int n = 0; n < 2; ++n) _Pragma("unroll") for (int k = 0; k < 2; ++k) \
;         acc[ai][bj][m][n] = __builtin_amdgcn_mfma_f32_16x16x32_bf16(Bt[n][k], At[m][k], acc[ai][bj][m][n], 0, 0, 0); __builtin_amdgcn_s_setprio(0); } while (0)
; #define PG8_WAIT_V(n) asm volatile("s_waitcnt vmcnt(" #n ")" ::: "memory")
; #define PG8_WAIT_L(n) asm volatile("s_waitcnt lgkmcnt(" #n ")" ::: "memory")
; #define PG8_BAR __builtin_amdgcn_s_barrier()
; #define PG8_SCHED __builtin_amdgcn_sched_barrier(0)
; template <class Epi>
; __device__ __forceinline__ void gemm_phase(LAS unsigned char* lds, const Gemm g, const StaticOrder& S, const Epi& E, const int tid) {
;     ...
;             PG8_WAIT_V(8); PG8_WAIT_L(0); PG8_BAR; PG8_MMA(1, 0, At, B0); PG8_MMA(1, 1, At, B1); PG8_BAR; PG8_SCHED;
;             PG8_LDB(B0, 1, 0); PG8_LDB(B1, 1, 1); PG8_SCHED; PG8_LDA(At, 1, 0); PG8_STAGE(PG8_SA(0, 1), a2 + hstep, voffA);
;             PG8_WAIT_V(8); PG8_WAIT_L(0); PG8_BAR; PG8_MMA(0, 0, At, B0); PG8_MMA(0, 1, At, B1); PG8_BAR; PG8_SCHED;
	s_setprio 1
	s_waitcnt lgkmcnt(0)
	v_mfma_f32_16x16x32_bf16 v[62:65], v[156:159], v[198:201], v[62:65]
	v_mfma_f32_16x16x32_bf16 v[58:61], v[164:167], v[198:201], v[58:61]
	v_mfma_f32_16x16x32_bf16 v[46:49], v[156:159], v[216:219], v[46:49]
	v_mfma_f32_16x16x32_bf16 v[42:45], v[164:167], v[216:219], v[42:45]
	v_mfma_f32_16x16x32_bf16 v[30:33], v[156:159], v[224:227], v[30:33]
	v_mfma_f32_16x16x32_bf16 v[26:29], v[164:167], v[224:227], v[26:29]
	v_mfma_f32_16x16x32_bf16 v[14:17], v[156:159], v[232:235], v[14:17]
	v_mfma_f32_16x16x32_bf16 v[10:13], v[164:167], v[232:235], v[10:13]
	v_mfma_f32_16x16x32_bf16 v[62:65], v[160:163], v[212:215], v[62:65]
	v_mfma_f32_16x16x32_bf16 v[58:61], v[178:181], v[212:215], v[58:61]
	v_mfma_f32_16x16x32_bf16 v[46:49], v[160:163], v[220:223], v[46:49]
	v_mfma_f32_16x16x32_bf16 v[42:45], v[178:181], v[220:223], v[42:45]
	v_mfma_f32_16x16x32_bf16 v[30:33], v[160:163], v[228:231], v[30:33]
	v_mfma_f32_16x16x32_bf16 v[26:29], v[178:181], v[228:231], v[26:29]
	v_mfma_f32_16x16x32_bf16 v[14:17], v[160:163], v[236:239], v[14:17]
	v_mfma_f32_16x16x32_bf16 v[10:13], v[178:181], v[236:239], v[10:13]
	s_setprio 0
	s_setprio 1
	v_mfma_f32_16x16x32_bf16 v[54:57], v[182:185], v[198:201], v[54:57]
	v_mfma_f32_16x16x32_bf16 v[50:53], v[190:193], v[198:201], v[50:53]
	v_mfma_f32_16x16x32_bf16 v[38:41], v[182:185], v[216:219], v[38:41]
	v_mfma_f32_16x16x32_bf16 v[34:37], v[190:193], v[216:219], v[34:37]
	v_mfma_f32_16x16x32_bf16 v[22:25], v[182:185], v[224:227], v[22:25]
	v_mfma_f32_16x16x32_bf16 v[18:21], v[190:193], v[224:227], v[18:21]
	v_mfma_f32_16x16x32_bf16 v[6:9], v[182:185], v[232:235], v[6:9]
	v_mfma_f32_16x16x32_bf16 v[2:5], v[190:193], v[232:235], v[2:5]
	v_mfma_f32_16x16x32_bf16 v[54:57], v[186:189], v[212:215], v[54:57]
	v_mfma_f32_16x16x32_bf16 v[50:53], v[194:197], v[212:215], v[50:53]
	v_mfma_f32_16x16x32_bf16 v[38:41], v[186:189], v[220:223], v[38:41]
	v_mfma_f32_16x16x32_bf16 v[34:37], v[194:197], v[220:223], v[34:37]
	v_mfma_f32_16x16x32_bf16 v[22:25], v[186:189], v[228:231], v[22:25]
	v_mfma_f32_16x16x32_bf16 v[18:21], v[194:197], v[228:231], v[18:21]
	v_mfma_f32_16x16x32_bf16 v[6:9], v[186:189], v[236:239], v[6:9]
	v_mfma_f32_16x16x32_bf16 v[2:5], v[194:197], v[236:239], v[2:5]
	s_setprio 0
	s_barrier
	s_add_i32 s49, 0, 0x18000
	v_add_u32_e32 v155, s49, v149
	s_add_i32 s50, 0, 0x1c000
	ds_read_b128 v[156:159], v155
	ds_read_b128 v[160:163], v155 offset:1024
	ds_read_b128 v[164:167], v155 offset:2048
	ds_read_b128 v[178:181], v155 offset:3072
	v_add_u32_e32 v155, s50, v149
	ds_read_b128 v[182:185], v155
	ds_read_b128 v[186:189], v155 offset:1024
	ds_read_b128 v[190:193], v155 offset:2048
	ds_read_b128 v[194:197], v155 offset:3072
	s_add_u32 s34, s34, 0x80000
	s_addc_u32 s35, s35, 0
	s_mov_b32 m0, s37
	v_lshl_add_u64 v[176:177], s[34:35], 0, v[130:131]
	ds_read_b128 v[198:201], v154 offset:32768
	global_load_lds_dwordx4 v[176:177], off
	v_lshl_add_u64 v[176:177], s[34:35], 0, v[132:133]
	s_mov_b32 m0, s38
	s_nop 0
	global_load_lds_dwordx4 v[176:177], off
	ds_read_b128 v[212:215], v154 offset:33792
	ds_read_b128 v[216:219], v154 offset:34816
	ds_read_b128 v[220:223], v154 offset:35840
	ds_read_b128 v[224:227], v154 offset:36864
	ds_read_b128 v[228:231], v154 offset:37888
	ds_read_b128 v[232:235], v154 offset:38912
	ds_read_b128 v[236:239], v154 offset:39936
	s_waitcnt vmcnt(8)
	s_waitcnt lgkmcnt(0)
	s_barrier
	s_setprio 1
	s_waitcnt lgkmcnt(0)
	v_mfma_f32_16x16x32_bf16 v[126:129], v[156:159], v[198:201], v[126:129]
	v_mfma_f32_16x16x32_bf16 v[122:125], v[164:167], v[198:201], v[122:125]
	v_mfma_f32_16x16x32_bf16 v[110:113], v[156:159], v[216:219], v[110:113]
	v_mfma_f32_16x16x32_bf16 v[106:109], v[164:167], v[216:219], v[106:109]
	v_mfma_f32_16x16x32_bf16 v[94:97], v[156:159], v[224:227], v[94:97]
	v_mfma_f32_16x16x32_bf16 v[90:93], v[164:167], v[224:227], v[90:93]
	v_mfma_f32_16x16x32_bf16 v[78:81], v[156:159], v[232:235], v[78:81]
	v_mfma_f32_16x16x32_bf16 v[74:77], v[164:167], v[232:235], v[74:77]
	v_mfma_f32_16x16x32_bf16 v[126:129], v[160:163], v[212:215], v[126:129]
	v_mfma_f32_16x16x32_bf16 v[122:125], v[178:181], v[212:215], v[122:125]
	v_mfma_f32_16x16x32_bf16 v[110:113], v[160:163], v[220:223], v[110:113]
	v_mfma_f32_16x16x32_bf16 v[106:109], v[178:181], v[220:223], v[106:109]
	v_mfma_f32_16x16x32_bf16 v[94:97], v[160:163], v[228:231], v[94:97]
	v_mfma_f32_16x16x32_bf16 v[90:93], v[178:181], v[228:231], v[90:93]
	v_mfma_f32_16x16x32_bf16 v[78:81], v[160:163], v[236:239], v[78:81]
	v_mfma_f32_16x16x32_bf16 v[74:77], v[178:181], v[236:239], v[74:77]
	s_setprio 0
	s_setprio 1
	v_mfma_f32_16x16x32_bf16 v[118:121], v[182:185], v[198:201], v[118:121]
	v_mfma_f32_16x16x32_bf16 v[114:117], v[190:193], v[198:201], v[114:117]
	v_mfma_f32_16x16x32_bf16 v[102:105], v[182:185], v[216:219], v[102:105]
	v_mfma_f32_16x16x32_bf16 v[98:101], v[190:193], v[216:219], v[98:101]
	v_mfma_f32_16x16x32_bf16 v[86:89], v[182:185], v[224:227], v[86:89]
	v_mfma_f32_16x16x32_bf16 v[82:85], v[190:193], v[224:227], v[82:85]
	v_mfma_f32_16x16x32_bf16 v[70:73], v[182:185], v[232:235], v[70:73]
	v_mfma_f32_16x16x32_bf16 v[66:69], v[190:193], v[232:235], v[66:69]
	v_mfma_f32_16x16x32_bf16 v[118:121], v[186:189], v[212:215], v[118:121]
	v_mfma_f32_16x16x32_bf16 v[114:117], v[194:197], v[212:215], v[114:117]
	v_mfma_f32_16x16x32_bf16 v[102:105], v[186:189], v[220:223], v[102:105]
	v_mfma_f32_16x16x32_bf16 v[98:101], v[194:197], v[220:223], v[98:101]
	v_mfma_f32_16x16x32_bf16 v[86:89], v[186:189], v[228:231], v[86:89]
	v_mfma_f32_16x16x32_bf16 v[82:85], v[194:197], v[228:231], v[82:85]
	v_mfma_f32_16x16x32_bf16 v[70:73], v[186:189], v[236:239], v[70:73]
	v_mfma_f32_16x16x32_bf16 v[66:69], v[194:197], v[236:239], v[66:69]
	s_setprio 0
	s_barrier
; #define PG8_STAGE(bufoff, gbase, voff) do { _Pragma("unroll") for (int _i = 0; _i < 2; ++_i) \
;         __builtin_amdgcn_global_load_lds((const unsigned*)((const char*)(gbase) + (voff)[_i]), (LAS unsigned*)(lds + (bufoff) + ldsw + _i * 8192), 16, 0, 0); } while (0)
; #define PG8_LDA(dst, b, h) do { _Pragma("unroll") for (int m = 0; m < 4; ++m) _Pragma("unroll") for (int k = 0; k < 2; ++k) dst[m][k] = *(const LAS bf16x8*)(lds + PG8_SA(b, h) + aoff + m * 2048 + k * 1024); } while (0)
; #define PG8_MMA(ai, bj, At, Bt) do { __builtin_amdgcn_s_setprio(1); _Pragma("unroll") for (int m = 0; m < 4; ++m) _Pragma("unroll") for (int n = 0; n < 2; ++n) _Pragma("unroll") for (int k = 0; k < 2; ++k) \
;         acc[ai][bj][m][n] = __builtin_amdgcn_mfma_f32_16x16x32_bf16(Bt[n][k], At[m][k], acc[ai][bj][m][n], 0, 0, 0); __builtin_amdgcn_s_setprio(0); } while (0)
; #define PG8_WAIT_V(n) asm volatile("s_waitcnt vmcnt(" #n ")" ::: "memory")
; #define PG8_WAIT_L(n) asm volatile("s_waitcnt lgkmcnt(" #n ")" ::: "memory")
; #define PG8_BAR __builtin_amdgcn_s_barrier()
; #define PG8_SCHED __builtin_amdgcn_sched_barrier(0)
; template <class Epi>
; __device__ __forceinline__ void gemm_phase(LAS unsigned char* lds, const Gemm g, const StaticOrder& S, const Epi& E, const int tid) {
;     ...
;             PG8_LDA(At, 1, 1); PG8_STAGE(PG8_SB(1, 0), b3, voffB); PG8_STAGE(PG8_SB(1, 1), b3 + bhs, voffB); PG8_STAGE(PG8_SA(1, 0), a3, voffA);
;             PG8_WAIT_V(8); PG8_WAIT_L(0); PG8_BAR; PG8_MMA(1, 0, At, B0); PG8_MMA(1, 1, At, B1); PG8_BAR; PG8_SCHED;
;     ...
;         if (ALIGN_EPI) { if (wr == 0) PG8_BAR; }
	s_add_i32 s34, s49, s36
	v_lshl_add_u64 v[142:143], v[142:143], 0, s[70:71]
	s_mov_b32 m0, s34
	ds_read_b128 v[198:201], v154 offset:49152
	global_load_lds_dwordx4 v[142:143], off
	s_add_i32 m0, s34, 0x2000
	s_add_u32 s30, s30, 0x8080
	v_lshl_add_u64 v[142:143], v[168:169], 0, s[70:71]
	s_addc_u32 s31, s31, 0
	s_add_i32 s34, s50, s36
	global_load_lds_dwordx4 v[142:143], off
	v_lshl_add_u64 v[142:143], s[30:31], 0, v[0:1]
	s_mov_b32 m0, s34
	s_nop 0
	global_load_lds_dwordx4 v[142:143], off
	v_lshl_add_u64 v[142:143], s[30:31], 0, v[134:135]
	s_add_i32 m0, s34, 0x2000
	s_nop 0
	global_load_lds_dwordx4 v[142:143], off
	v_lshl_add_u64 v[142:143], v[172:173], 0, s[70:71]
	s_mov_b32 m0, s39
	s_nop 0
	global_load_lds_dwordx4 v[142:143], off
	v_lshl_add_u64 v[142:143], v[174:175], 0, s[70:71]
	s_mov_b32 m0, s40
	s_nop 0
	global_load_lds_dwordx4 v[142:143], off
	ds_read_b128 v[212:215], v154 offset:50176
	ds_read_b128 v[216:219], v154 offset:51200
	ds_read_b128 v[220:223], v154 offset:52224
	ds_read_b128 v[224:227], v154 offset:53248
	ds_read_b128 v[228:231], v154 offset:54272
	ds_read_b128 v[232:235], v154 offset:55296
	ds_read_b128 v[236:239], v154 offset:56320
	s_waitcnt vmcnt(8)
	s_waitcnt lgkmcnt(0)
	s_barrier
	s_setprio 1
	s_waitcnt lgkmcnt(0)
	v_mfma_f32_16x16x32_bf16 v[62:65], v[156:159], v[198:201], v[62:65]
	v_mfma_f32_16x16x32_bf16 v[58:61], v[164:167], v[198:201], v[58:61]
	v_mfma_f32_16x16x32_bf16 v[46:49], v[156:159], v[216:219], v[46:49]
	v_mfma_f32_16x16x32_bf16 v[42:45], v[164:167], v[216:219], v[42:45]
	v_mfma_f32_16x16x32_bf16 v[30:33], v[156:159], v[224:227], v[30:33]
	v_mfma_f32_16x16x32_bf16 v[26:29], v[164:167], v[224:227], v[26:29]
	v_mfma_f32_16x16x32_bf16 v[14:17], v[156:159], v[232:235], v[14:17]
	v_mfma_f32_16x16x32_bf16 v[10:13], v[164:167], v[232:235], v[10:13]
	v_mfma_f32_16x16x32_bf16 v[62:65], v[160:163], v[212:215], v[62:65]
	v_mfma_f32_16x16x32_bf16 v[58:61], v[178:181], v[212:215], v[58:61]
	v_mfma_f32_16x16x32_bf16 v[46:49], v[160:163], v[220:223], v[46:49]
	v_mfma_f32_16x16x32_bf16 v[42:45], v[178:181], v[220:223], v[42:45]
	v_mfma_f32_16x16x32_bf16 v[30:33], v[160:163], v[228:231], v[30:33]
	v_mfma_f32_16x16x32_bf16 v[26:29], v[178:181], v[228:231], v[26:29]
	v_mfma_f32_16x16x32_bf16 v[14:17], v[160:163], v[236:239], v[14:17]
	v_mfma_f32_16x16x32_bf16 v[10:13], v[178:181], v[236:239], v[10:13]
	s_setprio 0
	s_setprio 1
	v_mfma_f32_16x16x32_bf16 v[54:57], v[182:185], v[198:201], v[54:57]
	v_mfma_f32_16x16x32_bf16 v[50:53], v[190:193], v[198:201], v[50:53]
	v_mfma_f32_16x16x32_bf16 v[38:41], v[182:185], v[216:219], v[38:41]
	v_mfma_f32_16x16x32_bf16 v[34:37], v[190:193], v[216:219], v[34:37]
	v_mfma_f32_16x16x32_bf16 v[22:25], v[182:185], v[224:227], v[22:25]
	v_mfma_f32_16x16x32_bf16 v[18:21], v[190:193], v[224:227], v[18:21]
	v_mfma_f32_16x16x32_bf16 v[6:9], v[182:185], v[232:235], v[6:9]
	v_mfma_f32_16x16x32_bf16 v[2:5], v[190:193], v[232:235], v[2:5]
	v_mfma_f32_16x16x32_bf16 v[54:57], v[186:189], v[212:215], v[54:57]
	v_mfma_f32_16x16x32_bf16 v[50:53], v[194:197], v[212:215], v[50:53]
	v_mfma_f32_16x16x32_bf16 v[38:41], v[186:189], v[220:223], v[38:41]
	v_mfma_f32_16x16x32_bf16 v[34:37], v[194:197], v[220:223], v[34:37]
	v_mfma_f32_16x16x32_bf16 v[22:25], v[186:189], v[228:231], v[22:25]
	v_mfma_f32_16x16x32_bf16 v[18:21], v[194:197], v[228:231], v[18:21]
	v_mfma_f32_16x16x32_bf16 v[6:9], v[186:189], v[236:239], v[6:9]
	v_mfma_f32_16x16x32_bf16 v[2:5], v[194:197], v[236:239], v[2:5]
	s_setprio 0
	s_barrier
	s_add_i32 s48, s48, 2
	s_add_u32 s46, s46, 0x100
	s_addc_u32 s47, s47, 0
	s_add_u32 s28, s28, 0x100
	s_addc_u32 s29, s29, 0
	s_cmp_gt_u32 s48, 29
	s_cbranch_scc0 .LBB0_261
	s_and_b64 vcc, exec, s[14:15]
	s_cbranch_vccz .LBB0_264
	s_barrier

; #define PG8_STAGE(bufoff, gbase, voff) do { _Pragma("unroll") for (int _i = 0; _i < 2; ++_i) \
;         __builtin_amdgcn_global_load_lds((const unsigned*)((const char*)(gbase) + (voff)[_i]), (LAS unsigned*)(lds + (bufoff) + ldsw + _i * 8192), 16, 0, 0); } while (0)
; #define PG8_LDA(dst, b, h) do { _Pragma("unroll") for (int m = 0; m < 4; ++m) _Pragma("unroll") for (int k = 0; k < 2; ++k) dst[m][k] = *(const LAS bf16x8*)(lds + PG8_SA(b, h) + aoff + m * 2048 + k * 1024); } while (0)
; #define PG8_LDB(dst, b, h) do { _Pragma("unroll") for (int n = 0; n < 2; ++n) _Pragma("unroll") for (int k = 0; k < 2; ++k) dst[n][k] = *(const LAS bf16x8*)(lds + PG8_SB(b, h) + boff + n * 2048 + k * 1024); } while (0)
; #define PG8_MMA(ai, bj, At, Bt) do { __builtin_amdgcn_s_setprio(1); _Pragma("unroll") for (int m = 0; m < 4; ++m) _Pragma("unroll") for (int n = 0; n < 2; ++n) _Pragma("unroll") for (int k = 0; k < 2; ++k) \
;         acc[ai][bj][m][n] = __builtin_amdgcn_mfma_f32_16x16x32_bf16(Bt[n][k], At[m][k], acc[ai][bj][m][n], 0, 0, 0); __builtin_amdgcn_s_setprio(0); } while (0)
; #define PG8_WAIT_V(n) asm volatile("s_waitcnt vmcnt(" #n ")" ::: "memory")
; #define PG8_WAIT_L(n) asm volatile("s_waitcnt lgkmcnt(" #n ")" ::: "memory")
; #define PG8_BAR __builtin_amdgcn_s_barrier()
; template <class Epi>
; __device__ __forceinline__ void gemm_phase(LAS unsigned char* lds, const Gemm g, const StaticOrder& S, const Epi& E, const int tid) {
;     ...
;             const char* a2 = last ? nA : (s2 ? cA2 + (size_t)(t + 2 - nt) * kstep : cA + (size_t)(t + 2) * kstep);
;             const char* b2 = last ? nB : (s2 ? cB2 + (size_t)(t + 2 - nt) * kstep : cB + (size_t)(t + 2) * kstep);
;             const char* a3 = a2 + kstep; const char* b3 = b2 + kstep;
;             if constexpr (Epi::TWO) { if (t == nt) E.mid(acc, cur, wr, wc, fr, fq); }
;             if constexpr (SP2) {
;             PG8_LDB(B0, 0, 0); PG8_LDB(B1, 0, 1); PG8_SCHED; PG8_LDA(At, 0, 0); PG8_STAGE(PG8_SA(1, 1), a1 + hstep, voffA);
;             PG8_WAIT_V(8); PG8_WAIT_L(0); PG8_BAR; PG8_MMA(0, 0, At, B0); PG8_MMA(0, 1, At, B1); PG8_BAR; PG8_SCHED;
;             PG8_LDA(At, 0, 1); PG8_STAGE(PG8_SB(0, 0), b2, voffB); PG8_STAGE(PG8_SB(0, 1), b2 + bhs, voffB); PG8_STAGE(PG8_SA(0, 0), a2, voffA);
;             PG8_WAIT_V(8); PG8_WAIT_L(0); PG8_BAR; PG8_MMA(1, 0, At, B0); PG8_MMA(1, 1, At, B1); PG8_BAR; PG8_SCHED;
.LBB0_314:
	s_add_u32 s40, s6, 0xfff80080
	s_addc_u32 s41, s7, -1
	s_add_i32 s56, 0, 0x10000
	s_cmp_eq_u32 s55, 28
	s_cselect_b32 s43, s27, s41
	s_cselect_b32 s42, s39, s40
	s_cselect_b32 s41, s25, s54
	s_cselect_b32 s40, s52, s53
	s_add_i32 s58, 0, 0x14000
	v_add_u32_e32 v46, s56, v212
	v_add_u32_e32 v70, s58, v212
	ds_read_b128 v[34:37], v46
	ds_read_b128 v[38:41], v46 offset:1024
	ds_read_b128 v[42:45], v46 offset:2048
	ds_read_b128 v[46:49], v46 offset:3072
	ds_read_b128 v[58:61], v70
	ds_read_b128 v[62:65], v70 offset:1024
	ds_read_b128 v[66:69], v70 offset:2048
	ds_read_b128 v[70:73], v70 offset:3072
	v_lshl_add_u64 v[172:173], s[6:7], 0, v[188:189]
	s_add_i32 m0, s44, 0xc000
	ds_read_b128 v[162:165], v220
	global_load_lds_dwordx4 v[172:173], off
	v_lshl_add_u64 v[172:173], s[6:7], 0, v[186:187]
	s_add_i32 m0, s44, 0xe000
	s_nop 0
	global_load_lds_dwordx4 v[172:173], off
	ds_read_b128 v[166:169], v220 offset:1024
	ds_read_b128 v[190:193], v220 offset:2048
	ds_read_b128 v[194:197], v220 offset:3072
	ds_read_b128 v[198:201], v220 offset:4096
	ds_read_b128 v[222:225], v220 offset:5120
	ds_read_b128 v[226:229], v220 offset:6144
	ds_read_b128 v[230:233], v220 offset:7168
	s_waitcnt vmcnt(8)
	s_waitcnt lgkmcnt(0)
	s_barrier
	s_setprio 1
	s_waitcnt lgkmcnt(0)
	v_mfma_f32_16x16x32_bf16 v[158:161], v[34:37], v[162:165], v[158:161]
	v_mfma_f32_16x16x32_bf16 v[154:157], v[42:45], v[162:165], v[154:157]
	v_mfma_f32_16x16x32_bf16 v[142:145], v[34:37], v[190:193], v[142:145]
	v_mfma_f32_16x16x32_bf16 v[138:141], v[42:45], v[190:193], v[138:141]
	v_mfma_f32_16x16x32_bf16 v[126:129], v[34:37], v[198:201], v[126:129]
	v_mfma_f32_16x16x32_bf16 v[122:125], v[42:45], v[198:201], v[122:125]
	v_mfma_f32_16x16x32_bf16 v[110:113], v[34:37], v[226:229], v[110:113]
	v_mfma_f32_16x16x32_bf16 v[106:109], v[42:45], v[226:229], v[106:109]
	v_mfma_f32_16x16x32_bf16 v[158:161], v[38:41], v[166:169], v[158:161]
	v_mfma_f32_16x16x32_bf16 v[154:157], v[46:49], v[166:169], v[154:157]
	v_mfma_f32_16x16x32_bf16 v[142:145], v[38:41], v[194:197], v[142:145]
	v_mfma_f32_16x16x32_bf16 v[138:141], v[46:49], v[194:197], v[138:141]
	v_mfma_f32_16x16x32_bf16 v[126:129], v[38:41], v[222:225], v[126:129]
	v_mfma_f32_16x16x32_bf16 v[122:125], v[46:49], v[222:225], v[122:125]
	v_mfma_f32_16x16x32_bf16 v[110:113], v[38:41], v[230:233], v[110:113]
	v_mfma_f32_16x16x32_bf16 v[106:109], v[46:49], v[230:233], v[106:109]
	s_setprio 0
	s_setprio 1
	v_mfma_f32_16x16x32_bf16 v[150:153], v[58:61], v[162:165], v[150:153]
	v_mfma_f32_16x16x32_bf16 v[146:149], v[66:69], v[162:165], v[146:149]
	v_mfma_f32_16x16x32_bf16 v[134:137], v[58:61], v[190:193], v[134:137]
	v_mfma_f32_16x16x32_bf16 v[130:133], v[66:69], v[190:193], v[130:133]
	v_mfma_f32_16x16x32_bf16 v[118:121], v[58:61], v[198:201], v[118:121]
	v_mfma_f32_16x16x32_bf16 v[114:117], v[66:69], v[198:201], v[114:117]
	v_mfma_f32_16x16x32_bf16 v[102:105], v[58:61], v[226:229], v[102:105]
	v_mfma_f32_16x16x32_bf16 v[98:101], v[66:69], v[226:229], v[98:101]
	v_mfma_f32_16x16x32_bf16 v[150:153], v[62:65], v[166:169], v[150:153]
	v_mfma_f32_16x16x32_bf16 v[146:149], v[70:73], v[166:169], v[146:149]
	v_mfma_f32_16x16x32_bf16 v[134:137], v[62:65], v[194:197], v[134:137]
	v_mfma_f32_16x16x32_bf16 v[130:133], v[70:73], v[194:197], v[130:133]
	v_mfma_f32_16x16x32_bf16 v[118:121], v[62:65], v[222:225], v[118:121]
	v_mfma_f32_16x16x32_bf16 v[114:117], v[70:73], v[222:225], v[114:117]
	v_mfma_f32_16x16x32_bf16 v[102:105], v[62:65], v[230:233], v[102:105]
	v_mfma_f32_16x16x32_bf16 v[98:101], v[70:73], v[230:233], v[98:101]
	s_setprio 0
	s_barrier
	s_add_i32 s56, s56, s33
	v_lshl_add_u64 v[172:173], s[40:41], 0, v[0:1]
	s_mov_b32 m0, s56
	ds_read_b128 v[162:165], v220 offset:16384
	global_load_lds_dwordx4 v[172:173], off
	s_add_i32 m0, s56, 0x2000
	s_add_u32 s56, s40, 0x8000
	v_lshl_add_u64 v[174:175], s[40:41], 0, v[182:183]
	s_addc_u32 s57, s41, 0
	s_add_i32 s58, s58, s33
	global_load_lds_dwordx4 v[174:175], off
	v_lshl_add_u64 v[176:177], s[56:57], 0, v[0:1]
	s_mov_b32 m0, s58
	v_lshl_add_u64 v[238:239], s[42:43], 0, v[180:181]
	global_load_lds_dwordx4 v[176:177], off
	v_lshl_add_u64 v[176:177], s[56:57], 0, v[182:183]
	s_add_i32 m0, s58, 0x2000
	s_nop 0
	global_load_lds_dwordx4 v[176:177], off
	v_lshl_add_u64 v[176:177], s[42:43], 0, v[178:179]
	s_mov_b32 m0, s44
	s_nop 0
	global_load_lds_dwordx4 v[176:177], off
	s_mov_b32 m0, s45
	s_nop 0
	global_load_lds_dwordx4 v[238:239], off
	ds_read_b128 v[166:169], v220 offset:17408
	ds_read_b128 v[190:193], v220 offset:18432
	ds_read_b128 v[194:197], v220 offset:19456
	ds_read_b128 v[198:201], v220 offset:20480
	ds_read_b128 v[222:225], v220 offset:21504
	ds_read_b128 v[226:229], v220 offset:22528
	ds_read_b128 v[230:233], v220 offset:23552
	s_waitcnt vmcnt(8)
	s_waitcnt lgkmcnt(0)
	s_barrier
; #define PG8_STAGE(bufoff, gbase, voff) do { _Pragma("unroll") for (int _i = 0; _i < 2; ++_i) \
;         __builtin_amdgcn_global_load_lds((const unsigned*)((const char*)(gbase) + (voff)[_i]), (LAS unsigned*)(lds + (bufoff) + ldsw + _i * 8192), 16, 0, 0); } while (0)
; #define PG8_LDA(dst, b, h) do { _Pragma("unroll") for (int m = 0; m < 4; ++m) _Pragma("unroll") for (int k = 0; k < 2; ++k) dst[m][k] = *(const LAS bf16x8*)(lds + PG8_SA(b, h) + aoff + m * 2048 + k * 1024); } while (0)
; #define PG8_LDB(dst, b, h) do { _Pragma("unroll") for (int n = 0; n < 2; ++n) _Pragma("unroll") for (int k = 0; k < 2; ++k) dst[n][k] = *(const LAS bf16x8*)(lds + PG8_SB(b, h) + boff + n * 2048 + k * 1024); } while (0)
; #define PG8_MMA(ai, bj, At, Bt) do { __builtin_amdgcn_s_setprio(1); _Pragma("unroll") for (int m = 0; m < 4; ++m) _Pragma("unroll") for (int n = 0; n < 2; ++n) _Pragma("unroll") for (int k = 0; k < 2; ++k) \
;         acc[ai][bj][m][n] = __builtin_amdgcn_mfma_f32_16x16x32_bf16(Bt[n][k], At[m][k], acc[ai][bj][m][n], 0, 0, 0); __builtin_amdgcn_s_setprio(0); } while (0)
; #define PG8_WAIT_V(n) asm volatile("s_waitcnt vmcnt(" #n ")" ::: "memory")
; #define PG8_WAIT_L(n) asm volatile("s_waitcnt lgkmcnt(" #n ")" ::: "memory")
; #define PG8_BAR __builtin_amdgcn_s_barrier()
; #define PG8_SCHED __builtin_amdgcn_sched_barrier(0)
; template <class Epi>
; __device__ __forceinline__ void gemm_phase(LAS unsigned char* lds, const Gemm g, const StaticOrder& S, const Epi& E, const int tid) {
;     ...
;             PG8_WAIT_V(8); PG8_WAIT_L(0); PG8_BAR; PG8_MMA(1, 0, At, B0); PG8_MMA(1, 1, At, B1); PG8_BAR; PG8_SCHED;
;             PG8_LDB(B0, 1, 0); PG8_LDB(B1, 1, 1); PG8_SCHED; PG8_LDA(At, 1, 0); PG8_STAGE(PG8_SA(0, 1), a2 + hstep, voffA);
;             PG8_WAIT_V(8); PG8_WAIT_L(0); PG8_BAR; PG8_MMA(0, 0, At, B0); PG8_MMA(0, 1, At, B1); PG8_BAR; PG8_SCHED;
	s_setprio 1
	s_waitcnt lgkmcnt(0)
	v_mfma_f32_16x16x32_bf16 v[94:97], v[34:37], v[162:165], v[94:97]
	v_mfma_f32_16x16x32_bf16 v[90:93], v[42:45], v[162:165], v[90:93]
	v_mfma_f32_16x16x32_bf16 v[78:81], v[34:37], v[190:193], v[78:81]
	v_mfma_f32_16x16x32_bf16 v[74:77], v[42:45], v[190:193], v[74:77]
	v_mfma_f32_16x16x32_bf16 v[30:33], v[34:37], v[198:201], v[30:33]
	v_mfma_f32_16x16x32_bf16 v[26:29], v[42:45], v[198:201], v[26:29]
	v_mfma_f32_16x16x32_bf16 v[14:17], v[34:37], v[226:229], v[14:17]
	v_mfma_f32_16x16x32_bf16 v[10:13], v[42:45], v[226:229], v[10:13]
	v_mfma_f32_16x16x32_bf16 v[94:97], v[38:41], v[166:169], v[94:97]
	v_mfma_f32_16x16x32_bf16 v[90:93], v[46:49], v[166:169], v[90:93]
	v_mfma_f32_16x16x32_bf16 v[78:81], v[38:41], v[194:197], v[78:81]
	v_mfma_f32_16x16x32_bf16 v[74:77], v[46:49], v[194:197], v[74:77]
	v_mfma_f32_16x16x32_bf16 v[30:33], v[38:41], v[222:225], v[30:33]
	v_mfma_f32_16x16x32_bf16 v[26:29], v[46:49], v[222:225], v[26:29]
	v_mfma_f32_16x16x32_bf16 v[14:17], v[38:41], v[230:233], v[14:17]
	v_mfma_f32_16x16x32_bf16 v[10:13], v[46:49], v[230:233], v[10:13]
	s_setprio 0
	s_setprio 1
	v_mfma_f32_16x16x32_bf16 v[22:25], v[58:61], v[198:201], v[22:25]
	v_mfma_f32_16x16x32_bf16 v[18:21], v[66:69], v[198:201], v[18:21]
	v_mfma_f32_16x16x32_bf16 v[6:9], v[58:61], v[226:229], v[6:9]
	v_mfma_f32_16x16x32_bf16 v[2:5], v[66:69], v[226:229], v[2:5]
	v_mfma_f32_16x16x32_bf16 v[34:37], v[58:61], v[162:165], v[86:89]
	v_mfma_f32_16x16x32_bf16 v[38:41], v[66:69], v[162:165], v[82:85]
	v_mfma_f32_16x16x32_bf16 v[42:45], v[58:61], v[190:193], v[54:57]
	v_mfma_f32_16x16x32_bf16 v[46:49], v[66:69], v[190:193], v[50:53]
	v_mfma_f32_16x16x32_bf16 v[22:25], v[62:65], v[222:225], v[22:25]
	v_mfma_f32_16x16x32_bf16 v[18:21], v[70:73], v[222:225], v[18:21]
	v_mfma_f32_16x16x32_bf16 v[6:9], v[62:65], v[230:233], v[6:9]
	v_mfma_f32_16x16x32_bf16 v[2:5], v[70:73], v[230:233], v[2:5]
	v_mfma_f32_16x16x32_bf16 v[34:37], v[62:65], v[166:169], v[34:37]
	v_mfma_f32_16x16x32_bf16 v[38:41], v[70:73], v[166:169], v[38:41]
	v_mfma_f32_16x16x32_bf16 v[42:45], v[62:65], v[194:197], v[42:45]
	v_mfma_f32_16x16x32_bf16 v[46:49], v[70:73], v[194:197], v[46:49]
	s_setprio 0
	s_barrier
	s_add_i32 s56, 0, 0x18000
	s_add_i32 s57, 0, 0x1c000
	v_add_u32_e32 v62, s56, v212
	v_add_u32_e32 v82, s57, v212
	ds_read_b128 v[50:53], v62
	ds_read_b128 v[54:57], v62 offset:1024
	ds_read_b128 v[58:61], v62 offset:2048
	ds_read_b128 v[62:65], v62 offset:3072
	ds_read_b128 v[66:69], v82
	ds_read_b128 v[70:73], v82 offset:1024
	ds_read_b128 v[162:165], v82 offset:2048
	ds_read_b128 v[166:169], v82 offset:3072
	s_add_u32 s42, s42, 0x80000
	s_addc_u32 s43, s43, 0
	s_mov_b32 m0, s46
	v_lshl_add_u64 v[234:235], s[42:43], 0, v[178:179]
	ds_read_b128 v[82:85], v220 offset:32768
	global_load_lds_dwordx4 v[234:235], off
	v_lshl_add_u64 v[234:235], s[42:43], 0, v[180:181]
	s_mov_b32 m0, s47
	s_nop 0
	global_load_lds_dwordx4 v[234:235], off
	ds_read_b128 v[86:89], v220 offset:33792
	ds_read_b128 v[190:193], v220 offset:34816
	ds_read_b128 v[194:197], v220 offset:35840
	ds_read_b128 v[198:201], v220 offset:36864
	ds_read_b128 v[222:225], v220 offset:37888
	ds_read_b128 v[226:229], v220 offset:38912
	ds_read_b128 v[230:233], v220 offset:39936
	s_waitcnt vmcnt(8)
	s_waitcnt lgkmcnt(0)
	s_barrier
	s_setprio 1
	s_waitcnt lgkmcnt(0)
	v_mfma_f32_16x16x32_bf16 v[158:161], v[50:53], v[82:85], v[158:161]
	v_mfma_f32_16x16x32_bf16 v[154:157], v[58:61], v[82:85], v[154:157]
	v_mfma_f32_16x16x32_bf16 v[142:145], v[50:53], v[190:193], v[142:145]
	v_mfma_f32_16x16x32_bf16 v[138:141], v[58:61], v[190:193], v[138:141]
	v_mfma_f32_16x16x32_bf16 v[126:129], v[50:53], v[198:201], v[126:129]
	v_mfma_f32_16x16x32_bf16 v[122:125], v[58:61], v[198:201], v[122:125]
	v_mfma_f32_16x16x32_bf16 v[110:113], v[50:53], v[226:229], v[110:113]
	v_mfma_f32_16x16x32_bf16 v[106:109], v[58:61], v[226:229], v[106:109]
	v_mfma_f32_16x16x32_bf16 v[158:161], v[54:57], v[86:89], v[158:161]
	v_mfma_f32_16x16x32_bf16 v[154:157], v[62:65], v[86:89], v[154:157]
	v_mfma_f32_16x16x32_bf16 v[142:145], v[54:57], v[194:197], v[142:145]
	v_mfma_f32_16x16x32_bf16 v[138:141], v[62:65], v[194:197], v[138:141]
	v_mfma_f32_16x16x32_bf16 v[126:129], v[54:57], v[222:225], v[126:129]
	v_mfma_f32_16x16x32_bf16 v[122:125], v[62:65], v[222:225], v[122:125]
	v_mfma_f32_16x16x32_bf16 v[110:113], v[54:57], v[230:233], v[110:113]
	v_mfma_f32_16x16x32_bf16 v[106:109], v[62:65], v[230:233], v[106:109]
	s_setprio 0
	s_setprio 1
	v_mfma_f32_16x16x32_bf16 v[150:153], v[66:69], v[82:85], v[150:153]
	v_mfma_f32_16x16x32_bf16 v[82:85], v[162:165], v[82:85], v[146:149]
	v_mfma_f32_16x16x32_bf16 v[146:149], v[166:169], v[86:89], v[82:85]
	v_mfma_f32_16x16x32_bf16 v[82:85], v[66:69], v[190:193], v[134:137]
	v_mfma_f32_16x16x32_bf16 v[134:137], v[70:73], v[194:197], v[82:85]
	v_mfma_f32_16x16x32_bf16 v[82:85], v[162:165], v[190:193], v[130:133]
	v_mfma_f32_16x16x32_bf16 v[130:133], v[166:169], v[194:197], v[82:85]
	v_mfma_f32_16x16x32_bf16 v[82:85], v[66:69], v[198:201], v[118:121]
	v_mfma_f32_16x16x32_bf16 v[118:121], v[70:73], v[222:225], v[82:85]
	v_mfma_f32_16x16x32_bf16 v[82:85], v[162:165], v[198:201], v[114:117]
	v_mfma_f32_16x16x32_bf16 v[114:117], v[166:169], v[222:225], v[82:85]
	v_mfma_f32_16x16x32_bf16 v[82:85], v[66:69], v[226:229], v[102:105]
	v_mfma_f32_16x16x32_bf16 v[102:105], v[70:73], v[230:233], v[82:85]
	v_mfma_f32_16x16x32_bf16 v[82:85], v[162:165], v[226:229], v[98:101]
	v_mfma_f32_16x16x32_bf16 v[150:153], v[70:73], v[86:89], v[150:153]
	v_mfma_f32_16x16x32_bf16 v[98:101], v[166:169], v[230:233], v[82:85]
	s_setprio 0
	s_barrier
; #define PG8_STAGE(bufoff, gbase, voff) do { _Pragma("unroll") for (int _i = 0; _i < 2; ++_i) \
;         __builtin_amdgcn_global_load_lds((const unsigned*)((const char*)(gbase) + (voff)[_i]), (LAS unsigned*)(lds + (bufoff) + ldsw + _i * 8192), 16, 0, 0); } while (0)
; #define PG8_LDA(dst, b, h) do { _Pragma("unroll") for (int m = 0; m < 4; ++m) _Pragma("unroll") for (int k = 0; k < 2; ++k) dst[m][k] = *(const LAS bf16x8*)(lds + PG8_SA(b, h) + aoff + m * 2048 + k * 1024); } while (0)
; #define PG8_MMA(ai, bj, At, Bt) do { __builtin_amdgcn_s_setprio(1); _Pragma("unroll") for (int m = 0; m < 4; ++m) _Pragma("unroll") for (int n = 0; n < 2; ++n) _Pragma("unroll") for (int k = 0; k < 2; ++k) \
;         acc[ai][bj][m][n] = __builtin_amdgcn_mfma_f32_16x16x32_bf16(Bt[n][k], At[m][k], acc[ai][bj][m][n], 0, 0, 0); __builtin_amdgcn_s_setprio(0); } while (0)
; #define PG8_WAIT_V(n) asm volatile("s_waitcnt vmcnt(" #n ")" ::: "memory")
; #define PG8_WAIT_L(n) asm volatile("s_waitcnt lgkmcnt(" #n ")" ::: "memory")
; #define PG8_BAR __builtin_amdgcn_s_barrier()
; #define PG8_SCHED __builtin_amdgcn_sched_barrier(0)
; template <class Epi>
; __device__ __forceinline__ void gemm_phase(LAS unsigned char* lds, const Gemm g, const StaticOrder& S, const Epi& E, const int tid) {
;     ...
;             PG8_LDA(At, 1, 1); PG8_STAGE(PG8_SB(1, 0), b3, voffB); PG8_STAGE(PG8_SB(1, 1), b3 + bhs, voffB); PG8_STAGE(PG8_SA(1, 0), a3, voffA);
;             PG8_WAIT_V(8); PG8_WAIT_L(0); PG8_BAR; PG8_MMA(1, 0, At, B0); PG8_MMA(1, 1, At, B1); PG8_BAR; PG8_SCHED;
;     ...
;         if (ALIGN_EPI) { if (wr == 0) PG8_BAR; }
	s_add_i32 s42, s56, s33
	v_lshl_add_u64 v[86:87], v[172:173], 0, s[70:71]
	s_mov_b32 m0, s42
	s_nop 0
	ds_read_b128 v[82:85], v220 offset:49152
	global_load_lds_dwordx4 v[86:87], off
	s_add_i32 m0, s42, 0x2000
	s_add_u32 s40, s40, 0x8080
	v_lshl_add_u64 v[86:87], v[174:175], 0, s[70:71]
	s_addc_u32 s41, s41, 0
	s_add_i32 s42, s57, s33
	global_load_lds_dwordx4 v[86:87], off
	v_lshl_add_u64 v[86:87], s[40:41], 0, v[0:1]
	s_mov_b32 m0, s42
	s_nop 0
	global_load_lds_dwordx4 v[86:87], off
	v_lshl_add_u64 v[86:87], s[40:41], 0, v[182:183]
	s_add_i32 m0, s42, 0x2000
	s_nop 0
	global_load_lds_dwordx4 v[86:87], off
	v_lshl_add_u64 v[86:87], v[176:177], 0, s[70:71]
	s_mov_b32 m0, s48
	s_nop 0
	global_load_lds_dwordx4 v[86:87], off
	v_lshl_add_u64 v[86:87], v[238:239], 0, s[70:71]
	s_mov_b32 m0, s49
	s_nop 0
	global_load_lds_dwordx4 v[86:87], off
	ds_read_b128 v[190:193], v220 offset:50176
	ds_read_b128 v[194:197], v220 offset:51200
	ds_read_b128 v[198:201], v220 offset:52224
	ds_read_b128 v[222:225], v220 offset:53248
	ds_read_b128 v[226:229], v220 offset:54272
	ds_read_b128 v[230:233], v220 offset:55296
	ds_read_b128 v[234:237], v220 offset:56320
	s_waitcnt vmcnt(8)
	s_waitcnt lgkmcnt(0)
	s_barrier
	s_setprio 1
	s_waitcnt lgkmcnt(0)
	v_mfma_f32_16x16x32_bf16 v[86:89], v[50:53], v[82:85], v[94:97]
	v_mfma_f32_16x16x32_bf16 v[94:97], v[54:57], v[190:193], v[86:89]
	v_mfma_f32_16x16x32_bf16 v[86:89], v[58:61], v[82:85], v[90:93]
	v_mfma_f32_16x16x32_bf16 v[78:81], v[50:53], v[194:197], v[78:81]
	v_mfma_f32_16x16x32_bf16 v[74:77], v[58:61], v[194:197], v[74:77]
	v_mfma_f32_16x16x32_bf16 v[30:33], v[50:53], v[222:225], v[30:33]
	v_mfma_f32_16x16x32_bf16 v[26:29], v[58:61], v[222:225], v[26:29]
	v_mfma_f32_16x16x32_bf16 v[14:17], v[50:53], v[230:233], v[14:17]
	v_mfma_f32_16x16x32_bf16 v[10:13], v[58:61], v[230:233], v[10:13]
	v_mfma_f32_16x16x32_bf16 v[90:93], v[62:65], v[190:193], v[86:89]
	v_mfma_f32_16x16x32_bf16 v[78:81], v[54:57], v[198:201], v[78:81]
	v_mfma_f32_16x16x32_bf16 v[74:77], v[62:65], v[198:201], v[74:77]
	v_mfma_f32_16x16x32_bf16 v[30:33], v[54:57], v[226:229], v[30:33]
	v_mfma_f32_16x16x32_bf16 v[26:29], v[62:65], v[226:229], v[26:29]
	v_mfma_f32_16x16x32_bf16 v[14:17], v[54:57], v[234:237], v[14:17]
	v_mfma_f32_16x16x32_bf16 v[10:13], v[62:65], v[234:237], v[10:13]
	s_setprio 0
	s_setprio 1
	v_mfma_f32_16x16x32_bf16 v[34:37], v[66:69], v[82:85], v[34:37]
	v_mfma_f32_16x16x32_bf16 v[86:89], v[70:73], v[190:193], v[34:37]
	v_mfma_f32_16x16x32_bf16 v[34:37], v[162:165], v[82:85], v[38:41]
	v_mfma_f32_16x16x32_bf16 v[82:85], v[166:169], v[190:193], v[34:37]
	v_mfma_f32_16x16x32_bf16 v[34:37], v[66:69], v[194:197], v[42:45]
	v_mfma_f32_16x16x32_bf16 v[54:57], v[70:73], v[198:201], v[34:37]
	v_mfma_f32_16x16x32_bf16 v[34:37], v[162:165], v[194:197], v[46:49]
	v_mfma_f32_16x16x32_bf16 v[22:25], v[66:69], v[222:225], v[22:25]
	v_mfma_f32_16x16x32_bf16 v[18:21], v[162:165], v[222:225], v[18:21]
	v_mfma_f32_16x16x32_bf16 v[6:9], v[66:69], v[230:233], v[6:9]
	v_mfma_f32_16x16x32_bf16 v[2:5], v[162:165], v[230:233], v[2:5]
	v_mfma_f32_16x16x32_bf16 v[50:53], v[166:169], v[198:201], v[34:37]
	v_mfma_f32_16x16x32_bf16 v[22:25], v[70:73], v[226:229], v[22:25]
	v_mfma_f32_16x16x32_bf16 v[18:21], v[166:169], v[226:229], v[18:21]
	v_mfma_f32_16x16x32_bf16 v[6:9], v[70:73], v[234:237], v[6:9]
	v_mfma_f32_16x16x32_bf16 v[2:5], v[166:169], v[234:237], v[2:5]
	s_setprio 0
	s_barrier
	s_add_i32 s55, s55, 2
	s_add_u32 s53, s53, 0x100
	s_addc_u32 s54, s54, 0
	s_add_u32 s6, s6, 0x100
	s_addc_u32 s7, s7, 0
	s_cmp_gt_u32 s55, 29
	s_cbranch_scc0 .LBB0_314
	s_and_b64 vcc, exec, s[22:23]
	s_cbranch_vccz .LBB0_317
	s_barrier

; #define PG8_STAGE(bufoff, gbase, voff) do { _Pragma("unroll") for (int _i = 0; _i < 2; ++_i) \
;         __builtin_amdgcn_global_load_lds((const unsigned*)((const char*)(gbase) + (voff)[_i]), (LAS unsigned*)(lds + (bufoff) + ldsw + _i * 8192), 16, 0, 0); } while (0)
; #define PG8_LDA(dst, b, h) do { _Pragma("unroll") for (int m = 0; m < 4; ++m) _Pragma("unroll") for (int k = 0; k < 2; ++k) dst[m][k] = *(const LAS bf16x8*)(lds + PG8_SA(b, h) + aoff + m * 2048 + k * 1024); } while (0)
; #define PG8_LDB(dst, b, h) do { _Pragma("unroll") for (int n = 0; n < 2; ++n) _Pragma("unroll") for (int k = 0; k < 2; ++k) dst[n][k] = *(const LAS bf16x8*)(lds + PG8_SB(b, h) + boff + n * 2048 + k * 1024); } while (0)
; #define PG8_MMA(ai, bj, At, Bt) do { __builtin_amdgcn_s_setprio(1); _Pragma("unroll") for (int m = 0; m < 4; ++m) _Pragma("unroll") for (int n = 0; n < 2; ++n) _Pragma("unroll") for (int k = 0; k < 2; ++k) \
;         acc[ai][bj][m][n] = __builtin_amdgcn_mfma_f32_16x16x32_bf16(Bt[n][k], At[m][k], acc[ai][bj][m][n], 0, 0, 0); __builtin_amdgcn_s_setprio(0); } while (0)
; #define PG8_WAIT_V(n) asm volatile("s_waitcnt vmcnt(" #n ")" ::: "memory")
; #define PG8_WAIT_L(n) asm volatile("s_waitcnt lgkmcnt(" #n ")" ::: "memory")
; #define PG8_BAR __builtin_amdgcn_s_barrier()
; #define PG8_SCHED __builtin_amdgcn_sched_barrier(0)
; template <class Epi>
; __device__ __forceinline__ void gemm_phase(LAS unsigned char* lds, const Gemm g, const StaticOrder& S, const Epi& E, const int tid) {
;     ...
;             PG8_LDB(B0, 0, 0); PG8_LDB(B1, 0, 1); PG8_SCHED; PG8_LDA(At, 0, 0); PG8_STAGE(PG8_SA(1, 1), a1 + hstep, voffA);
;             PG8_WAIT_V(8); PG8_WAIT_L(0); PG8_BAR; PG8_MMA(0, 0, At, B0); PG8_MMA(0, 1, At, B1); PG8_BAR; PG8_SCHED;
;             PG8_LDA(At, 0, 1); PG8_STAGE(PG8_SB(0, 0), b2, voffB); PG8_STAGE(PG8_SB(0, 1), b2 + bhs, voffB); PG8_STAGE(PG8_SA(0, 0), a2, voffA);
;             PG8_WAIT_V(8); PG8_WAIT_L(0); PG8_BAR; PG8_MMA(1, 0, At, B0); PG8_MMA(1, 1, At, B1); PG8_BAR; PG8_SCHED;
.LBB0_454:
	s_add_i32 s13, 0, 0x10000
	v_add_u32_e32 v0, s13, v153
	s_add_i32 s36, 0, 0x14000
	ds_read_b128 v[132:135], v0
	ds_read_b128 v[136:139], v0 offset:1024
	ds_read_b128 v[156:159], v0 offset:2048
	ds_read_b128 v[160:163], v0 offset:3072
	v_add_u32_e32 v0, s36, v153
	ds_read_b128 v[164:167], v0
	ds_read_b128 v[178:181], v0 offset:1024
	ds_read_b128 v[182:185], v0 offset:2048
	ds_read_b128 v[186:189], v0 offset:3072
	s_add_u32 s34, s34, 0x40000
	s_addc_u32 s35, s35, 0
	v_lshl_add_u64 v[2:3], s[34:35], 0, v[140:141]
	s_add_i32 m0, s43, 0xc000
	ds_read_b128 v[190:193], v155
	global_load_lds_dwordx4 v[2:3], off
	v_lshl_add_u64 v[2:3], s[34:35], 0, v[144:145]
	s_add_i32 m0, s43, 0xe000
	s_nop 0
	global_load_lds_dwordx4 v[2:3], off
	ds_read_b128 v[194:197], v155 offset:1024
	ds_read_b128 v[198:201], v155 offset:2048
	ds_read_b128 v[212:215], v155 offset:3072
	ds_read_b128 v[216:219], v155 offset:4096
	ds_read_b128 v[220:223], v155 offset:5120
	ds_read_b128 v[224:227], v155 offset:6144
	ds_read_b128 v[228:231], v155 offset:7168
	s_waitcnt vmcnt(8)
	s_waitcnt lgkmcnt(0)
	s_barrier
	s_setprio 1
	s_waitcnt lgkmcnt(0)
	v_mfma_f32_16x16x32_bf16 v[128:131], v[132:135], v[190:193], v[128:131]
	v_mfma_f32_16x16x32_bf16 v[124:127], v[156:159], v[190:193], v[124:127]
	v_mfma_f32_16x16x32_bf16 v[112:115], v[132:135], v[198:201], v[112:115]
	v_mfma_f32_16x16x32_bf16 v[108:111], v[156:159], v[198:201], v[108:111]
	v_mfma_f32_16x16x32_bf16 v[96:99], v[132:135], v[216:219], v[96:99]
	v_mfma_f32_16x16x32_bf16 v[92:95], v[156:159], v[216:219], v[92:95]
	v_mfma_f32_16x16x32_bf16 v[80:83], v[132:135], v[224:227], v[80:83]
	v_mfma_f32_16x16x32_bf16 v[76:79], v[156:159], v[224:227], v[76:79]
	v_mfma_f32_16x16x32_bf16 v[128:131], v[136:139], v[194:197], v[128:131]
	v_mfma_f32_16x16x32_bf16 v[124:127], v[160:163], v[194:197], v[124:127]
	v_mfma_f32_16x16x32_bf16 v[112:115], v[136:139], v[212:215], v[112:115]
	v_mfma_f32_16x16x32_bf16 v[108:111], v[160:163], v[212:215], v[108:111]
	v_mfma_f32_16x16x32_bf16 v[96:99], v[136:139], v[220:223], v[96:99]
	v_mfma_f32_16x16x32_bf16 v[92:95], v[160:163], v[220:223], v[92:95]
	v_mfma_f32_16x16x32_bf16 v[80:83], v[136:139], v[228:231], v[80:83]
	v_mfma_f32_16x16x32_bf16 v[76:79], v[160:163], v[228:231], v[76:79]
	s_setprio 0
	s_setprio 1
	v_mfma_f32_16x16x32_bf16 v[120:123], v[164:167], v[190:193], v[120:123]
	v_mfma_f32_16x16x32_bf16 v[116:119], v[182:185], v[190:193], v[116:119]
	v_mfma_f32_16x16x32_bf16 v[104:107], v[164:167], v[198:201], v[104:107]
	v_mfma_f32_16x16x32_bf16 v[100:103], v[182:185], v[198:201], v[100:103]
	v_mfma_f32_16x16x32_bf16 v[88:91], v[164:167], v[216:219], v[88:91]
	v_mfma_f32_16x16x32_bf16 v[84:87], v[182:185], v[216:219], v[84:87]
	v_mfma_f32_16x16x32_bf16 v[72:75], v[164:167], v[224:227], v[72:75]
	v_mfma_f32_16x16x32_bf16 v[68:71], v[182:185], v[224:227], v[68:71]
	v_mfma_f32_16x16x32_bf16 v[120:123], v[178:181], v[194:197], v[120:123]
	v_mfma_f32_16x16x32_bf16 v[116:119], v[186:189], v[194:197], v[116:119]
	v_mfma_f32_16x16x32_bf16 v[104:107], v[178:181], v[212:215], v[104:107]
	v_mfma_f32_16x16x32_bf16 v[100:103], v[186:189], v[212:215], v[100:103]
	v_mfma_f32_16x16x32_bf16 v[88:91], v[178:181], v[220:223], v[88:91]
	v_mfma_f32_16x16x32_bf16 v[84:87], v[186:189], v[220:223], v[84:87]
	v_mfma_f32_16x16x32_bf16 v[72:75], v[178:181], v[228:231], v[72:75]
	v_mfma_f32_16x16x32_bf16 v[68:71], v[186:189], v[228:231], v[68:71]
	s_setprio 0
	s_barrier
	s_add_i32 s13, s13, s42
	v_lshl_add_u64 v[168:169], s[28:29], 0, v[142:143]
	s_mov_b32 m0, s13
	ds_read_b128 v[190:193], v155 offset:16384
	global_load_lds_dwordx4 v[168:169], off
	s_add_i32 m0, s13, 0x2000
	s_add_u32 s34, s28, 0x4000
	v_lshl_add_u64 v[172:173], s[28:29], 0, v[146:147]
	s_addc_u32 s35, s29, 0
	s_add_i32 s13, s36, s42
	global_load_lds_dwordx4 v[172:173], off
	v_lshl_add_u64 v[2:3], s[34:35], 0, v[142:143]
	s_mov_b32 m0, s13
	v_lshl_add_u64 v[174:175], s[30:31], 0, v[140:141]
	global_load_lds_dwordx4 v[2:3], off
	v_lshl_add_u64 v[2:3], s[34:35], 0, v[146:147]
	s_add_i32 m0, s13, 0x2000
	v_lshl_add_u64 v[176:177], s[30:31], 0, v[144:145]
	global_load_lds_dwordx4 v[2:3], off
	s_mov_b32 m0, s43
	s_nop 0
	global_load_lds_dwordx4 v[174:175], off
	s_mov_b32 m0, s44
	s_nop 0
	global_load_lds_dwordx4 v[176:177], off
	ds_read_b128 v[194:197], v155 offset:17408
	ds_read_b128 v[198:201], v155 offset:18432
	ds_read_b128 v[212:215], v155 offset:19456
	ds_read_b128 v[216:219], v155 offset:20480
	ds_read_b128 v[220:223], v155 offset:21504
	ds_read_b128 v[224:227], v155 offset:22528
	ds_read_b128 v[228:231], v155 offset:23552
	s_waitcnt vmcnt(8)
	s_waitcnt lgkmcnt(0)
	s_barrier
; #define PG8_STAGE(bufoff, gbase, voff) do { _Pragma("unroll") for (int _i = 0; _i < 2; ++_i) \
;         __builtin_amdgcn_global_load_lds((const unsigned*)((const char*)(gbase) + (voff)[_i]), (LAS unsigned*)(lds + (bufoff) + ldsw + _i * 8192), 16, 0, 0); } while (0)
; #define PG8_LDA(dst, b, h) do { _Pragma("unroll") for (int m = 0; m < 4; ++m) _Pragma("unroll") for (int k = 0; k < 2; ++k) dst[m][k] = *(const LAS bf16x8*)(lds + PG8_SA(b, h) + aoff + m * 2048 + k * 1024); } while (0)
; #define PG8_LDB(dst, b, h) do { _Pragma("unroll") for (int n = 0; n < 2; ++n) _Pragma("unroll") for (int k = 0; k < 2; ++k) dst[n][k] = *(const LAS bf16x8*)(lds + PG8_SB(b, h) + boff + n * 2048 + k * 1024); } while (0)
; #define PG8_MMA(ai, bj, At, Bt) do { __builtin_amdgcn_s_setprio(1); _Pragma("unroll") for (int m = 0; m < 4; ++m) _Pragma("unroll") for (int n = 0; n < 2; ++n) _Pragma("unroll") for (int k = 0; k < 2; ++k) \
;         acc[ai][bj][m][n] = __builtin_amdgcn_mfma_f32_16x16x32_bf16(Bt[n][k], At[m][k], acc[ai][bj][m][n], 0, 0, 0); __builtin_amdgcn_s_setprio(0); } while (0)
; #define PG8_WAIT_V(n) asm volatile("s_waitcnt vmcnt(" #n ")" ::: "memory")
; #define PG8_WAIT_L(n) asm volatile("s_waitcnt lgkmcnt(" #n ")" ::: "memory")
; #define PG8_BAR __builtin_amdgcn_s_barrier()
; #define PG8_SCHED __builtin_amdgcn_sched_barrier(0)
; template <class Epi>
; __device__ __forceinline__ void gemm_phase(LAS unsigned char* lds, const Gemm g, const StaticOrder& S, const Epi& E, const int tid) {
;     ...
;             PG8_WAIT_V(8); PG8_WAIT_L(0); PG8_BAR; PG8_MMA(1, 0, At, B0); PG8_MMA(1, 1, At, B1); PG8_BAR; PG8_SCHED;
;             PG8_LDB(B0, 1, 0); PG8_LDB(B1, 1, 1); PG8_SCHED; PG8_LDA(At, 1, 0); PG8_STAGE(PG8_SA(0, 1), a2 + hstep, voffA);
;             PG8_WAIT_V(8); PG8_WAIT_L(0); PG8_BAR; PG8_MMA(0, 0, At, B0); PG8_MMA(0, 1, At, B1); PG8_BAR; PG8_SCHED;
	s_setprio 1
	s_waitcnt lgkmcnt(0)
	v_mfma_f32_16x16x32_bf16 v[64:67], v[132:135], v[190:193], v[64:67]
	v_mfma_f32_16x16x32_bf16 v[60:63], v[156:159], v[190:193], v[60:63]
	v_mfma_f32_16x16x32_bf16 v[48:51], v[132:135], v[198:201], v[48:51]
	v_mfma_f32_16x16x32_bf16 v[44:47], v[156:159], v[198:201], v[44:47]
	v_mfma_f32_16x16x32_bf16 v[32:35], v[132:135], v[216:219], v[32:35]
	v_mfma_f32_16x16x32_bf16 v[28:31], v[156:159], v[216:219], v[28:31]
	v_mfma_f32_16x16x32_bf16 v[16:19], v[132:135], v[224:227], v[16:19]
	v_mfma_f32_16x16x32_bf16 v[12:15], v[156:159], v[224:227], v[12:15]
	v_mfma_f32_16x16x32_bf16 v[64:67], v[136:139], v[194:197], v[64:67]
	v_mfma_f32_16x16x32_bf16 v[60:63], v[160:163], v[194:197], v[60:63]
	v_mfma_f32_16x16x32_bf16 v[48:51], v[136:139], v[212:215], v[48:51]
	v_mfma_f32_16x16x32_bf16 v[44:47], v[160:163], v[212:215], v[44:47]
	v_mfma_f32_16x16x32_bf16 v[32:35], v[136:139], v[220:223], v[32:35]
	v_mfma_f32_16x16x32_bf16 v[28:31], v[160:163], v[220:223], v[28:31]
	v_mfma_f32_16x16x32_bf16 v[16:19], v[136:139], v[228:231], v[16:19]
	v_mfma_f32_16x16x32_bf16 v[12:15], v[160:163], v[228:231], v[12:15]
	s_setprio 0
	s_setprio 1
	v_mfma_f32_16x16x32_bf16 v[56:59], v[164:167], v[190:193], v[56:59]
	v_mfma_f32_16x16x32_bf16 v[52:55], v[182:185], v[190:193], v[52:55]
	v_mfma_f32_16x16x32_bf16 v[40:43], v[164:167], v[198:201], v[40:43]
	v_mfma_f32_16x16x32_bf16 v[36:39], v[182:185], v[198:201], v[36:39]
	v_mfma_f32_16x16x32_bf16 v[24:27], v[164:167], v[216:219], v[24:27]
	v_mfma_f32_16x16x32_bf16 v[20:23], v[182:185], v[216:219], v[20:23]
	v_mfma_f32_16x16x32_bf16 v[8:11], v[164:167], v[224:227], v[8:11]
	v_mfma_f32_16x16x32_bf16 v[2:5], v[182:185], v[224:227], v[4:7]
	v_mfma_f32_16x16x32_bf16 v[56:59], v[178:181], v[194:197], v[56:59]
	v_mfma_f32_16x16x32_bf16 v[52:55], v[186:189], v[194:197], v[52:55]
	v_mfma_f32_16x16x32_bf16 v[40:43], v[178:181], v[212:215], v[40:43]
	v_mfma_f32_16x16x32_bf16 v[36:39], v[186:189], v[212:215], v[36:39]
	v_mfma_f32_16x16x32_bf16 v[24:27], v[178:181], v[220:223], v[24:27]
	v_mfma_f32_16x16x32_bf16 v[20:23], v[186:189], v[220:223], v[20:23]
	v_mfma_f32_16x16x32_bf16 v[8:11], v[178:181], v[228:231], v[8:11]
	v_mfma_f32_16x16x32_bf16 v[2:5], v[186:189], v[228:231], v[2:5]
	s_setprio 0
	s_barrier
	s_add_i32 s13, 0, 0x18000
	v_add_u32_e32 v0, s13, v153
	s_add_i32 s34, 0, 0x1c000
	ds_read_b128 v[132:135], v0
	ds_read_b128 v[136:139], v0 offset:1024
	ds_read_b128 v[156:159], v0 offset:2048
	ds_read_b128 v[160:163], v0 offset:3072
	v_add_u32_e32 v0, s34, v153
	ds_read_b128 v[164:167], v0
	ds_read_b128 v[178:181], v0 offset:1024
	ds_read_b128 v[182:185], v0 offset:2048
	ds_read_b128 v[186:189], v0 offset:3072
	s_add_u32 s30, s30, 0x40000
	s_addc_u32 s31, s31, 0
	s_mov_b32 m0, s45
	v_lshl_add_u64 v[6:7], s[30:31], 0, v[140:141]
	ds_read_b128 v[190:193], v155 offset:32768
	global_load_lds_dwordx4 v[6:7], off
	v_lshl_add_u64 v[6:7], s[30:31], 0, v[144:145]
	s_mov_b32 m0, s46
	s_nop 0
	global_load_lds_dwordx4 v[6:7], off
	ds_read_b128 v[194:197], v155 offset:33792
	ds_read_b128 v[198:201], v155 offset:34816
	ds_read_b128 v[212:215], v155 offset:35840
	ds_read_b128 v[216:219], v155 offset:36864
	ds_read_b128 v[220:223], v155 offset:37888
	ds_read_b128 v[224:227], v155 offset:38912
	ds_read_b128 v[228:231], v155 offset:39936
	s_waitcnt vmcnt(8)
	s_waitcnt lgkmcnt(0)
	s_barrier
	s_setprio 1
	s_waitcnt lgkmcnt(0)
	v_mfma_f32_16x16x32_bf16 v[128:131], v[132:135], v[190:193], v[128:131]
	v_mfma_f32_16x16x32_bf16 v[124:127], v[156:159], v[190:193], v[124:127]
	v_mfma_f32_16x16x32_bf16 v[112:115], v[132:135], v[198:201], v[112:115]
	v_mfma_f32_16x16x32_bf16 v[108:111], v[156:159], v[198:201], v[108:111]
	v_mfma_f32_16x16x32_bf16 v[96:99], v[132:135], v[216:219], v[96:99]
	v_mfma_f32_16x16x32_bf16 v[92:95], v[156:159], v[216:219], v[92:95]
	v_mfma_f32_16x16x32_bf16 v[80:83], v[132:135], v[224:227], v[80:83]
	v_mfma_f32_16x16x32_bf16 v[76:79], v[156:159], v[224:227], v[76:79]
	v_mfma_f32_16x16x32_bf16 v[128:131], v[136:139], v[194:197], v[128:131]
	v_mfma_f32_16x16x32_bf16 v[124:127], v[160:163], v[194:197], v[124:127]
	v_mfma_f32_16x16x32_bf16 v[112:115], v[136:139], v[212:215], v[112:115]
	v_mfma_f32_16x16x32_bf16 v[108:111], v[160:163], v[212:215], v[108:111]
	v_mfma_f32_16x16x32_bf16 v[96:99], v[136:139], v[220:223], v[96:99]
	v_mfma_f32_16x16x32_bf16 v[92:95], v[160:163], v[220:223], v[92:95]
	v_mfma_f32_16x16x32_bf16 v[80:83], v[136:139], v[228:231], v[80:83]
	v_mfma_f32_16x16x32_bf16 v[76:79], v[160:163], v[228:231], v[76:79]
	s_setprio 0
	s_setprio 1
	v_mfma_f32_16x16x32_bf16 v[120:123], v[164:167], v[190:193], v[120:123]
	v_mfma_f32_16x16x32_bf16 v[116:119], v[182:185], v[190:193], v[116:119]
	v_mfma_f32_16x16x32_bf16 v[104:107], v[164:167], v[198:201], v[104:107]
	v_mfma_f32_16x16x32_bf16 v[100:103], v[182:185], v[198:201], v[100:103]
	v_mfma_f32_16x16x32_bf16 v[88:91], v[164:167], v[216:219], v[88:91]
	v_mfma_f32_16x16x32_bf16 v[84:87], v[182:185], v[216:219], v[84:87]
	v_mfma_f32_16x16x32_bf16 v[72:75], v[164:167], v[224:227], v[72:75]
	v_mfma_f32_16x16x32_bf16 v[68:71], v[182:185], v[224:227], v[68:71]
	v_mfma_f32_16x16x32_bf16 v[120:123], v[178:181], v[194:197], v[120:123]
	v_mfma_f32_16x16x32_bf16 v[116:119], v[186:189], v[194:197], v[116:119]
	v_mfma_f32_16x16x32_bf16 v[104:107], v[178:181], v[212:215], v[104:107]
	v_mfma_f32_16x16x32_bf16 v[100:103], v[186:189], v[212:215], v[100:103]
	v_mfma_f32_16x16x32_bf16 v[88:91], v[178:181], v[220:223], v[88:91]
	v_mfma_f32_16x16x32_bf16 v[84:87], v[186:189], v[220:223], v[84:87]
	v_mfma_f32_16x16x32_bf16 v[72:75], v[178:181], v[228:231], v[72:75]
	v_mfma_f32_16x16x32_bf16 v[68:71], v[186:189], v[228:231], v[68:71]
	s_setprio 0
	s_barrier
; #define PG8_STAGE(bufoff, gbase, voff) do { _Pragma("unroll") for (int _i = 0; _i < 2; ++_i) \
;         __builtin_amdgcn_global_load_lds((const unsigned*)((const char*)(gbase) + (voff)[_i]), (LAS unsigned*)(lds + (bufoff) + ldsw + _i * 8192), 16, 0, 0); } while (0)
; #define PG8_LDA(dst, b, h) do { _Pragma("unroll") for (int m = 0; m < 4; ++m) _Pragma("unroll") for (int k = 0; k < 2; ++k) dst[m][k] = *(const LAS bf16x8*)(lds + PG8_SA(b, h) + aoff + m * 2048 + k * 1024); } while (0)
; #define PG8_MMA(ai, bj, At, Bt) do { __builtin_amdgcn_s_setprio(1); _Pragma("unroll") for (int m = 0; m < 4; ++m) _Pragma("unroll") for (int n = 0; n < 2; ++n) _Pragma("unroll") for (int k = 0; k < 2; ++k) \
;         acc[ai][bj][m][n] = __builtin_amdgcn_mfma_f32_16x16x32_bf16(Bt[n][k], At[m][k], acc[ai][bj][m][n], 0, 0, 0); __builtin_amdgcn_s_setprio(0); } while (0)
; #define PG8_WAIT_V(n) asm volatile("s_waitcnt vmcnt(" #n ")" ::: "memory")
; #define PG8_WAIT_L(n) asm volatile("s_waitcnt lgkmcnt(" #n ")" ::: "memory")
; #define PG8_BAR __builtin_amdgcn_s_barrier()
; #define PG8_SCHED __builtin_amdgcn_sched_barrier(0)
; template <class Epi>
; __device__ __forceinline__ void gemm_phase(LAS unsigned char* lds, const Gemm g, const StaticOrder& S, const Epi& E, const int tid) {
;     ...
;         for (int t = 0; t < ntt; t += 2) {
;     ...
;             PG8_LDA(At, 1, 1); PG8_STAGE(PG8_SB(1, 0), b3, voffB); PG8_STAGE(PG8_SB(1, 1), b3 + bhs, voffB); PG8_STAGE(PG8_SA(1, 0), a3, voffA);
;             PG8_WAIT_V(8); PG8_WAIT_L(0); PG8_BAR; PG8_MMA(1, 0, At, B0); PG8_MMA(1, 1, At, B1); PG8_BAR; PG8_SCHED;
	s_add_i32 s13, s13, s42
	v_lshl_add_u64 v[6:7], v[168:169], 0, s[70:71]
	s_mov_b32 m0, s13
	ds_read_b128 v[190:193], v155 offset:49152
	global_load_lds_dwordx4 v[6:7], off
	s_add_i32 m0, s13, 0x2000
	s_add_u32 s28, s28, 0x4080
	v_lshl_add_u64 v[6:7], v[172:173], 0, s[70:71]
	s_addc_u32 s29, s29, 0
	s_add_i32 s13, s34, s42
	global_load_lds_dwordx4 v[6:7], off
	v_lshl_add_u64 v[6:7], s[28:29], 0, v[142:143]
	s_mov_b32 m0, s13
	s_nop 0
	global_load_lds_dwordx4 v[6:7], off
	v_lshl_add_u64 v[6:7], s[28:29], 0, v[146:147]
	s_add_i32 m0, s13, 0x2000
	s_nop 0
	global_load_lds_dwordx4 v[6:7], off
	v_lshl_add_u64 v[6:7], v[174:175], 0, s[70:71]
	s_mov_b32 m0, s47
	s_nop 0
	global_load_lds_dwordx4 v[6:7], off
	v_lshl_add_u64 v[6:7], v[176:177], 0, s[70:71]
	s_mov_b32 m0, s48
	s_nop 0
	global_load_lds_dwordx4 v[6:7], off
	ds_read_b128 v[194:197], v155 offset:50176
	ds_read_b128 v[198:201], v155 offset:51200
	ds_read_b128 v[212:215], v155 offset:52224
	ds_read_b128 v[216:219], v155 offset:53248
	ds_read_b128 v[220:223], v155 offset:54272
	ds_read_b128 v[224:227], v155 offset:55296
	ds_read_b128 v[228:231], v155 offset:56320
	s_waitcnt vmcnt(8)
	s_waitcnt lgkmcnt(0)
	s_barrier
	s_setprio 1
	s_waitcnt lgkmcnt(0)
	v_mfma_f32_16x16x32_bf16 v[64:67], v[132:135], v[190:193], v[64:67]
	v_mfma_f32_16x16x32_bf16 v[60:63], v[156:159], v[190:193], v[60:63]
	v_mfma_f32_16x16x32_bf16 v[48:51], v[132:135], v[198:201], v[48:51]
	v_mfma_f32_16x16x32_bf16 v[44:47], v[156:159], v[198:201], v[44:47]
	v_mfma_f32_16x16x32_bf16 v[32:35], v[132:135], v[216:219], v[32:35]
	v_mfma_f32_16x16x32_bf16 v[28:31], v[156:159], v[216:219], v[28:31]
	v_mfma_f32_16x16x32_bf16 v[16:19], v[132:135], v[224:227], v[16:19]
	v_mfma_f32_16x16x32_bf16 v[12:15], v[156:159], v[224:227], v[12:15]
	v_mfma_f32_16x16x32_bf16 v[64:67], v[136:139], v[194:197], v[64:67]
	v_mfma_f32_16x16x32_bf16 v[60:63], v[160:163], v[194:197], v[60:63]
	v_mfma_f32_16x16x32_bf16 v[48:51], v[136:139], v[212:215], v[48:51]
	v_mfma_f32_16x16x32_bf16 v[44:47], v[160:163], v[212:215], v[44:47]
	v_mfma_f32_16x16x32_bf16 v[32:35], v[136:139], v[220:223], v[32:35]
	v_mfma_f32_16x16x32_bf16 v[28:31], v[160:163], v[220:223], v[28:31]
	v_mfma_f32_16x16x32_bf16 v[16:19], v[136:139], v[228:231], v[16:19]
	v_mfma_f32_16x16x32_bf16 v[12:15], v[160:163], v[228:231], v[12:15]
	s_setprio 0
	s_setprio 1
	v_mfma_f32_16x16x32_bf16 v[56:59], v[164:167], v[190:193], v[56:59]
	v_mfma_f32_16x16x32_bf16 v[52:55], v[182:185], v[190:193], v[52:55]
	v_mfma_f32_16x16x32_bf16 v[40:43], v[164:167], v[198:201], v[40:43]
	v_mfma_f32_16x16x32_bf16 v[36:39], v[182:185], v[198:201], v[36:39]
	v_mfma_f32_16x16x32_bf16 v[24:27], v[164:167], v[216:219], v[24:27]
	v_mfma_f32_16x16x32_bf16 v[20:23], v[182:185], v[216:219], v[20:23]
	v_mfma_f32_16x16x32_bf16 v[6:9], v[164:167], v[224:227], v[8:11]
	v_mfma_f32_16x16x32_bf16 v[2:5], v[182:185], v[224:227], v[2:5]
	v_mfma_f32_16x16x32_bf16 v[56:59], v[178:181], v[194:197], v[56:59]
	v_mfma_f32_16x16x32_bf16 v[52:55], v[186:189], v[194:197], v[52:55]
	v_mfma_f32_16x16x32_bf16 v[40:43], v[178:181], v[212:215], v[40:43]
	v_mfma_f32_16x16x32_bf16 v[36:39], v[186:189], v[212:215], v[36:39]
	v_mfma_f32_16x16x32_bf16 v[24:27], v[178:181], v[220:223], v[24:27]
	v_mfma_f32_16x16x32_bf16 v[20:23], v[186:189], v[220:223], v[20:23]
	v_mfma_f32_16x16x32_bf16 v[8:11], v[178:181], v[228:231], v[6:9]
	v_mfma_f32_16x16x32_bf16 v[4:7], v[186:189], v[228:231], v[2:5]
	s_setprio 0
	s_barrier
	s_add_i32 s2, s2, 2
	s_add_u32 s24, s24, 0x100
	s_addc_u32 s25, s25, 0
	s_add_u32 s26, s26, 0x100
	s_addc_u32 s27, s27, 0
	s_cmp_gt_u32 s11, 29
	s_cbranch_scc1 .LBB0_467

; #define PG8_STAGE(bufoff, gbase, voff) do { _Pragma("unroll") for (int _i = 0; _i < 2; ++_i) \
;         __builtin_amdgcn_global_load_lds((const unsigned*)((const char*)(gbase) + (voff)[_i]), (LAS unsigned*)(lds + (bufoff) + ldsw + _i * 8192), 16, 0, 0); } while (0)
; #define PG8_LDA(dst, b, h) do { _Pragma("unroll") for (int m = 0; m < 4; ++m) _Pragma("unroll") for (int k = 0; k < 2; ++k) dst[m][k] = *(const LAS bf16x8*)(lds + PG8_SA(b, h) + aoff + m * 2048 + k * 1024); } while (0)
; #define PG8_LDB(dst, b, h) do { _Pragma("unroll") for (int n = 0; n < 2; ++n) _Pragma("unroll") for (int k = 0; k < 2; ++k) dst[n][k] = *(const LAS bf16x8*)(lds + PG8_SB(b, h) + boff + n * 2048 + k * 1024); } while (0)
; #define PG8_WAIT_V(n) asm volatile("s_waitcnt vmcnt(" #n ")" ::: "memory")
; #define PG8_WAIT_L(n) asm volatile("s_waitcnt lgkmcnt(" #n ")" ::: "memory")
; #define PG8_BAR __builtin_amdgcn_s_barrier()
; #define PG8_SCHED __builtin_amdgcn_sched_barrier(0)
; template <class Epi>
; __device__ __forceinline__ void gemm_phase(LAS unsigned char* lds, const Gemm g, const StaticOrder& S, const Epi& E, const int tid) {
;     ...
;             const bool last = (t == ntt - 2);
;             const bool s1 = Epi::TWO && (t >= nt), s2 = Epi::TWO && (t + 2 >= nt);
;             const char* a1 = (s1 ? cA2 + (size_t)(t - nt + 1) * kstep : cA + (size_t)(t + 1) * kstep);
;             const char* a2 = last ? nA : (s2 ? cA2 + (size_t)(t + 2 - nt) * kstep : cA + (size_t)(t + 2) * kstep);
;             const char* b2 = last ? nB : (s2 ? cB2 + (size_t)(t + 2 - nt) * kstep : cB + (size_t)(t + 2) * kstep);
;             const char* a3 = a2 + kstep; const char* b3 = b2 + kstep;
;             if constexpr (Epi::TWO) { if (t == nt) E.mid(acc, cur, wr, wc, fr, fq); }
;             if constexpr (SP2) {
;             PG8_LDB(B0, 0, 0); PG8_LDB(B1, 0, 1); PG8_SCHED; PG8_LDA(At, 0, 0); PG8_STAGE(PG8_SA(1, 1), a1 + hstep, voffA);
;             PG8_WAIT_V(8); PG8_WAIT_L(0); PG8_BAR; PG8_MMA(0, 0, At, B0); PG8_MMA(0, 1, At, B1); PG8_BAR; PG8_SCHED;
;             PG8_LDA(At, 0, 1); PG8_STAGE(PG8_SB(0, 0), b2, voffB); PG8_STAGE(PG8_SB(0, 1), b2 + bhs, voffB); PG8_STAGE(PG8_SA(0, 0), a2, voffA);
;             PG8_WAIT_V(8); PG8_WAIT_L(0); PG8_BAR; PG8_MMA(1, 0, At, B0); PG8_MMA(1, 1, At, B1); PG8_BAR; PG8_SCHED;
.LBB0_546:
	s_add_u32 s28, s26, 0xfff80080
	s_addc_u32 s29, s27, -1
	s_add_i32 s44, 0, 0x10000
	s_cmp_eq_u32 s39, 28
	s_cselect_b32 s35, s19, s29
	s_cselect_b32 s34, s31, s28
	v_add_u32_e32 v0, s44, v149
	s_cselect_b32 s29, s17, s38
	s_cselect_b32 s28, s33, s37
	s_add_i32 s46, 0, 0x14000
	ds_read_b128 v[150:153], v0
	ds_read_b128 v[154:157], v0 offset:1024
	ds_read_b128 v[158:161], v0 offset:2048
	ds_read_b128 v[186:189], v0 offset:3072
	v_add_u32_e32 v0, s46, v149
	ds_read_b128 v[190:193], v0
	ds_read_b128 v[194:197], v0 offset:1024
	ds_read_b128 v[198:201], v0 offset:2048
	ds_read_b128 v[212:215], v0 offset:3072
	v_lshl_add_u64 v[162:163], s[26:27], 0, v[146:147]
	s_add_i32 m0, s57, 0xc000
	ds_read_b128 v[216:219], v184
	global_load_lds_dwordx4 v[162:163], off
	v_lshl_add_u64 v[162:163], s[26:27], 0, v[144:145]
	s_add_i32 m0, s57, 0xe000
	s_nop 0
	global_load_lds_dwordx4 v[162:163], off
	ds_read_b128 v[220:223], v184 offset:1024
	ds_read_b128 v[224:227], v184 offset:2048
	ds_read_b128 v[228:231], v184 offset:3072
	ds_read_b128 v[232:235], v184 offset:4096
	ds_read_b128 v[236:239], v184 offset:5120
	ds_read_b128 v[240:243], v184 offset:6144
	ds_read_b128 v[244:247], v184 offset:7168
	s_waitcnt vmcnt(8)
	s_waitcnt lgkmcnt(0)
	s_barrier
	s_setprio 1
	s_waitcnt lgkmcnt(0)
	v_mfma_f32_16x16x32_bf16 v[126:129], v[150:153], v[216:219], v[126:129]
	v_mfma_f32_16x16x32_bf16 v[122:125], v[158:161], v[216:219], v[122:125]
	v_mfma_f32_16x16x32_bf16 v[110:113], v[150:153], v[224:227], v[110:113]
	v_mfma_f32_16x16x32_bf16 v[106:109], v[158:161], v[224:227], v[106:109]
	v_mfma_f32_16x16x32_bf16 v[94:97], v[150:153], v[232:235], v[94:97]
	v_mfma_f32_16x16x32_bf16 v[90:93], v[158:161], v[232:235], v[90:93]
	v_mfma_f32_16x16x32_bf16 v[78:81], v[150:153], v[240:243], v[78:81]
	v_mfma_f32_16x16x32_bf16 v[74:77], v[158:161], v[240:243], v[74:77]
	v_mfma_f32_16x16x32_bf16 v[126:129], v[154:157], v[220:223], v[126:129]
	v_mfma_f32_16x16x32_bf16 v[122:125], v[186:189], v[220:223], v[122:125]
	v_mfma_f32_16x16x32_bf16 v[110:113], v[154:157], v[228:231], v[110:113]
	v_mfma_f32_16x16x32_bf16 v[106:109], v[186:189], v[228:231], v[106:109]
	v_mfma_f32_16x16x32_bf16 v[94:97], v[154:157], v[236:239], v[94:97]
	v_mfma_f32_16x16x32_bf16 v[90:93], v[186:189], v[236:239], v[90:93]
	v_mfma_f32_16x16x32_bf16 v[78:81], v[154:157], v[244:247], v[78:81]
	v_mfma_f32_16x16x32_bf16 v[74:77], v[186:189], v[244:247], v[74:77]
	s_setprio 0
	s_setprio 1
	v_mfma_f32_16x16x32_bf16 v[118:121], v[190:193], v[216:219], v[118:121]
	v_mfma_f32_16x16x32_bf16 v[114:117], v[198:201], v[216:219], v[114:117]
	v_mfma_f32_16x16x32_bf16 v[102:105], v[190:193], v[224:227], v[102:105]
	v_mfma_f32_16x16x32_bf16 v[98:101], v[198:201], v[224:227], v[98:101]
	v_mfma_f32_16x16x32_bf16 v[86:89], v[190:193], v[232:235], v[86:89]
	v_mfma_f32_16x16x32_bf16 v[82:85], v[198:201], v[232:235], v[82:85]
	v_mfma_f32_16x16x32_bf16 v[70:73], v[190:193], v[240:243], v[70:73]
	v_mfma_f32_16x16x32_bf16 v[66:69], v[198:201], v[240:243], v[66:69]
	v_mfma_f32_16x16x32_bf16 v[118:121], v[194:197], v[220:223], v[118:121]
	v_mfma_f32_16x16x32_bf16 v[114:117], v[212:215], v[220:223], v[114:117]
	v_mfma_f32_16x16x32_bf16 v[102:105], v[194:197], v[228:231], v[102:105]
	v_mfma_f32_16x16x32_bf16 v[98:101], v[212:215], v[228:231], v[98:101]
	v_mfma_f32_16x16x32_bf16 v[86:89], v[194:197], v[236:239], v[86:89]
	v_mfma_f32_16x16x32_bf16 v[82:85], v[212:215], v[236:239], v[82:85]
	v_mfma_f32_16x16x32_bf16 v[70:73], v[194:197], v[244:247], v[70:73]
	v_mfma_f32_16x16x32_bf16 v[66:69], v[212:215], v[244:247], v[66:69]
	s_setprio 0
	s_barrier
	s_add_i32 s44, s44, s56
	v_lshl_add_u64 v[162:163], s[28:29], 0, v[132:133]
	s_mov_b32 m0, s44
	ds_read_b128 v[216:219], v184 offset:16384
	global_load_lds_dwordx4 v[162:163], off
	s_add_i32 m0, s44, 0x2000
	s_add_u32 s44, s28, 0x8000
	v_lshl_add_u64 v[248:249], s[28:29], 0, v[136:137]
	s_addc_u32 s45, s29, 0
	s_add_i32 s46, s46, s56
	global_load_lds_dwordx4 v[248:249], off
	v_lshl_add_u64 v[172:173], s[44:45], 0, v[132:133]
	s_mov_b32 m0, s46
	v_lshl_add_u64 v[174:175], s[34:35], 0, v[134:135]
	global_load_lds_dwordx4 v[172:173], off
	v_lshl_add_u64 v[172:173], s[44:45], 0, v[136:137]
	s_add_i32 m0, s46, 0x2000
	s_nop 0
	global_load_lds_dwordx4 v[172:173], off
	v_lshl_add_u64 v[172:173], s[34:35], 0, v[130:131]
	s_mov_b32 m0, s57
	s_nop 0
	global_load_lds_dwordx4 v[172:173], off
	s_mov_b32 m0, s58
	s_nop 0
	global_load_lds_dwordx4 v[174:175], off
	ds_read_b128 v[220:223], v184 offset:17408
	ds_read_b128 v[224:227], v184 offset:18432
	ds_read_b128 v[228:231], v184 offset:19456
	ds_read_b128 v[232:235], v184 offset:20480
	ds_read_b128 v[236:239], v184 offset:21504
	ds_read_b128 v[240:243], v184 offset:22528
	ds_read_b128 v[244:247], v184 offset:23552
	s_waitcnt vmcnt(8)
	s_waitcnt lgkmcnt(0)
	s_barrier
; #define PG8_STAGE(bufoff, gbase, voff) do { _Pragma("unroll") for (int _i = 0; _i < 2; ++_i) \
;         __builtin_amdgcn_global_load_lds((const unsigned*)((const char*)(gbase) + (voff)[_i]), (LAS unsigned*)(lds + (bufoff) + ldsw + _i * 8192), 16, 0, 0); } while (0)
; #define PG8_LDA(dst, b, h) do { _Pragma("unroll") for (int m = 0; m < 4; ++m) _Pragma("unroll") for (int k = 0; k < 2; ++k) dst[m][k] = *(const LAS bf16x8*)(lds + PG8_SA(b, h) + aoff + m * 2048 + k * 1024); } while (0)
; #define PG8_LDB(dst, b, h) do { _Pragma("unroll") for (int n = 0; n < 2; ++n) _Pragma("unroll") for (int k = 0; k < 2; ++k) dst[n][k] = *(const LAS bf16x8*)(lds + PG8_SB(b, h) + boff + n * 2048 + k * 1024); } while (0)
; #define PG8_MMA(ai, bj, At, Bt) do { __builtin_amdgcn_s_setprio(1); _Pragma("unroll") for (int m = 0; m < 4; ++m) _Pragma("unroll") for (int n = 0; n < 2; ++n) _Pragma("unroll") for (int k = 0; k < 2; ++k) \
;         acc[ai][bj][m][n] = __builtin_amdgcn_mfma_f32_16x16x32_bf16(Bt[n][k], At[m][k], acc[ai][bj][m][n], 0, 0, 0); __builtin_amdgcn_s_setprio(0); } while (0)
; #define PG8_WAIT_V(n) asm volatile("s_waitcnt vmcnt(" #n ")" ::: "memory")
; #define PG8_WAIT_L(n) asm volatile("s_waitcnt lgkmcnt(" #n ")" ::: "memory")
; #define PG8_BAR __builtin_amdgcn_s_barrier()
; #define PG8_SCHED __builtin_amdgcn_sched_barrier(0)
; template <class Epi>
; __device__ __forceinline__ void gemm_phase(LAS unsigned char* lds, const Gemm g, const StaticOrder& S, const Epi& E, const int tid) {
;     ...
;             PG8_WAIT_V(8); PG8_WAIT_L(0); PG8_BAR; PG8_MMA(1, 0, At, B0); PG8_MMA(1, 1, At, B1); PG8_BAR; PG8_SCHED;
;             PG8_LDB(B0, 1, 0); PG8_LDB(B1, 1, 1); PG8_SCHED; PG8_LDA(At, 1, 0); PG8_STAGE(PG8_SA(0, 1), a2 + hstep, voffA);
;             PG8_WAIT_V(8); PG8_WAIT_L(0); PG8_BAR; PG8_MMA(0, 0, At, B0); PG8_MMA(0, 1, At, B1); PG8_BAR; PG8_SCHED;
	s_setprio 1
	s_waitcnt lgkmcnt(0)
	v_mfma_f32_16x16x32_bf16 v[62:65], v[150:153], v[216:219], v[62:65]
	v_mfma_f32_16x16x32_bf16 v[58:61], v[158:161], v[216:219], v[58:61]
	v_mfma_f32_16x16x32_bf16 v[46:49], v[150:153], v[224:227], v[46:49]
	v_mfma_f32_16x16x32_bf16 v[42:45], v[158:161], v[224:227], v[42:45]
	v_mfma_f32_16x16x32_bf16 v[30:33], v[150:153], v[232:235], v[30:33]
	v_mfma_f32_16x16x32_bf16 v[26:29], v[158:161], v[232:235], v[26:29]
	v_mfma_f32_16x16x32_bf16 v[14:17], v[150:153], v[240:243], v[14:17]
	v_mfma_f32_16x16x32_bf16 v[10:13], v[158:161], v[240:243], v[10:13]
	v_mfma_f32_16x16x32_bf16 v[62:65], v[154:157], v[220:223], v[62:65]
	v_mfma_f32_16x16x32_bf16 v[58:61], v[186:189], v[220:223], v[58:61]
	v_mfma_f32_16x16x32_bf16 v[46:49], v[154:157], v[228:231], v[46:49]
	v_mfma_f32_16x16x32_bf16 v[42:45], v[186:189], v[228:231], v[42:45]
	v_mfma_f32_16x16x32_bf16 v[30:33], v[154:157], v[236:239], v[30:33]
	v_mfma_f32_16x16x32_bf16 v[26:29], v[186:189], v[236:239], v[26:29]
	v_mfma_f32_16x16x32_bf16 v[14:17], v[154:157], v[244:247], v[14:17]
	v_mfma_f32_16x16x32_bf16 v[10:13], v[186:189], v[244:247], v[10:13]
	s_setprio 0
	s_setprio 1
	v_mfma_f32_16x16x32_bf16 v[54:57], v[190:193], v[216:219], v[54:57]
	v_mfma_f32_16x16x32_bf16 v[50:53], v[198:201], v[216:219], v[50:53]
	v_mfma_f32_16x16x32_bf16 v[38:41], v[190:193], v[224:227], v[38:41]
	v_mfma_f32_16x16x32_bf16 v[34:37], v[198:201], v[224:227], v[34:37]
	v_mfma_f32_16x16x32_bf16 v[22:25], v[190:193], v[232:235], v[22:25]
	v_mfma_f32_16x16x32_bf16 v[18:21], v[198:201], v[232:235], v[18:21]
	v_mfma_f32_16x16x32_bf16 v[6:9], v[190:193], v[240:243], v[6:9]
	v_mfma_f32_16x16x32_bf16 v[2:5], v[198:201], v[240:243], v[2:5]
	v_mfma_f32_16x16x32_bf16 v[54:57], v[194:197], v[220:223], v[54:57]
	v_mfma_f32_16x16x32_bf16 v[50:53], v[212:215], v[220:223], v[50:53]
	v_mfma_f32_16x16x32_bf16 v[38:41], v[194:197], v[228:231], v[38:41]
	v_mfma_f32_16x16x32_bf16 v[34:37], v[212:215], v[228:231], v[34:37]
	v_mfma_f32_16x16x32_bf16 v[22:25], v[194:197], v[236:239], v[22:25]
	v_mfma_f32_16x16x32_bf16 v[18:21], v[212:215], v[236:239], v[18:21]
	v_mfma_f32_16x16x32_bf16 v[6:9], v[194:197], v[244:247], v[6:9]
	v_mfma_f32_16x16x32_bf16 v[2:5], v[212:215], v[244:247], v[2:5]
	s_setprio 0
	s_barrier
	s_add_i32 s44, 0, 0x18000
	v_add_u32_e32 v0, s44, v149
	s_add_i32 s45, 0, 0x1c000
	ds_read_b128 v[150:153], v0
	ds_read_b128 v[154:157], v0 offset:1024
	ds_read_b128 v[158:161], v0 offset:2048
	ds_read_b128 v[186:189], v0 offset:3072
	v_add_u32_e32 v0, s45, v149
	ds_read_b128 v[190:193], v0
	ds_read_b128 v[194:197], v0 offset:1024
	ds_read_b128 v[198:201], v0 offset:2048
	ds_read_b128 v[212:215], v0 offset:3072
	s_add_u32 s34, s34, 0x80000
	s_addc_u32 s35, s35, 0
	s_mov_b32 m0, s59
	v_lshl_add_u64 v[176:177], s[34:35], 0, v[130:131]
	ds_read_b128 v[216:219], v184 offset:32768
	global_load_lds_dwordx4 v[176:177], off
	v_lshl_add_u64 v[176:177], s[34:35], 0, v[134:135]
	s_mov_b32 m0, s60
	s_nop 0
	global_load_lds_dwordx4 v[176:177], off
	ds_read_b128 v[220:223], v184 offset:33792
	ds_read_b128 v[224:227], v184 offset:34816
	ds_read_b128 v[228:231], v184 offset:35840
	ds_read_b128 v[232:235], v184 offset:36864
	ds_read_b128 v[236:239], v184 offset:37888
	ds_read_b128 v[240:243], v184 offset:38912
	ds_read_b128 v[244:247], v184 offset:39936
	s_waitcnt vmcnt(8)
	s_waitcnt lgkmcnt(0)
	s_barrier
	s_setprio 1
	s_waitcnt lgkmcnt(0)
	v_mfma_f32_16x16x32_bf16 v[126:129], v[150:153], v[216:219], v[126:129]
	v_mfma_f32_16x16x32_bf16 v[122:125], v[158:161], v[216:219], v[122:125]
	v_mfma_f32_16x16x32_bf16 v[110:113], v[150:153], v[224:227], v[110:113]
	v_mfma_f32_16x16x32_bf16 v[106:109], v[158:161], v[224:227], v[106:109]
	v_mfma_f32_16x16x32_bf16 v[94:97], v[150:153], v[232:235], v[94:97]
	v_mfma_f32_16x16x32_bf16 v[90:93], v[158:161], v[232:235], v[90:93]
	v_mfma_f32_16x16x32_bf16 v[78:81], v[150:153], v[240:243], v[78:81]
	v_mfma_f32_16x16x32_bf16 v[74:77], v[158:161], v[240:243], v[74:77]
	v_mfma_f32_16x16x32_bf16 v[126:129], v[154:157], v[220:223], v[126:129]
	v_mfma_f32_16x16x32_bf16 v[122:125], v[186:189], v[220:223], v[122:125]
	v_mfma_f32_16x16x32_bf16 v[110:113], v[154:157], v[228:231], v[110:113]
	v_mfma_f32_16x16x32_bf16 v[106:109], v[186:189], v[228:231], v[106:109]
	v_mfma_f32_16x16x32_bf16 v[94:97], v[154:157], v[236:239], v[94:97]
	v_mfma_f32_16x16x32_bf16 v[90:93], v[186:189], v[236:239], v[90:93]
	v_mfma_f32_16x16x32_bf16 v[78:81], v[154:157], v[244:247], v[78:81]
	v_mfma_f32_16x16x32_bf16 v[74:77], v[186:189], v[244:247], v[74:77]
	s_setprio 0
	s_setprio 1
	v_mfma_f32_16x16x32_bf16 v[118:121], v[190:193], v[216:219], v[118:121]
	v_mfma_f32_16x16x32_bf16 v[114:117], v[198:201], v[216:219], v[114:117]
	v_mfma_f32_16x16x32_bf16 v[102:105], v[190:193], v[224:227], v[102:105]
	v_mfma_f32_16x16x32_bf16 v[98:101], v[198:201], v[224:227], v[98:101]
	v_mfma_f32_16x16x32_bf16 v[86:89], v[190:193], v[232:235], v[86:89]
	v_mfma_f32_16x16x32_bf16 v[82:85], v[198:201], v[232:235], v[82:85]
	v_mfma_f32_16x16x32_bf16 v[70:73], v[190:193], v[240:243], v[70:73]
	v_mfma_f32_16x16x32_bf16 v[66:69], v[198:201], v[240:243], v[66:69]
	v_mfma_f32_16x16x32_bf16 v[118:121], v[194:197], v[220:223], v[118:121]
	v_mfma_f32_16x16x32_bf16 v[114:117], v[212:215], v[220:223], v[114:117]
	v_mfma_f32_16x16x32_bf16 v[102:105], v[194:197], v[228:231], v[102:105]
	v_mfma_f32_16x16x32_bf16 v[98:101], v[212:215], v[228:231], v[98:101]
	v_mfma_f32_16x16x32_bf16 v[86:89], v[194:197], v[236:239], v[86:89]
	v_mfma_f32_16x16x32_bf16 v[82:85], v[212:215], v[236:239], v[82:85]
	v_mfma_f32_16x16x32_bf16 v[70:73], v[194:197], v[244:247], v[70:73]
	v_mfma_f32_16x16x32_bf16 v[66:69], v[212:215], v[244:247], v[66:69]
	s_setprio 0
	s_barrier
; #define PG8_STAGE(bufoff, gbase, voff) do { _Pragma("unroll") for (int _i = 0; _i < 2; ++_i) \
;         __builtin_amdgcn_global_load_lds((const unsigned*)((const char*)(gbase) + (voff)[_i]), (LAS unsigned*)(lds + (bufoff) + ldsw + _i * 8192), 16, 0, 0); } while (0)
; #define PG8_LDA(dst, b, h) do { _Pragma("unroll") for (int m = 0; m < 4; ++m) _Pragma("unroll") for (int k = 0; k < 2; ++k) dst[m][k] = *(const LAS bf16x8*)(lds + PG8_SA(b, h) + aoff + m * 2048 + k * 1024); } while (0)
; #define PG8_MMA(ai, bj, At, Bt) do { __builtin_amdgcn_s_setprio(1); _Pragma("unroll") for (int m = 0; m < 4; ++m) _Pragma("unroll") for (int n = 0; n < 2; ++n) _Pragma("unroll") for (int k = 0; k < 2; ++k) \
;         acc[ai][bj][m][n] = __builtin_amdgcn_mfma_f32_16x16x32_bf16(Bt[n][k], At[m][k], acc[ai][bj][m][n], 0, 0, 0); __builtin_amdgcn_s_setprio(0); } while (0)
; #define PG8_WAIT_V(n) asm volatile("s_waitcnt vmcnt(" #n ")" ::: "memory")
; #define PG8_WAIT_L(n) asm volatile("s_waitcnt lgkmcnt(" #n ")" ::: "memory")
; #define PG8_BAR __builtin_amdgcn_s_barrier()
; #define PG8_SCHED __builtin_amdgcn_sched_barrier(0)
; template <class Epi>
; __device__ __forceinline__ void gemm_phase(LAS unsigned char* lds, const Gemm g, const StaticOrder& S, const Epi& E, const int tid) {
;     ...
;             PG8_LDA(At, 1, 1); PG8_STAGE(PG8_SB(1, 0), b3, voffB); PG8_STAGE(PG8_SB(1, 1), b3 + bhs, voffB); PG8_STAGE(PG8_SA(1, 0), a3, voffA);
;             PG8_WAIT_V(8); PG8_WAIT_L(0); PG8_BAR; PG8_MMA(1, 0, At, B0); PG8_MMA(1, 1, At, B1); PG8_BAR; PG8_SCHED;
;     ...
;         if (ALIGN_EPI) { if (wr == 0) PG8_BAR; }
	s_add_i32 s34, s44, s56
	v_lshl_add_u64 v[162:163], v[162:163], 0, s[70:71]
	s_mov_b32 m0, s34
	ds_read_b128 v[216:219], v184 offset:49152
	global_load_lds_dwordx4 v[162:163], off
	s_add_i32 m0, s34, 0x2000
	s_add_u32 s28, s28, 0x8080
	v_lshl_add_u64 v[162:163], v[248:249], 0, s[70:71]
	s_addc_u32 s29, s29, 0
	s_add_i32 s34, s45, s56
	global_load_lds_dwordx4 v[162:163], off
	v_lshl_add_u64 v[162:163], s[28:29], 0, v[132:133]
	s_mov_b32 m0, s34
	s_nop 0
	global_load_lds_dwordx4 v[162:163], off
	v_lshl_add_u64 v[162:163], s[28:29], 0, v[136:137]
	s_add_i32 m0, s34, 0x2000
	s_nop 0
	global_load_lds_dwordx4 v[162:163], off
	v_lshl_add_u64 v[162:163], v[172:173], 0, s[70:71]
	s_mov_b32 m0, s61
	s_nop 0
	global_load_lds_dwordx4 v[162:163], off
	v_lshl_add_u64 v[162:163], v[174:175], 0, s[70:71]
	s_mov_b32 m0, s62
	s_nop 0
	global_load_lds_dwordx4 v[162:163], off
	ds_read_b128 v[220:223], v184 offset:50176
	ds_read_b128 v[224:227], v184 offset:51200
	ds_read_b128 v[228:231], v184 offset:52224
	ds_read_b128 v[232:235], v184 offset:53248
	ds_read_b128 v[236:239], v184 offset:54272
	ds_read_b128 v[240:243], v184 offset:55296
	ds_read_b128 v[244:247], v184 offset:56320
	s_waitcnt vmcnt(8)
	s_waitcnt lgkmcnt(0)
	s_barrier
	s_setprio 1
	s_waitcnt lgkmcnt(0)
	v_mfma_f32_16x16x32_bf16 v[62:65], v[150:153], v[216:219], v[62:65]
	v_mfma_f32_16x16x32_bf16 v[58:61], v[158:161], v[216:219], v[58:61]
	v_mfma_f32_16x16x32_bf16 v[46:49], v[150:153], v[224:227], v[46:49]
	v_mfma_f32_16x16x32_bf16 v[42:45], v[158:161], v[224:227], v[42:45]
	v_mfma_f32_16x16x32_bf16 v[30:33], v[150:153], v[232:235], v[30:33]
	v_mfma_f32_16x16x32_bf16 v[26:29], v[158:161], v[232:235], v[26:29]
	v_mfma_f32_16x16x32_bf16 v[14:17], v[150:153], v[240:243], v[14:17]
	v_mfma_f32_16x16x32_bf16 v[10:13], v[158:161], v[240:243], v[10:13]
	v_mfma_f32_16x16x32_bf16 v[62:65], v[154:157], v[220:223], v[62:65]
	v_mfma_f32_16x16x32_bf16 v[58:61], v[186:189], v[220:223], v[58:61]
	v_mfma_f32_16x16x32_bf16 v[46:49], v[154:157], v[228:231], v[46:49]
	v_mfma_f32_16x16x32_bf16 v[42:45], v[186:189], v[228:231], v[42:45]
	v_mfma_f32_16x16x32_bf16 v[30:33], v[154:157], v[236:239], v[30:33]
	v_mfma_f32_16x16x32_bf16 v[26:29], v[186:189], v[236:239], v[26:29]
	v_mfma_f32_16x16x32_bf16 v[14:17], v[154:157], v[244:247], v[14:17]
	v_mfma_f32_16x16x32_bf16 v[10:13], v[186:189], v[244:247], v[10:13]
	s_setprio 0
	s_setprio 1
	v_mfma_f32_16x16x32_bf16 v[54:57], v[190:193], v[216:219], v[54:57]
	v_mfma_f32_16x16x32_bf16 v[50:53], v[198:201], v[216:219], v[50:53]
	v_mfma_f32_16x16x32_bf16 v[38:41], v[190:193], v[224:227], v[38:41]
	v_mfma_f32_16x16x32_bf16 v[34:37], v[198:201], v[224:227], v[34:37]
	v_mfma_f32_16x16x32_bf16 v[22:25], v[190:193], v[232:235], v[22:25]
	v_mfma_f32_16x16x32_bf16 v[18:21], v[198:201], v[232:235], v[18:21]
	v_mfma_f32_16x16x32_bf16 v[6:9], v[190:193], v[240:243], v[6:9]
	v_mfma_f32_16x16x32_bf16 v[2:5], v[198:201], v[240:243], v[2:5]
	v_mfma_f32_16x16x32_bf16 v[54:57], v[194:197], v[220:223], v[54:57]
	v_mfma_f32_16x16x32_bf16 v[50:53], v[212:215], v[220:223], v[50:53]
	v_mfma_f32_16x16x32_bf16 v[38:41], v[194:197], v[228:231], v[38:41]
	v_mfma_f32_16x16x32_bf16 v[34:37], v[212:215], v[228:231], v[34:37]
	v_mfma_f32_16x16x32_bf16 v[22:25], v[194:197], v[236:239], v[22:25]
	v_mfma_f32_16x16x32_bf16 v[18:21], v[212:215], v[236:239], v[18:21]
	v_mfma_f32_16x16x32_bf16 v[6:9], v[194:197], v[244:247], v[6:9]
	v_mfma_f32_16x16x32_bf16 v[2:5], v[212:215], v[244:247], v[2:5]
	s_setprio 0
	s_barrier
	s_add_i32 s39, s39, 2
	s_add_u32 s37, s37, 0x100
	s_addc_u32 s38, s38, 0
	s_add_u32 s26, s26, 0x100
	s_addc_u32 s27, s27, 0
	s_cmp_gt_u32 s39, 29
	s_cbranch_scc0 .LBB0_546
	s_and_b64 vcc, exec, s[14:15]
	s_cbranch_vccz .LBB0_549
	s_barrier

; #define PG8_STAGE(bufoff, gbase, voff) do { _Pragma("unroll") for (int _i = 0; _i < 2; ++_i) \
;         __builtin_amdgcn_global_load_lds((const unsigned*)((const char*)(gbase) + (voff)[_i]), (LAS unsigned*)(lds + (bufoff) + ldsw + _i * 8192), 16, 0, 0); } while (0)
; #define PG8_LDA(dst, b, h) do { _Pragma("unroll") for (int m = 0; m < 4; ++m) _Pragma("unroll") for (int k = 0; k < 2; ++k) dst[m][k] = *(const LAS bf16x8*)(lds + PG8_SA(b, h) + aoff + m * 2048 + k * 1024); } while (0)
; #define PG8_LDB(dst, b, h) do { _Pragma("unroll") for (int n = 0; n < 2; ++n) _Pragma("unroll") for (int k = 0; k < 2; ++k) dst[n][k] = *(const LAS bf16x8*)(lds + PG8_SB(b, h) + boff + n * 2048 + k * 1024); } while (0)
; #define PG8_WAIT_V(n) asm volatile("s_waitcnt vmcnt(" #n ")" ::: "memory")
; #define PG8_WAIT_L(n) asm volatile("s_waitcnt lgkmcnt(" #n ")" ::: "memory")
; #define PG8_BAR __builtin_amdgcn_s_barrier()
; #define PG8_SCHED __builtin_amdgcn_sched_barrier(0)
; template <class Epi>
; __device__ __forceinline__ void gemm_phase(LAS unsigned char* lds, const Gemm g, const StaticOrder& S, const Epi& E, const int tid) {
;     ...
;             const bool last = (t == ntt - 2);
;             const bool s1 = Epi::TWO && (t >= nt), s2 = Epi::TWO && (t + 2 >= nt);
;             const char* a1 = (s1 ? cA2 + (size_t)(t - nt + 1) * kstep : cA + (size_t)(t + 1) * kstep);
;             const char* a2 = last ? nA : (s2 ? cA2 + (size_t)(t + 2 - nt) * kstep : cA + (size_t)(t + 2) * kstep);
;             const char* b2 = last ? nB : (s2 ? cB2 + (size_t)(t + 2 - nt) * kstep : cB + (size_t)(t + 2) * kstep);
;             const char* a3 = a2 + kstep; const char* b3 = b2 + kstep;
;             if constexpr (Epi::TWO) { if (t == nt) E.mid(acc, cur, wr, wc, fr, fq); }
;             if constexpr (SP2) {
;             PG8_LDB(B0, 0, 0); PG8_LDB(B1, 0, 1); PG8_SCHED; PG8_LDA(At, 0, 0); PG8_STAGE(PG8_SA(1, 1), a1 + hstep, voffA);
;             PG8_WAIT_V(8); PG8_WAIT_L(0); PG8_BAR; PG8_MMA(0, 0, At, B0); PG8_MMA(0, 1, At, B1); PG8_BAR; PG8_SCHED;
;             PG8_LDA(At, 0, 1); PG8_STAGE(PG8_SB(0, 0), b2, voffB); PG8_STAGE(PG8_SB(0, 1), b2 + bhs, voffB); PG8_STAGE(PG8_SA(0, 0), a2, voffA);
;             PG8_WAIT_V(8); PG8_WAIT_L(0); PG8_BAR; PG8_MMA(1, 0, At, B0); PG8_MMA(1, 1, At, B1); PG8_BAR; PG8_SCHED;
.LBB0_844:
	s_add_u32 s28, s26, 0xfff80080
	s_addc_u32 s29, s27, -1
	s_add_i32 s48, 0, 0x10000
	s_cmp_eq_u32 s47, 28
	s_cselect_b32 s31, s15, s29
	s_cselect_b32 s30, s43, s28
	v_add_u32_e32 v145, s48, v142
	s_cselect_b32 s29, s13, s46
	s_cselect_b32 s28, s44, s45
	s_add_i32 s50, 0, 0x14000
	ds_read_b128 v[146:149], v145
	ds_read_b128 v[150:153], v145 offset:1024
	ds_read_b128 v[154:157], v145 offset:2048
	ds_read_b128 v[158:161], v145 offset:3072
	v_add_u32_e32 v145, s50, v142
	ds_read_b128 v[162:165], v145
	ds_read_b128 v[166:169], v145 offset:1024
	ds_read_b128 v[178:181], v145 offset:2048
	ds_read_b128 v[182:185], v145 offset:3072
	v_lshl_add_u64 v[172:173], s[26:27], 0, v[138:139]
	s_add_i32 m0, s23, 0xc000
	ds_read_b128 v[186:189], v144
	global_load_lds_dwordx4 v[172:173], off
	v_lshl_add_u64 v[172:173], s[26:27], 0, v[136:137]
	s_add_i32 m0, s23, 0xe000
	s_nop 0
	global_load_lds_dwordx4 v[172:173], off
	ds_read_b128 v[190:193], v144 offset:1024
	ds_read_b128 v[194:197], v144 offset:2048
	ds_read_b128 v[198:201], v144 offset:3072
	ds_read_b128 v[212:215], v144 offset:4096
	ds_read_b128 v[216:219], v144 offset:5120
	ds_read_b128 v[220:223], v144 offset:6144
	ds_read_b128 v[224:227], v144 offset:7168
	s_waitcnt vmcnt(8)
	s_waitcnt lgkmcnt(0)
	s_barrier
	s_setprio 1
	s_waitcnt lgkmcnt(0)
	v_mfma_f32_16x16x32_bf16 v[126:129], v[146:149], v[186:189], v[126:129]
	v_mfma_f32_16x16x32_bf16 v[122:125], v[154:157], v[186:189], v[122:125]
	v_mfma_f32_16x16x32_bf16 v[118:121], v[146:149], v[194:197], v[118:121]
	v_mfma_f32_16x16x32_bf16 v[110:113], v[154:157], v[194:197], v[110:113]
	v_mfma_f32_16x16x32_bf16 v[102:105], v[146:149], v[212:215], v[102:105]
	v_mfma_f32_16x16x32_bf16 v[94:97], v[154:157], v[212:215], v[94:97]
	v_mfma_f32_16x16x32_bf16 v[86:89], v[146:149], v[220:223], v[86:89]
	v_mfma_f32_16x16x32_bf16 v[78:81], v[154:157], v[220:223], v[78:81]
	v_mfma_f32_16x16x32_bf16 v[126:129], v[150:153], v[190:193], v[126:129]
	v_mfma_f32_16x16x32_bf16 v[122:125], v[158:161], v[190:193], v[122:125]
	v_mfma_f32_16x16x32_bf16 v[118:121], v[150:153], v[198:201], v[118:121]
	v_mfma_f32_16x16x32_bf16 v[110:113], v[158:161], v[198:201], v[110:113]
	v_mfma_f32_16x16x32_bf16 v[102:105], v[150:153], v[216:219], v[102:105]
	v_mfma_f32_16x16x32_bf16 v[94:97], v[158:161], v[216:219], v[94:97]
	v_mfma_f32_16x16x32_bf16 v[86:89], v[150:153], v[224:227], v[86:89]
	v_mfma_f32_16x16x32_bf16 v[78:81], v[158:161], v[224:227], v[78:81]
	s_setprio 0
	s_setprio 1
	v_mfma_f32_16x16x32_bf16 v[114:117], v[162:165], v[186:189], v[114:117]
	v_mfma_f32_16x16x32_bf16 v[106:109], v[178:181], v[186:189], v[106:109]
	v_mfma_f32_16x16x32_bf16 v[98:101], v[162:165], v[194:197], v[98:101]
	v_mfma_f32_16x16x32_bf16 v[90:93], v[178:181], v[194:197], v[90:93]
	v_mfma_f32_16x16x32_bf16 v[82:85], v[162:165], v[212:215], v[82:85]
	v_mfma_f32_16x16x32_bf16 v[74:77], v[178:181], v[212:215], v[74:77]
	v_mfma_f32_16x16x32_bf16 v[70:73], v[162:165], v[220:223], v[70:73]
	v_mfma_f32_16x16x32_bf16 v[66:69], v[178:181], v[220:223], v[66:69]
	v_mfma_f32_16x16x32_bf16 v[114:117], v[166:169], v[190:193], v[114:117]
	v_mfma_f32_16x16x32_bf16 v[106:109], v[182:185], v[190:193], v[106:109]
	v_mfma_f32_16x16x32_bf16 v[98:101], v[166:169], v[198:201], v[98:101]
	v_mfma_f32_16x16x32_bf16 v[90:93], v[182:185], v[198:201], v[90:93]
	v_mfma_f32_16x16x32_bf16 v[82:85], v[166:169], v[216:219], v[82:85]
	v_mfma_f32_16x16x32_bf16 v[74:77], v[182:185], v[216:219], v[74:77]
	v_mfma_f32_16x16x32_bf16 v[70:73], v[166:169], v[224:227], v[70:73]
	v_mfma_f32_16x16x32_bf16 v[66:69], v[182:185], v[224:227], v[66:69]
	s_setprio 0
	s_barrier
	s_add_i32 s48, s48, s37
	v_lshl_add_u64 v[172:173], s[28:29], 0, v[0:1]
	s_mov_b32 m0, s48
	ds_read_b128 v[186:189], v144 offset:16384
	global_load_lds_dwordx4 v[172:173], off
	s_add_i32 m0, s48, 0x2000
	s_add_u32 s48, s28, 0x8000
	v_lshl_add_u64 v[174:175], s[28:29], 0, v[134:135]
	s_addc_u32 s49, s29, 0
	s_add_i32 s50, s50, s37
	global_load_lds_dwordx4 v[174:175], off
	v_lshl_add_u64 v[176:177], s[48:49], 0, v[0:1]
	s_mov_b32 m0, s50
	v_lshl_add_u64 v[228:229], s[30:31], 0, v[132:133]
	global_load_lds_dwordx4 v[176:177], off
	v_lshl_add_u64 v[176:177], s[48:49], 0, v[134:135]
	s_add_i32 m0, s50, 0x2000
	s_nop 0
	global_load_lds_dwordx4 v[176:177], off
	v_lshl_add_u64 v[176:177], s[30:31], 0, v[130:131]
	s_mov_b32 m0, s23
	s_nop 0
	global_load_lds_dwordx4 v[176:177], off
	s_mov_b32 m0, s25
	s_nop 0
	global_load_lds_dwordx4 v[228:229], off
	ds_read_b128 v[190:193], v144 offset:17408
	ds_read_b128 v[194:197], v144 offset:18432
	ds_read_b128 v[198:201], v144 offset:19456
	ds_read_b128 v[212:215], v144 offset:20480
	ds_read_b128 v[216:219], v144 offset:21504
	ds_read_b128 v[220:223], v144 offset:22528
	ds_read_b128 v[224:227], v144 offset:23552
	s_waitcnt vmcnt(8)
	s_waitcnt lgkmcnt(0)
	s_barrier
; #define PG8_STAGE(bufoff, gbase, voff) do { _Pragma("unroll") for (int _i = 0; _i < 2; ++_i) \
;         __builtin_amdgcn_global_load_lds((const unsigned*)((const char*)(gbase) + (voff)[_i]), (LAS unsigned*)(lds + (bufoff) + ldsw + _i * 8192), 16, 0, 0); } while (0)
; #define PG8_LDA(dst, b, h) do { _Pragma("unroll") for (int m = 0; m < 4; ++m) _Pragma("unroll") for (int k = 0; k < 2; ++k) dst[m][k] = *(const LAS bf16x8*)(lds + PG8_SA(b, h) + aoff + m * 2048 + k * 1024); } while (0)
; #define PG8_LDB(dst, b, h) do { _Pragma("unroll") for (int n = 0; n < 2; ++n) _Pragma("unroll") for (int k = 0; k < 2; ++k) dst[n][k] = *(const LAS bf16x8*)(lds + PG8_SB(b, h) + boff + n * 2048 + k * 1024); } while (0)
; #define PG8_MMA(ai, bj, At, Bt) do { __builtin_amdgcn_s_setprio(1); _Pragma("unroll") for (int m = 0; m < 4; ++m) _Pragma("unroll") for (int n = 0; n < 2; ++n) _Pragma("unroll") for (int k = 0; k < 2; ++k) \
;         acc[ai][bj][m][n] = __builtin_amdgcn_mfma_f32_16x16x32_bf16(Bt[n][k], At[m][k], acc[ai][bj][m][n], 0, 0, 0); __builtin_amdgcn_s_setprio(0); } while (0)
; #define PG8_WAIT_V(n) asm volatile("s_waitcnt vmcnt(" #n ")" ::: "memory")
; #define PG8_WAIT_L(n) asm volatile("s_waitcnt lgkmcnt(" #n ")" ::: "memory")
; #define PG8_BAR __builtin_amdgcn_s_barrier()
; #define PG8_SCHED __builtin_amdgcn_sched_barrier(0)
; template <class Epi>
; __device__ __forceinline__ void gemm_phase(LAS unsigned char* lds, const Gemm g, const StaticOrder& S, const Epi& E, const int tid) {
;     ...
;             PG8_WAIT_V(8); PG8_WAIT_L(0); PG8_BAR; PG8_MMA(1, 0, At, B0); PG8_MMA(1, 1, At, B1); PG8_BAR; PG8_SCHED;
;             PG8_LDB(B0, 1, 0); PG8_LDB(B1, 1, 1); PG8_SCHED; PG8_LDA(At, 1, 0); PG8_STAGE(PG8_SA(0, 1), a2 + hstep, voffA);
;             PG8_WAIT_V(8); PG8_WAIT_L(0); PG8_BAR; PG8_MMA(0, 0, At, B0); PG8_MMA(0, 1, At, B1); PG8_BAR; PG8_SCHED;
	s_setprio 1
	s_waitcnt lgkmcnt(0)
	v_mfma_f32_16x16x32_bf16 v[62:65], v[146:149], v[186:189], v[62:65]
	v_mfma_f32_16x16x32_bf16 v[58:61], v[154:157], v[186:189], v[58:61]
	v_mfma_f32_16x16x32_bf16 v[54:57], v[146:149], v[194:197], v[54:57]
	v_mfma_f32_16x16x32_bf16 v[46:49], v[154:157], v[194:197], v[46:49]
	v_mfma_f32_16x16x32_bf16 v[38:41], v[146:149], v[212:215], v[38:41]
	v_mfma_f32_16x16x32_bf16 v[30:33], v[154:157], v[212:215], v[30:33]
	v_mfma_f32_16x16x32_bf16 v[22:25], v[146:149], v[220:223], v[22:25]
	v_mfma_f32_16x16x32_bf16 v[14:17], v[154:157], v[220:223], v[14:17]
	v_mfma_f32_16x16x32_bf16 v[62:65], v[150:153], v[190:193], v[62:65]
	v_mfma_f32_16x16x32_bf16 v[58:61], v[158:161], v[190:193], v[58:61]
	v_mfma_f32_16x16x32_bf16 v[54:57], v[150:153], v[198:201], v[54:57]
	v_mfma_f32_16x16x32_bf16 v[46:49], v[158:161], v[198:201], v[46:49]
	v_mfma_f32_16x16x32_bf16 v[38:41], v[150:153], v[216:219], v[38:41]
	v_mfma_f32_16x16x32_bf16 v[30:33], v[158:161], v[216:219], v[30:33]
	v_mfma_f32_16x16x32_bf16 v[22:25], v[150:153], v[224:227], v[22:25]
	v_mfma_f32_16x16x32_bf16 v[14:17], v[158:161], v[224:227], v[14:17]
	s_setprio 0
	s_setprio 1
	v_mfma_f32_16x16x32_bf16 v[50:53], v[162:165], v[186:189], v[50:53]
	v_mfma_f32_16x16x32_bf16 v[42:45], v[178:181], v[186:189], v[42:45]
	v_mfma_f32_16x16x32_bf16 v[34:37], v[162:165], v[194:197], v[34:37]
	v_mfma_f32_16x16x32_bf16 v[26:29], v[178:181], v[194:197], v[26:29]
	v_mfma_f32_16x16x32_bf16 v[18:21], v[162:165], v[212:215], v[18:21]
	v_mfma_f32_16x16x32_bf16 v[10:13], v[178:181], v[212:215], v[10:13]
	v_mfma_f32_16x16x32_bf16 v[6:9], v[162:165], v[220:223], v[6:9]
	v_mfma_f32_16x16x32_bf16 v[2:5], v[178:181], v[220:223], v[2:5]
	v_mfma_f32_16x16x32_bf16 v[50:53], v[166:169], v[190:193], v[50:53]
	v_mfma_f32_16x16x32_bf16 v[42:45], v[182:185], v[190:193], v[42:45]
	v_mfma_f32_16x16x32_bf16 v[34:37], v[166:169], v[198:201], v[34:37]
	v_mfma_f32_16x16x32_bf16 v[26:29], v[182:185], v[198:201], v[26:29]
	v_mfma_f32_16x16x32_bf16 v[18:21], v[166:169], v[216:219], v[18:21]
	v_mfma_f32_16x16x32_bf16 v[10:13], v[182:185], v[216:219], v[10:13]
	v_mfma_f32_16x16x32_bf16 v[6:9], v[166:169], v[224:227], v[6:9]
	v_mfma_f32_16x16x32_bf16 v[2:5], v[182:185], v[224:227], v[2:5]
	s_setprio 0
	s_barrier
	s_add_i32 s48, 0, 0x18000
	v_add_u32_e32 v145, s48, v142
	s_add_i32 s49, 0, 0x1c000
	ds_read_b128 v[146:149], v145
	ds_read_b128 v[150:153], v145 offset:1024
	ds_read_b128 v[154:157], v145 offset:2048
	ds_read_b128 v[158:161], v145 offset:3072
	v_add_u32_e32 v145, s49, v142
	ds_read_b128 v[162:165], v145
	ds_read_b128 v[166:169], v145 offset:1024
	ds_read_b128 v[178:181], v145 offset:2048
	ds_read_b128 v[182:185], v145 offset:3072
	s_add_u32 s30, s30, 0x80000
	s_addc_u32 s31, s31, 0
	s_mov_b32 m0, s38
	v_lshl_add_u64 v[230:231], s[30:31], 0, v[130:131]
	ds_read_b128 v[186:189], v144 offset:32768
	global_load_lds_dwordx4 v[230:231], off
	v_lshl_add_u64 v[230:231], s[30:31], 0, v[132:133]
	s_mov_b32 m0, s39
	s_nop 0
	global_load_lds_dwordx4 v[230:231], off
	ds_read_b128 v[190:193], v144 offset:33792
	ds_read_b128 v[194:197], v144 offset:34816
	ds_read_b128 v[198:201], v144 offset:35840
	ds_read_b128 v[212:215], v144 offset:36864
	ds_read_b128 v[216:219], v144 offset:37888
	ds_read_b128 v[220:223], v144 offset:38912
	ds_read_b128 v[224:227], v144 offset:39936
	s_waitcnt vmcnt(8)
	s_waitcnt lgkmcnt(0)
	s_barrier
	s_setprio 1
	s_waitcnt lgkmcnt(0)
	v_mfma_f32_16x16x32_bf16 v[126:129], v[146:149], v[186:189], v[126:129]
	v_mfma_f32_16x16x32_bf16 v[122:125], v[154:157], v[186:189], v[122:125]
	v_mfma_f32_16x16x32_bf16 v[118:121], v[146:149], v[194:197], v[118:121]
	v_mfma_f32_16x16x32_bf16 v[110:113], v[154:157], v[194:197], v[110:113]
	v_mfma_f32_16x16x32_bf16 v[102:105], v[146:149], v[212:215], v[102:105]
	v_mfma_f32_16x16x32_bf16 v[94:97], v[154:157], v[212:215], v[94:97]
	v_mfma_f32_16x16x32_bf16 v[86:89], v[146:149], v[220:223], v[86:89]
	v_mfma_f32_16x16x32_bf16 v[78:81], v[154:157], v[220:223], v[78:81]
	v_mfma_f32_16x16x32_bf16 v[126:129], v[150:153], v[190:193], v[126:129]
	v_mfma_f32_16x16x32_bf16 v[122:125], v[158:161], v[190:193], v[122:125]
	v_mfma_f32_16x16x32_bf16 v[118:121], v[150:153], v[198:201], v[118:121]
	v_mfma_f32_16x16x32_bf16 v[110:113], v[158:161], v[198:201], v[110:113]
	v_mfma_f32_16x16x32_bf16 v[102:105], v[150:153], v[216:219], v[102:105]
	v_mfma_f32_16x16x32_bf16 v[94:97], v[158:161], v[216:219], v[94:97]
	v_mfma_f32_16x16x32_bf16 v[86:89], v[150:153], v[224:227], v[86:89]
	v_mfma_f32_16x16x32_bf16 v[78:81], v[158:161], v[224:227], v[78:81]
	s_setprio 0
	s_setprio 1
	v_mfma_f32_16x16x32_bf16 v[114:117], v[162:165], v[186:189], v[114:117]
	v_mfma_f32_16x16x32_bf16 v[106:109], v[178:181], v[186:189], v[106:109]
	v_mfma_f32_16x16x32_bf16 v[98:101], v[162:165], v[194:197], v[98:101]
	v_mfma_f32_16x16x32_bf16 v[90:93], v[178:181], v[194:197], v[90:93]
	v_mfma_f32_16x16x32_bf16 v[82:85], v[162:165], v[212:215], v[82:85]
	v_mfma_f32_16x16x32_bf16 v[74:77], v[178:181], v[212:215], v[74:77]
	v_mfma_f32_16x16x32_bf16 v[70:73], v[162:165], v[220:223], v[70:73]
	v_mfma_f32_16x16x32_bf16 v[66:69], v[178:181], v[220:223], v[66:69]
	v_mfma_f32_16x16x32_bf16 v[114:117], v[166:169], v[190:193], v[114:117]
	v_mfma_f32_16x16x32_bf16 v[106:109], v[182:185], v[190:193], v[106:109]
	v_mfma_f32_16x16x32_bf16 v[98:101], v[166:169], v[198:201], v[98:101]
	v_mfma_f32_16x16x32_bf16 v[90:93], v[182:185], v[198:201], v[90:93]
	v_mfma_f32_16x16x32_bf16 v[82:85], v[166:169], v[216:219], v[82:85]
	v_mfma_f32_16x16x32_bf16 v[74:77], v[182:185], v[216:219], v[74:77]
	v_mfma_f32_16x16x32_bf16 v[70:73], v[166:169], v[224:227], v[70:73]
	v_mfma_f32_16x16x32_bf16 v[66:69], v[182:185], v[224:227], v[66:69]
	s_setprio 0
	s_barrier
; #define PG8_STAGE(bufoff, gbase, voff) do { _Pragma("unroll") for (int _i = 0; _i < 2; ++_i) \
;         __builtin_amdgcn_global_load_lds((const unsigned*)((const char*)(gbase) + (voff)[_i]), (LAS unsigned*)(lds + (bufoff) + ldsw + _i * 8192), 16, 0, 0); } while (0)
; #define PG8_LDA(dst, b, h) do { _Pragma("unroll") for (int m = 0; m < 4; ++m) _Pragma("unroll") for (int k = 0; k < 2; ++k) dst[m][k] = *(const LAS bf16x8*)(lds + PG8_SA(b, h) + aoff + m * 2048 + k * 1024); } while (0)
; #define PG8_MMA(ai, bj, At, Bt) do { __builtin_amdgcn_s_setprio(1); _Pragma("unroll") for (int m = 0; m < 4; ++m) _Pragma("unroll") for (int n = 0; n < 2; ++n) _Pragma("unroll") for (int k = 0; k < 2; ++k) \
;         acc[ai][bj][m][n] = __builtin_amdgcn_mfma_f32_16x16x32_bf16(Bt[n][k], At[m][k], acc[ai][bj][m][n], 0, 0, 0); __builtin_amdgcn_s_setprio(0); } while (0)
; #define PG8_WAIT_V(n) asm volatile("s_waitcnt vmcnt(" #n ")" ::: "memory")
; #define PG8_WAIT_L(n) asm volatile("s_waitcnt lgkmcnt(" #n ")" ::: "memory")
; #define PG8_BAR __builtin_amdgcn_s_barrier()
; #define PG8_SCHED __builtin_amdgcn_sched_barrier(0)
; template <class Epi>
; __device__ __forceinline__ void gemm_phase(LAS unsigned char* lds, const Gemm g, const StaticOrder& S, const Epi& E, const int tid) {
;     ...
;             PG8_LDA(At, 1, 1); PG8_STAGE(PG8_SB(1, 0), b3, voffB); PG8_STAGE(PG8_SB(1, 1), b3 + bhs, voffB); PG8_STAGE(PG8_SA(1, 0), a3, voffA);
;             PG8_WAIT_V(8); PG8_WAIT_L(0); PG8_BAR; PG8_MMA(1, 0, At, B0); PG8_MMA(1, 1, At, B1); PG8_BAR; PG8_SCHED;
;     ...
;         if (ALIGN_EPI) { if (wr == 0) PG8_BAR; }
	s_add_i32 s30, s48, s37
	v_lshl_add_u64 v[172:173], v[172:173], 0, s[70:71]
	s_mov_b32 m0, s30
	ds_read_b128 v[186:189], v144 offset:49152
	global_load_lds_dwordx4 v[172:173], off
	s_add_i32 m0, s30, 0x2000
	s_add_u32 s28, s28, 0x8080
	v_lshl_add_u64 v[172:173], v[174:175], 0, s[70:71]
	s_addc_u32 s29, s29, 0
	s_add_i32 s30, s49, s37
	global_load_lds_dwordx4 v[172:173], off
	v_lshl_add_u64 v[172:173], s[28:29], 0, v[0:1]
	s_mov_b32 m0, s30
	s_nop 0
	global_load_lds_dwordx4 v[172:173], off
	v_lshl_add_u64 v[172:173], s[28:29], 0, v[134:135]
	s_add_i32 m0, s30, 0x2000
	s_nop 0
	global_load_lds_dwordx4 v[172:173], off
	v_lshl_add_u64 v[172:173], v[176:177], 0, s[70:71]
	s_mov_b32 m0, s40
	s_nop 0
	global_load_lds_dwordx4 v[172:173], off
	v_lshl_add_u64 v[172:173], v[228:229], 0, s[70:71]
	s_mov_b32 m0, s41
	s_nop 0
	global_load_lds_dwordx4 v[172:173], off
	ds_read_b128 v[190:193], v144 offset:50176
	ds_read_b128 v[194:197], v144 offset:51200
	ds_read_b128 v[198:201], v144 offset:52224
	ds_read_b128 v[212:215], v144 offset:53248
	ds_read_b128 v[216:219], v144 offset:54272
	ds_read_b128 v[220:223], v144 offset:55296
	ds_read_b128 v[224:227], v144 offset:56320
	s_waitcnt vmcnt(8)
	s_waitcnt lgkmcnt(0)
	s_barrier
	s_setprio 1
	s_waitcnt lgkmcnt(0)
	v_mfma_f32_16x16x32_bf16 v[62:65], v[146:149], v[186:189], v[62:65]
	v_mfma_f32_16x16x32_bf16 v[58:61], v[154:157], v[186:189], v[58:61]
	v_mfma_f32_16x16x32_bf16 v[54:57], v[146:149], v[194:197], v[54:57]
	v_mfma_f32_16x16x32_bf16 v[46:49], v[154:157], v[194:197], v[46:49]
	v_mfma_f32_16x16x32_bf16 v[38:41], v[146:149], v[212:215], v[38:41]
	v_mfma_f32_16x16x32_bf16 v[30:33], v[154:157], v[212:215], v[30:33]
	v_mfma_f32_16x16x32_bf16 v[22:25], v[146:149], v[220:223], v[22:25]
	v_mfma_f32_16x16x32_bf16 v[14:17], v[154:157], v[220:223], v[14:17]
	v_mfma_f32_16x16x32_bf16 v[62:65], v[150:153], v[190:193], v[62:65]
	v_mfma_f32_16x16x32_bf16 v[58:61], v[158:161], v[190:193], v[58:61]
	v_mfma_f32_16x16x32_bf16 v[54:57], v[150:153], v[198:201], v[54:57]
	v_mfma_f32_16x16x32_bf16 v[46:49], v[158:161], v[198:201], v[46:49]
	v_mfma_f32_16x16x32_bf16 v[38:41], v[150:153], v[216:219], v[38:41]
	v_mfma_f32_16x16x32_bf16 v[30:33], v[158:161], v[216:219], v[30:33]
	v_mfma_f32_16x16x32_bf16 v[22:25], v[150:153], v[224:227], v[22:25]
	v_mfma_f32_16x16x32_bf16 v[14:17], v[158:161], v[224:227], v[14:17]
	s_setprio 0
	s_setprio 1
	v_mfma_f32_16x16x32_bf16 v[50:53], v[162:165], v[186:189], v[50:53]
	v_mfma_f32_16x16x32_bf16 v[42:45], v[178:181], v[186:189], v[42:45]
	v_mfma_f32_16x16x32_bf16 v[34:37], v[162:165], v[194:197], v[34:37]
	v_mfma_f32_16x16x32_bf16 v[26:29], v[178:181], v[194:197], v[26:29]
	v_mfma_f32_16x16x32_bf16 v[18:21], v[162:165], v[212:215], v[18:21]
	v_mfma_f32_16x16x32_bf16 v[10:13], v[178:181], v[212:215], v[10:13]
	v_mfma_f32_16x16x32_bf16 v[6:9], v[162:165], v[220:223], v[6:9]
	v_mfma_f32_16x16x32_bf16 v[2:5], v[178:181], v[220:223], v[2:5]
	v_mfma_f32_16x16x32_bf16 v[50:53], v[166:169], v[190:193], v[50:53]
	v_mfma_f32_16x16x32_bf16 v[42:45], v[182:185], v[190:193], v[42:45]
	v_mfma_f32_16x16x32_bf16 v[34:37], v[166:169], v[198:201], v[34:37]
	v_mfma_f32_16x16x32_bf16 v[26:29], v[182:185], v[198:201], v[26:29]
	v_mfma_f32_16x16x32_bf16 v[18:21], v[166:169], v[216:219], v[18:21]
	v_mfma_f32_16x16x32_bf16 v[10:13], v[182:185], v[216:219], v[10:13]
	v_mfma_f32_16x16x32_bf16 v[6:9], v[166:169], v[224:227], v[6:9]
	v_mfma_f32_16x16x32_bf16 v[2:5], v[182:185], v[224:227], v[2:5]
	s_setprio 0
	s_barrier
	s_add_i32 s47, s47, 2
	s_add_u32 s45, s45, 0x100
	s_addc_u32 s46, s46, 0
	s_add_u32 s26, s26, 0x100
	s_addc_u32 s27, s27, 0
	s_cmp_gt_u32 s47, 29
	s_cbranch_scc0 .LBB0_844
	s_and_b64 vcc, exec, s[10:11]
	s_cbranch_vccz .LBB0_847
	s_barrier

; #define PG8_STAGE(bufoff, gbase, voff) do { _Pragma("unroll") for (int _i = 0; _i < 2; ++_i) \
;         __builtin_amdgcn_global_load_lds((const unsigned*)((const char*)(gbase) + (voff)[_i]), (LAS unsigned*)(lds + (bufoff) + ldsw + _i * 8192), 16, 0, 0); } while (0)
; #define PG8_LDA(dst, b, h) do { _Pragma("unroll") for (int m = 0; m < 4; ++m) _Pragma("unroll") for (int k = 0; k < 2; ++k) dst[m][k] = *(const LAS bf16x8*)(lds + PG8_SA(b, h) + aoff + m * 2048 + k * 1024); } while (0)
; #define PG8_LDB(dst, b, h) do { _Pragma("unroll") for (int n = 0; n < 2; ++n) _Pragma("unroll") for (int k = 0; k < 2; ++k) dst[n][k] = *(const LAS bf16x8*)(lds + PG8_SB(b, h) + boff + n * 2048 + k * 1024); } while (0)
; #define PG8_WAIT_V(n) asm volatile("s_waitcnt vmcnt(" #n ")" ::: "memory")
; #define PG8_WAIT_L(n) asm volatile("s_waitcnt lgkmcnt(" #n ")" ::: "memory")
; #define PG8_BAR __builtin_amdgcn_s_barrier()
; #define PG8_SCHED __builtin_amdgcn_sched_barrier(0)
; template <class Epi>
; __device__ __forceinline__ void gemm_phase(LAS unsigned char* lds, const Gemm g, const StaticOrder& S, const Epi& E, const int tid) {
;     ...
;             const bool last = (t == ntt - 2);
;             const bool s1 = Epi::TWO && (t >= nt), s2 = Epi::TWO && (t + 2 >= nt);
;             const char* a1 = (s1 ? cA2 + (size_t)(t - nt + 1) * kstep : cA + (size_t)(t + 1) * kstep);
;             const char* a2 = last ? nA : (s2 ? cA2 + (size_t)(t + 2 - nt) * kstep : cA + (size_t)(t + 2) * kstep);
;             const char* b2 = last ? nB : (s2 ? cB2 + (size_t)(t + 2 - nt) * kstep : cB + (size_t)(t + 2) * kstep);
;             const char* a3 = a2 + kstep; const char* b3 = b2 + kstep;
;             if constexpr (Epi::TWO) { if (t == nt) E.mid(acc, cur, wr, wc, fr, fq); }
;             if constexpr (SP2) {
;             PG8_LDB(B0, 0, 0); PG8_LDB(B1, 0, 1); PG8_SCHED; PG8_LDA(At, 0, 0); PG8_STAGE(PG8_SA(1, 1), a1 + hstep, voffA);
;             PG8_WAIT_V(8); PG8_WAIT_L(0); PG8_BAR; PG8_MMA(0, 0, At, B0); PG8_MMA(0, 1, At, B1); PG8_BAR; PG8_SCHED;
;             PG8_LDA(At, 0, 1); PG8_STAGE(PG8_SB(0, 0), b2, voffB); PG8_STAGE(PG8_SB(0, 1), b2 + bhs, voffB); PG8_STAGE(PG8_SA(0, 0), a2, voffA);
;             PG8_WAIT_V(8); PG8_WAIT_L(0); PG8_BAR; PG8_MMA(1, 0, At, B0); PG8_MMA(1, 1, At, B1); PG8_BAR; PG8_SCHED;
.LBB0_861:
	s_add_u32 s30, s28, 0xfff80080
	s_addc_u32 s31, s29, -1
	s_add_i32 s51, 0, 0x10000
	s_cmp_eq_u32 s50, 28
	s_cselect_b32 s35, s17, s31
	s_cselect_b32 s34, s46, s30
	v_add_u32_e32 v145, s51, v142
	s_cselect_b32 s31, s15, s49
	s_cselect_b32 s30, s47, s48
	s_add_i32 s54, 0, 0x14000
	ds_read_b128 v[146:149], v145
	ds_read_b128 v[150:153], v145 offset:1024
	ds_read_b128 v[154:157], v145 offset:2048
	ds_read_b128 v[158:161], v145 offset:3072
	v_add_u32_e32 v145, s54, v142
	ds_read_b128 v[162:165], v145
	ds_read_b128 v[166:169], v145 offset:1024
	ds_read_b128 v[178:181], v145 offset:2048
	ds_read_b128 v[182:185], v145 offset:3072
	v_lshl_add_u64 v[172:173], s[28:29], 0, v[138:139]
	s_add_i32 m0, s25, 0xc000
	ds_read_b128 v[186:189], v144
	global_load_lds_dwordx4 v[172:173], off
	v_lshl_add_u64 v[172:173], s[28:29], 0, v[136:137]
	s_add_i32 m0, s25, 0xe000
	s_nop 0
	global_load_lds_dwordx4 v[172:173], off
	ds_read_b128 v[190:193], v144 offset:1024
	ds_read_b128 v[194:197], v144 offset:2048
	ds_read_b128 v[198:201], v144 offset:3072
	ds_read_b128 v[212:215], v144 offset:4096
	ds_read_b128 v[216:219], v144 offset:5120
	ds_read_b128 v[220:223], v144 offset:6144
	ds_read_b128 v[224:227], v144 offset:7168
	s_waitcnt vmcnt(8)
	s_waitcnt lgkmcnt(0)
	s_barrier
	s_setprio 1
	s_waitcnt lgkmcnt(0)
	v_mfma_f32_16x16x32_bf16 v[126:129], v[146:149], v[186:189], v[126:129]
	v_mfma_f32_16x16x32_bf16 v[122:125], v[154:157], v[186:189], v[122:125]
	v_mfma_f32_16x16x32_bf16 v[118:121], v[146:149], v[194:197], v[118:121]
	v_mfma_f32_16x16x32_bf16 v[110:113], v[154:157], v[194:197], v[110:113]
	v_mfma_f32_16x16x32_bf16 v[102:105], v[146:149], v[212:215], v[102:105]
	v_mfma_f32_16x16x32_bf16 v[94:97], v[154:157], v[212:215], v[94:97]
	v_mfma_f32_16x16x32_bf16 v[86:89], v[146:149], v[220:223], v[86:89]
	v_mfma_f32_16x16x32_bf16 v[78:81], v[154:157], v[220:223], v[78:81]
	v_mfma_f32_16x16x32_bf16 v[126:129], v[150:153], v[190:193], v[126:129]
	v_mfma_f32_16x16x32_bf16 v[122:125], v[158:161], v[190:193], v[122:125]
	v_mfma_f32_16x16x32_bf16 v[118:121], v[150:153], v[198:201], v[118:121]
	v_mfma_f32_16x16x32_bf16 v[110:113], v[158:161], v[198:201], v[110:113]
	v_mfma_f32_16x16x32_bf16 v[102:105], v[150:153], v[216:219], v[102:105]
	v_mfma_f32_16x16x32_bf16 v[94:97], v[158:161], v[216:219], v[94:97]
	v_mfma_f32_16x16x32_bf16 v[86:89], v[150:153], v[224:227], v[86:89]
	v_mfma_f32_16x16x32_bf16 v[78:81], v[158:161], v[224:227], v[78:81]
	s_setprio 0
	s_setprio 1
	v_mfma_f32_16x16x32_bf16 v[114:117], v[162:165], v[186:189], v[114:117]
	v_mfma_f32_16x16x32_bf16 v[106:109], v[178:181], v[186:189], v[106:109]
	v_mfma_f32_16x16x32_bf16 v[98:101], v[162:165], v[194:197], v[98:101]
	v_mfma_f32_16x16x32_bf16 v[90:93], v[178:181], v[194:197], v[90:93]
	v_mfma_f32_16x16x32_bf16 v[82:85], v[162:165], v[212:215], v[82:85]
	v_mfma_f32_16x16x32_bf16 v[74:77], v[178:181], v[212:215], v[74:77]
	v_mfma_f32_16x16x32_bf16 v[70:73], v[162:165], v[220:223], v[70:73]
	v_mfma_f32_16x16x32_bf16 v[66:69], v[178:181], v[220:223], v[66:69]
	v_mfma_f32_16x16x32_bf16 v[114:117], v[166:169], v[190:193], v[114:117]
	v_mfma_f32_16x16x32_bf16 v[106:109], v[182:185], v[190:193], v[106:109]
	v_mfma_f32_16x16x32_bf16 v[98:101], v[166:169], v[198:201], v[98:101]
	v_mfma_f32_16x16x32_bf16 v[90:93], v[182:185], v[198:201], v[90:93]
	v_mfma_f32_16x16x32_bf16 v[82:85], v[166:169], v[216:219], v[82:85]
	v_mfma_f32_16x16x32_bf16 v[74:77], v[182:185], v[216:219], v[74:77]
	v_mfma_f32_16x16x32_bf16 v[70:73], v[166:169], v[224:227], v[70:73]
	v_mfma_f32_16x16x32_bf16 v[66:69], v[182:185], v[224:227], v[66:69]
	s_setprio 0
	s_barrier
	s_add_i32 s51, s51, s40
	v_lshl_add_u64 v[172:173], s[30:31], 0, v[0:1]
	s_mov_b32 m0, s51
	ds_read_b128 v[186:189], v144 offset:16384
	global_load_lds_dwordx4 v[172:173], off
	s_add_i32 m0, s51, 0x2000
	s_add_u32 s52, s30, 0x8000
	v_lshl_add_u64 v[174:175], s[30:31], 0, v[134:135]
	s_addc_u32 s53, s31, 0
	s_add_i32 s51, s54, s40
	global_load_lds_dwordx4 v[174:175], off
	v_lshl_add_u64 v[176:177], s[52:53], 0, v[0:1]
	s_mov_b32 m0, s51
	v_lshl_add_u64 v[228:229], s[34:35], 0, v[132:133]
	global_load_lds_dwordx4 v[176:177], off
	v_lshl_add_u64 v[176:177], s[52:53], 0, v[134:135]
	s_add_i32 m0, s51, 0x2000
	s_nop 0
	global_load_lds_dwordx4 v[176:177], off
	v_lshl_add_u64 v[176:177], s[34:35], 0, v[130:131]
	s_mov_b32 m0, s25
	s_nop 0
	global_load_lds_dwordx4 v[176:177], off
	s_mov_b32 m0, s27
	s_nop 0
	global_load_lds_dwordx4 v[228:229], off
	ds_read_b128 v[190:193], v144 offset:17408
	ds_read_b128 v[194:197], v144 offset:18432
	ds_read_b128 v[198:201], v144 offset:19456
	ds_read_b128 v[212:215], v144 offset:20480
	ds_read_b128 v[216:219], v144 offset:21504
	ds_read_b128 v[220:223], v144 offset:22528
	ds_read_b128 v[224:227], v144 offset:23552
	s_waitcnt vmcnt(8)
	s_waitcnt lgkmcnt(0)
	s_barrier
; #define PG8_STAGE(bufoff, gbase, voff) do { _Pragma("unroll") for (int _i = 0; _i < 2; ++_i) \
;         __builtin_amdgcn_global_load_lds((const unsigned*)((const char*)(gbase) + (voff)[_i]), (LAS unsigned*)(lds + (bufoff) + ldsw + _i * 8192), 16, 0, 0); } while (0)
; #define PG8_LDA(dst, b, h) do { _Pragma("unroll") for (int m = 0; m < 4; ++m) _Pragma("unroll") for (int k = 0; k < 2; ++k) dst[m][k] = *(const LAS bf16x8*)(lds + PG8_SA(b, h) + aoff + m * 2048 + k * 1024); } while (0)
; #define PG8_LDB(dst, b, h) do { _Pragma("unroll") for (int n = 0; n < 2; ++n) _Pragma("unroll") for (int k = 0; k < 2; ++k) dst[n][k] = *(const LAS bf16x8*)(lds + PG8_SB(b, h) + boff + n * 2048 + k * 1024); } while (0)
; #define PG8_MMA(ai, bj, At, Bt) do { __builtin_amdgcn_s_setprio(1); _Pragma("unroll") for (int m = 0; m < 4; ++m) _Pragma("unroll") for (int n = 0; n < 2; ++n) _Pragma("unroll") for (int k = 0; k < 2; ++k) \
;         acc[ai][bj][m][n] = __builtin_amdgcn_mfma_f32_16x16x32_bf16(Bt[n][k], At[m][k], acc[ai][bj][m][n], 0, 0, 0); __builtin_amdgcn_s_setprio(0); } while (0)
; #define PG8_WAIT_V(n) asm volatile("s_waitcnt vmcnt(" #n ")" ::: "memory")
; #define PG8_WAIT_L(n) asm volatile("s_waitcnt lgkmcnt(" #n ")" ::: "memory")
; #define PG8_BAR __builtin_amdgcn_s_barrier()
; #define PG8_SCHED __builtin_amdgcn_sched_barrier(0)
; template <class Epi>
; __device__ __forceinline__ void gemm_phase(LAS unsigned char* lds, const Gemm g, const StaticOrder& S, const Epi& E, const int tid) {
;     ...
;             PG8_WAIT_V(8); PG8_WAIT_L(0); PG8_BAR; PG8_MMA(1, 0, At, B0); PG8_MMA(1, 1, At, B1); PG8_BAR; PG8_SCHED;
;             PG8_LDB(B0, 1, 0); PG8_LDB(B1, 1, 1); PG8_SCHED; PG8_LDA(At, 1, 0); PG8_STAGE(PG8_SA(0, 1), a2 + hstep, voffA);
;             PG8_WAIT_V(8); PG8_WAIT_L(0); PG8_BAR; PG8_MMA(0, 0, At, B0); PG8_MMA(0, 1, At, B1); PG8_BAR; PG8_SCHED;
	s_setprio 1
	s_waitcnt lgkmcnt(0)
	v_mfma_f32_16x16x32_bf16 v[62:65], v[146:149], v[186:189], v[62:65]
	v_mfma_f32_16x16x32_bf16 v[58:61], v[154:157], v[186:189], v[58:61]
	v_mfma_f32_16x16x32_bf16 v[54:57], v[146:149], v[194:197], v[54:57]
	v_mfma_f32_16x16x32_bf16 v[46:49], v[154:157], v[194:197], v[46:49]
	v_mfma_f32_16x16x32_bf16 v[38:41], v[146:149], v[212:215], v[38:41]
	v_mfma_f32_16x16x32_bf16 v[30:33], v[154:157], v[212:215], v[30:33]
	v_mfma_f32_16x16x32_bf16 v[22:25], v[146:149], v[220:223], v[22:25]
	v_mfma_f32_16x16x32_bf16 v[14:17], v[154:157], v[220:223], v[14:17]
	v_mfma_f32_16x16x32_bf16 v[62:65], v[150:153], v[190:193], v[62:65]
	v_mfma_f32_16x16x32_bf16 v[58:61], v[158:161], v[190:193], v[58:61]
	v_mfma_f32_16x16x32_bf16 v[54:57], v[150:153], v[198:201], v[54:57]
	v_mfma_f32_16x16x32_bf16 v[46:49], v[158:161], v[198:201], v[46:49]
	v_mfma_f32_16x16x32_bf16 v[38:41], v[150:153], v[216:219], v[38:41]
	v_mfma_f32_16x16x32_bf16 v[30:33], v[158:161], v[216:219], v[30:33]
	v_mfma_f32_16x16x32_bf16 v[22:25], v[150:153], v[224:227], v[22:25]
	v_mfma_f32_16x16x32_bf16 v[14:17], v[158:161], v[224:227], v[14:17]
	s_setprio 0
	s_setprio 1
	v_mfma_f32_16x16x32_bf16 v[50:53], v[162:165], v[186:189], v[50:53]
	v_mfma_f32_16x16x32_bf16 v[42:45], v[178:181], v[186:189], v[42:45]
	v_mfma_f32_16x16x32_bf16 v[34:37], v[162:165], v[194:197], v[34:37]
	v_mfma_f32_16x16x32_bf16 v[26:29], v[178:181], v[194:197], v[26:29]
	v_mfma_f32_16x16x32_bf16 v[18:21], v[162:165], v[212:215], v[18:21]
	v_mfma_f32_16x16x32_bf16 v[10:13], v[178:181], v[212:215], v[10:13]
	v_mfma_f32_16x16x32_bf16 v[6:9], v[162:165], v[220:223], v[6:9]
	v_mfma_f32_16x16x32_bf16 v[2:5], v[178:181], v[220:223], v[2:5]
	v_mfma_f32_16x16x32_bf16 v[50:53], v[166:169], v[190:193], v[50:53]
	v_mfma_f32_16x16x32_bf16 v[42:45], v[182:185], v[190:193], v[42:45]
	v_mfma_f32_16x16x32_bf16 v[34:37], v[166:169], v[198:201], v[34:37]
	v_mfma_f32_16x16x32_bf16 v[26:29], v[182:185], v[198:201], v[26:29]
	v_mfma_f32_16x16x32_bf16 v[18:21], v[166:169], v[216:219], v[18:21]
	v_mfma_f32_16x16x32_bf16 v[10:13], v[182:185], v[216:219], v[10:13]
	v_mfma_f32_16x16x32_bf16 v[6:9], v[166:169], v[224:227], v[6:9]
	v_mfma_f32_16x16x32_bf16 v[2:5], v[182:185], v[224:227], v[2:5]
	s_setprio 0
	s_barrier
	s_add_i32 s51, 0, 0x18000
	v_add_u32_e32 v145, s51, v142
	s_add_i32 s52, 0, 0x1c000
	ds_read_b128 v[146:149], v145
	ds_read_b128 v[150:153], v145 offset:1024
	ds_read_b128 v[154:157], v145 offset:2048
	ds_read_b128 v[158:161], v145 offset:3072
	v_add_u32_e32 v145, s52, v142
	ds_read_b128 v[162:165], v145
	ds_read_b128 v[166:169], v145 offset:1024
	ds_read_b128 v[178:181], v145 offset:2048
	ds_read_b128 v[182:185], v145 offset:3072
	s_add_u32 s34, s34, 0x80000
	s_addc_u32 s35, s35, 0
	s_mov_b32 m0, s41
	v_lshl_add_u64 v[230:231], s[34:35], 0, v[130:131]
	ds_read_b128 v[186:189], v144 offset:32768
	global_load_lds_dwordx4 v[230:231], off
	v_lshl_add_u64 v[230:231], s[34:35], 0, v[132:133]
	s_mov_b32 m0, s42
	s_nop 0
	global_load_lds_dwordx4 v[230:231], off
	ds_read_b128 v[190:193], v144 offset:33792
	ds_read_b128 v[194:197], v144 offset:34816
	ds_read_b128 v[198:201], v144 offset:35840
	ds_read_b128 v[212:215], v144 offset:36864
	ds_read_b128 v[216:219], v144 offset:37888
	ds_read_b128 v[220:223], v144 offset:38912
	ds_read_b128 v[224:227], v144 offset:39936
	s_waitcnt vmcnt(8)
	s_waitcnt lgkmcnt(0)
	s_barrier
	s_setprio 1
	s_waitcnt lgkmcnt(0)
	v_mfma_f32_16x16x32_bf16 v[126:129], v[146:149], v[186:189], v[126:129]
	v_mfma_f32_16x16x32_bf16 v[122:125], v[154:157], v[186:189], v[122:125]
	v_mfma_f32_16x16x32_bf16 v[118:121], v[146:149], v[194:197], v[118:121]
	v_mfma_f32_16x16x32_bf16 v[110:113], v[154:157], v[194:197], v[110:113]
	v_mfma_f32_16x16x32_bf16 v[102:105], v[146:149], v[212:215], v[102:105]
	v_mfma_f32_16x16x32_bf16 v[94:97], v[154:157], v[212:215], v[94:97]
	v_mfma_f32_16x16x32_bf16 v[86:89], v[146:149], v[220:223], v[86:89]
	v_mfma_f32_16x16x32_bf16 v[78:81], v[154:157], v[220:223], v[78:81]
	v_mfma_f32_16x16x32_bf16 v[126:129], v[150:153], v[190:193], v[126:129]
	v_mfma_f32_16x16x32_bf16 v[122:125], v[158:161], v[190:193], v[122:125]
	v_mfma_f32_16x16x32_bf16 v[118:121], v[150:153], v[198:201], v[118:121]
	v_mfma_f32_16x16x32_bf16 v[110:113], v[158:161], v[198:201], v[110:113]
	v_mfma_f32_16x16x32_bf16 v[102:105], v[150:153], v[216:219], v[102:105]
	v_mfma_f32_16x16x32_bf16 v[94:97], v[158:161], v[216:219], v[94:97]
	v_mfma_f32_16x16x32_bf16 v[86:89], v[150:153], v[224:227], v[86:89]
	v_mfma_f32_16x16x32_bf16 v[78:81], v[158:161], v[224:227], v[78:81]
	s_setprio 0
	s_setprio 1
	v_mfma_f32_16x16x32_bf16 v[114:117], v[162:165], v[186:189], v[114:117]
	v_mfma_f32_16x16x32_bf16 v[106:109], v[178:181], v[186:189], v[106:109]
	v_mfma_f32_16x16x32_bf16 v[98:101], v[162:165], v[194:197], v[98:101]
	v_mfma_f32_16x16x32_bf16 v[90:93], v[178:181], v[194:197], v[90:93]
	v_mfma_f32_16x16x32_bf16 v[82:85], v[162:165], v[212:215], v[82:85]
	v_mfma_f32_16x16x32_bf16 v[74:77], v[178:181], v[212:215], v[74:77]
	v_mfma_f32_16x16x32_bf16 v[70:73], v[162:165], v[220:223], v[70:73]
	v_mfma_f32_16x16x32_bf16 v[66:69], v[178:181], v[220:223], v[66:69]
	v_mfma_f32_16x16x32_bf16 v[114:117], v[166:169], v[190:193], v[114:117]
	v_mfma_f32_16x16x32_bf16 v[106:109], v[182:185], v[190:193], v[106:109]
	v_mfma_f32_16x16x32_bf16 v[98:101], v[166:169], v[198:201], v[98:101]
	v_mfma_f32_16x16x32_bf16 v[90:93], v[182:185], v[198:201], v[90:93]
	v_mfma_f32_16x16x32_bf16 v[82:85], v[166:169], v[216:219], v[82:85]
	v_mfma_f32_16x16x32_bf16 v[74:77], v[182:185], v[216:219], v[74:77]
	v_mfma_f32_16x16x32_bf16 v[70:73], v[166:169], v[224:227], v[70:73]
	v_mfma_f32_16x16x32_bf16 v[66:69], v[182:185], v[224:227], v[66:69]
	s_setprio 0
	s_barrier
; #define PG8_STAGE(bufoff, gbase, voff) do { _Pragma("unroll") for (int _i = 0; _i < 2; ++_i) \
;         __builtin_amdgcn_global_load_lds((const unsigned*)((const char*)(gbase) + (voff)[_i]), (LAS unsigned*)(lds + (bufoff) + ldsw + _i * 8192), 16, 0, 0); } while (0)
; #define PG8_LDA(dst, b, h) do { _Pragma("unroll") for (int m = 0; m < 4; ++m) _Pragma("unroll") for (int k = 0; k < 2; ++k) dst[m][k] = *(const LAS bf16x8*)(lds + PG8_SA(b, h) + aoff + m * 2048 + k * 1024); } while (0)
; #define PG8_MMA(ai, bj, At, Bt) do { __builtin_amdgcn_s_setprio(1); _Pragma("unroll") for (int m = 0; m < 4; ++m) _Pragma("unroll") for (int n = 0; n < 2; ++n) _Pragma("unroll") for (int k = 0; k < 2; ++k) \
;         acc[ai][bj][m][n] = __builtin_amdgcn_mfma_f32_16x16x32_bf16(Bt[n][k], At[m][k], acc[ai][bj][m][n], 0, 0, 0); __builtin_amdgcn_s_setprio(0); } while (0)
; #define PG8_WAIT_V(n) asm volatile("s_waitcnt vmcnt(" #n ")" ::: "memory")
; #define PG8_WAIT_L(n) asm volatile("s_waitcnt lgkmcnt(" #n ")" ::: "memory")
; #define PG8_BAR __builtin_amdgcn_s_barrier()
; #define PG8_SCHED __builtin_amdgcn_sched_barrier(0)
; template <class Epi>
; __device__ __forceinline__ void gemm_phase(LAS unsigned char* lds, const Gemm g, const StaticOrder& S, const Epi& E, const int tid) {
;     ...
;             PG8_LDA(At, 1, 1); PG8_STAGE(PG8_SB(1, 0), b3, voffB); PG8_STAGE(PG8_SB(1, 1), b3 + bhs, voffB); PG8_STAGE(PG8_SA(1, 0), a3, voffA);
;             PG8_WAIT_V(8); PG8_WAIT_L(0); PG8_BAR; PG8_MMA(1, 0, At, B0); PG8_MMA(1, 1, At, B1); PG8_BAR; PG8_SCHED;
;     ...
;         if (ALIGN_EPI) { if (wr == 0) PG8_BAR; }
	s_add_i32 s34, s51, s40
	v_lshl_add_u64 v[172:173], v[172:173], 0, s[70:71]
	s_mov_b32 m0, s34
	ds_read_b128 v[186:189], v144 offset:49152
	global_load_lds_dwordx4 v[172:173], off
	s_add_i32 m0, s34, 0x2000
	s_add_u32 s30, s30, 0x8080
	v_lshl_add_u64 v[172:173], v[174:175], 0, s[70:71]
	s_addc_u32 s31, s31, 0
	s_add_i32 s34, s52, s40
	global_load_lds_dwordx4 v[172:173], off
	v_lshl_add_u64 v[172:173], s[30:31], 0, v[0:1]
	s_mov_b32 m0, s34
	s_nop 0
	global_load_lds_dwordx4 v[172:173], off
	v_lshl_add_u64 v[172:173], s[30:31], 0, v[134:135]
	s_add_i32 m0, s34, 0x2000
	s_nop 0
	global_load_lds_dwordx4 v[172:173], off
	v_lshl_add_u64 v[172:173], v[176:177], 0, s[70:71]
	s_mov_b32 m0, s43
	s_nop 0
	global_load_lds_dwordx4 v[172:173], off
	v_lshl_add_u64 v[172:173], v[228:229], 0, s[70:71]
	s_mov_b32 m0, s44
	s_nop 0
	global_load_lds_dwordx4 v[172:173], off
	ds_read_b128 v[190:193], v144 offset:50176
	ds_read_b128 v[194:197], v144 offset:51200
	ds_read_b128 v[198:201], v144 offset:52224
	ds_read_b128 v[212:215], v144 offset:53248
	ds_read_b128 v[216:219], v144 offset:54272
	ds_read_b128 v[220:223], v144 offset:55296
	ds_read_b128 v[224:227], v144 offset:56320
	s_waitcnt vmcnt(8)
	s_waitcnt lgkmcnt(0)
	s_barrier
	s_setprio 1
	s_waitcnt lgkmcnt(0)
	v_mfma_f32_16x16x32_bf16 v[62:65], v[146:149], v[186:189], v[62:65]
	v_mfma_f32_16x16x32_bf16 v[58:61], v[154:157], v[186:189], v[58:61]
	v_mfma_f32_16x16x32_bf16 v[54:57], v[146:149], v[194:197], v[54:57]
	v_mfma_f32_16x16x32_bf16 v[46:49], v[154:157], v[194:197], v[46:49]
	v_mfma_f32_16x16x32_bf16 v[38:41], v[146:149], v[212:215], v[38:41]
	v_mfma_f32_16x16x32_bf16 v[30:33], v[154:157], v[212:215], v[30:33]
	v_mfma_f32_16x16x32_bf16 v[22:25], v[146:149], v[220:223], v[22:25]
	v_mfma_f32_16x16x32_bf16 v[14:17], v[154:157], v[220:223], v[14:17]
	v_mfma_f32_16x16x32_bf16 v[62:65], v[150:153], v[190:193], v[62:65]
	v_mfma_f32_16x16x32_bf16 v[58:61], v[158:161], v[190:193], v[58:61]
	v_mfma_f32_16x16x32_bf16 v[54:57], v[150:153], v[198:201], v[54:57]
	v_mfma_f32_16x16x32_bf16 v[46:49], v[158:161], v[198:201], v[46:49]
	v_mfma_f32_16x16x32_bf16 v[38:41], v[150:153], v[216:219], v[38:41]
	v_mfma_f32_16x16x32_bf16 v[30:33], v[158:161], v[216:219], v[30:33]
	v_mfma_f32_16x16x32_bf16 v[22:25], v[150:153], v[224:227], v[22:25]
	v_mfma_f32_16x16x32_bf16 v[14:17], v[158:161], v[224:227], v[14:17]
	s_setprio 0
	s_setprio 1
	v_mfma_f32_16x16x32_bf16 v[50:53], v[162:165], v[186:189], v[50:53]
	v_mfma_f32_16x16x32_bf16 v[42:45], v[178:181], v[186:189], v[42:45]
	v_mfma_f32_16x16x32_bf16 v[34:37], v[162:165], v[194:197], v[34:37]
	v_mfma_f32_16x16x32_bf16 v[26:29], v[178:181], v[194:197], v[26:29]
	v_mfma_f32_16x16x32_bf16 v[18:21], v[162:165], v[212:215], v[18:21]
	v_mfma_f32_16x16x32_bf16 v[10:13], v[178:181], v[212:215], v[10:13]
	v_mfma_f32_16x16x32_bf16 v[6:9], v[162:165], v[220:223], v[6:9]
	v_mfma_f32_16x16x32_bf16 v[2:5], v[178:181], v[220:223], v[2:5]
	v_mfma_f32_16x16x32_bf16 v[50:53], v[166:169], v[190:193], v[50:53]
	v_mfma_f32_16x16x32_bf16 v[42:45], v[182:185], v[190:193], v[42:45]
	v_mfma_f32_16x16x32_bf16 v[34:37], v[166:169], v[198:201], v[34:37]
	v_mfma_f32_16x16x32_bf16 v[26:29], v[182:185], v[198:201], v[26:29]
	v_mfma_f32_16x16x32_bf16 v[18:21], v[166:169], v[216:219], v[18:21]
	v_mfma_f32_16x16x32_bf16 v[10:13], v[182:185], v[216:219], v[10:13]
	v_mfma_f32_16x16x32_bf16 v[6:9], v[166:169], v[224:227], v[6:9]
	v_mfma_f32_16x16x32_bf16 v[2:5], v[182:185], v[224:227], v[2:5]
	s_setprio 0
	s_barrier
	s_add_i32 s50, s50, 2
	s_add_u32 s48, s48, 0x100
	s_addc_u32 s49, s49, 0
	s_add_u32 s28, s28, 0x100
	s_addc_u32 s29, s29, 0
	s_cmp_gt_u32 s50, 29
	s_cbranch_scc0 .LBB0_861
	s_and_b64 vcc, exec, s[12:13]
	s_cbranch_vccz .LBB0_864
	s_barrier
